# GEMM K-loops: first iteration peeled with C=0 on each accumulator's first MFMA, the 128 v_mov accumulator zero fills per tile dropped (all five 8-phase loops)
# speedup vs baseline: 1.0071x; 1.0043x over previous
; #define PG8_STAGE(bufoff, gbase, voff) do { _Pragma("unroll") for (int _i = 0; _i < 2; ++_i) \
;         __builtin_amdgcn_global_load_lds((const unsigned*)((const char*)(gbase) + (voff)[_i]), (PG8_LAS unsigned*)(lds + (bufoff) + ldsw + _i * 8192), 16, 0, 0); } while (0)
; #define PG8_LDA(dst, b, h) do { _Pragma("unroll") for (int m = 0; m < 4; ++m) _Pragma("unroll") for (int k = 0; k < 2; ++k) dst[m][k] = *(const PG8_LAS bf16x8*)(lds + PG8_SA(b, h) + aoff + m * 2048 + k * 1024); } while (0)
; #define PG8_LDB(dst, b, h) do { _Pragma("unroll") for (int n = 0; n < 2; ++n) _Pragma("unroll") for (int k = 0; k < 2; ++k) dst[n][k] = *(const PG8_LAS bf16x8*)(lds + PG8_SB(b, h) + boff + n * 2048 + k * 1024); } while (0)
; #define PG8_WAIT_V(n) asm volatile("s_waitcnt vmcnt(" #n ")" ::: "memory")
; #define PG8_WAIT_L(n) asm volatile("s_waitcnt lgkmcnt(" #n ")" ::: "memory")
; #define PG8_BAR __builtin_amdgcn_s_barrier()
; template <class Epi, class Sched>
; __device__ __forceinline__ void gemm_phase(PG8_LAS unsigned char* lds, const Gemm g, const Sched& S, const Epi& E) {
;     ...
;         for (int t = 0; t < nt; t += 2) {
;             const bool last = (t == nt - 2);
;             const char* a1 = cA + (size_t)(t + 1) * kstep;
;             const char* a2 = last ? nA : cA + (size_t)(t + 2) * kstep; const char* b2 = last ? nB : cB + (size_t)(t + 2) * kstep;
;             const char* a3 = a2 + kstep; const char* b3 = b2 + kstep;
;             if (last && has_next) S.a_ready(nxt);
;             PG8_LDB(B0, 0, 0); PG8_SCHED; PG8_LDA(At, 0, 0); PG8_STAGE(PG8_SA(1, 1), a1 + hstep, voffA);
;             PG8_WAIT_L(8); PG8_BAR; PG8_WAIT_L(0); PG8_MMA(0, 0, At, B0); PG8_BAR; PG8_SCHED;
;             PG8_LDB(B1, 0, 1); PG8_STAGE(PG8_SB(0, 0), b2, voffB);
;             PG8_BAR; PG8_WAIT_L(0); PG8_MMA(0, 1, At, B1); PG8_BAR;
;             PG8_LDA(At, 0, 1); PG8_STAGE(PG8_SA(0, 0), a2, voffA);
;             PG8_BAR; PG8_WAIT_L(0); PG8_MMA(1, 0, At, B0); PG8_BAR; PG8_SCHED;
;             PG8_STAGE(PG8_SB(0, 1), b2 + hstep, voffB);
;             PG8_WAIT_V(6); PG8_BAR; PG8_MMA(1, 1, At, B1); PG8_BAR;
;     ...
; #pragma unroll
;         for (int a = 0; a < 2; ++a)
; #pragma unroll
;             for (int b = 0; b < 2; ++b)
; #pragma unroll
;                 for (int m = 0; m < 4; ++m)
; #pragma unroll
;                     for (int n = 0; n < 2; ++n) acc[a][b][m][n] = (f32x4){0.f, 0.f, 0.f, 0.f};
.LBB0_151:
	s_ashr_i32 s23, s22, 31
	v_cmp_lt_i64_e32 vcc, s[24:25], v[152:153]
	s_lshl_b64 s[24:25], s[22:23], 19
	s_add_u32 s24, s82, s24
	s_addc_u32 s25, s83, s25
	s_and_b64 s[26:27], vcc, exec
	s_cselect_b32 s7, s25, s31
	s_cselect_b32 s23, s24, s30
	s_ashr_i32 s21, s20, 31
	s_lshl_b64 s[26:27], s[20:21], 19
	s_add_u32 s26, s64, s26
	s_addc_u32 s27, s65, s27
	s_and_b64 s[36:37], vcc, exec
	s_cselect_b32 s21, s27, s35
	s_cselect_b32 s29, s26, s34
	s_add_u32 s30, s30, 0x40080
	s_addc_u32 s31, s31, 0
	s_add_u32 s48, s34, 0x100
	s_addc_u32 s49, s35, 0
	s_mov_b32 s50, -2
	ds_read_b128 v[128:131], v167
	ds_read_b128 v[132:135], v167 offset:1024
	ds_read_b128 v[156:159], v167 offset:2048
	ds_read_b128 v[160:163], v167 offset:3072
	s_add_u32 s34, s30, 0xfffc0080
	s_addc_u32 s35, s31, -1
	s_cmp_eq_u32 s50, 12
	s_cselect_b32 s37, s7, s35
	s_cselect_b32 s36, s23, s34
	s_cselect_b32 s35, s21, s49
	s_cselect_b32 s34, s29, s48
	v_lshl_add_u64 v[204:205], s[30:31], 0, v[148:149]
	s_add_i32 m0, s3, 0xc000
	ds_read_b128 v[172:175], v168
	ds_read_b128 v[180:183], v168 offset:1024
	ds_read_b128 v[184:187], v168 offset:2048
	ds_read_b128 v[188:191], v168 offset:3072
	ds_read_b128 v[192:195], v168 offset:4096
	ds_read_b128 v[196:199], v168 offset:5120
	ds_read_b128 v[200:203], v168 offset:6144
	ds_read_b128 v[208:211], v168 offset:7168
	global_load_lds_dwordx4 v[204:205], off
	v_lshl_add_u64 v[204:205], s[30:31], 0, v[150:151]
	s_add_i32 m0, s3, 0xe000
	s_nop 0
	global_load_lds_dwordx4 v[204:205], off
	s_waitcnt lgkmcnt(8)
	s_barrier
	s_waitcnt lgkmcnt(0)
	s_setprio 1
	v_mfma_f32_16x16x32_bf16 v[124:127], v[128:131], v[172:175], 0
	v_mfma_f32_16x16x32_bf16 v[120:123], v[156:159], v[172:175], 0
	v_mfma_f32_16x16x32_bf16 v[108:111], v[128:131], v[184:187], 0
	v_mfma_f32_16x16x32_bf16 v[104:107], v[156:159], v[184:187], 0
	v_mfma_f32_16x16x32_bf16 v[92:95], v[128:131], v[192:195], 0
	v_mfma_f32_16x16x32_bf16 v[88:91], v[156:159], v[192:195], 0
	v_mfma_f32_16x16x32_bf16 v[76:79], v[128:131], v[200:203], 0
	v_mfma_f32_16x16x32_bf16 v[72:75], v[156:159], v[200:203], 0
	v_mfma_f32_16x16x32_bf16 v[124:127], v[132:135], v[180:183], v[124:127]
	v_mfma_f32_16x16x32_bf16 v[120:123], v[160:163], v[180:183], v[120:123]
	v_mfma_f32_16x16x32_bf16 v[108:111], v[132:135], v[188:191], v[108:111]
	v_mfma_f32_16x16x32_bf16 v[104:107], v[160:163], v[188:191], v[104:107]
	v_mfma_f32_16x16x32_bf16 v[92:95], v[132:135], v[196:199], v[92:95]
	v_mfma_f32_16x16x32_bf16 v[88:91], v[160:163], v[196:199], v[88:91]
	v_mfma_f32_16x16x32_bf16 v[76:79], v[132:135], v[208:211], v[76:79]
	v_mfma_f32_16x16x32_bf16 v[72:75], v[160:163], v[208:211], v[72:75]
	s_setprio 0
	s_barrier
	s_add_i32 s51, s45, s1
	v_lshl_add_u64 v[204:205], s[34:35], 0, v[138:139]
	s_mov_b32 m0, s51
	ds_read_b128 v[212:215], v169
	ds_read_b128 v[216:219], v169 offset:1024
	ds_read_b128 v[220:223], v169 offset:2048
	ds_read_b128 v[224:227], v169 offset:3072
	global_load_lds_dwordx4 v[204:205], off
	v_lshl_add_u64 v[228:229], s[34:35], 0, v[142:143]
	s_add_i32 m0, s51, 0x2000
	s_nop 0
	global_load_lds_dwordx4 v[228:229], off
	s_barrier
	s_waitcnt lgkmcnt(0)
	s_setprio 1
	v_mfma_f32_16x16x32_bf16 v[116:119], v[212:215], v[172:175], 0
	v_mfma_f32_16x16x32_bf16 v[112:115], v[220:223], v[172:175], 0
	v_mfma_f32_16x16x32_bf16 v[100:103], v[212:215], v[184:187], 0
	v_mfma_f32_16x16x32_bf16 v[96:99], v[220:223], v[184:187], 0
	v_mfma_f32_16x16x32_bf16 v[84:87], v[212:215], v[192:195], 0
	v_mfma_f32_16x16x32_bf16 v[80:83], v[220:223], v[192:195], 0
	v_mfma_f32_16x16x32_bf16 v[68:71], v[212:215], v[200:203], 0
	v_mfma_f32_16x16x32_bf16 v[64:67], v[220:223], v[200:203], 0
	v_mfma_f32_16x16x32_bf16 v[116:119], v[216:219], v[180:183], v[116:119]
	v_mfma_f32_16x16x32_bf16 v[112:115], v[224:227], v[180:183], v[112:115]
	v_mfma_f32_16x16x32_bf16 v[100:103], v[216:219], v[188:191], v[100:103]
	v_mfma_f32_16x16x32_bf16 v[96:99], v[224:227], v[188:191], v[96:99]
	v_mfma_f32_16x16x32_bf16 v[84:87], v[216:219], v[196:199], v[84:87]
	v_mfma_f32_16x16x32_bf16 v[80:83], v[224:227], v[196:199], v[80:83]
	v_mfma_f32_16x16x32_bf16 v[68:71], v[216:219], v[208:211], v[68:71]
	v_mfma_f32_16x16x32_bf16 v[64:67], v[224:227], v[208:211], v[64:67]
	s_setprio 0
	s_mov_b32 m0, s3
	v_lshl_add_u64 v[230:231], s[36:37], 0, v[136:137]
	s_barrier
	ds_read_b128 v[172:175], v168 offset:16384
	ds_read_b128 v[180:183], v168 offset:17408
	ds_read_b128 v[184:187], v168 offset:18432
	ds_read_b128 v[188:191], v168 offset:19456
	ds_read_b128 v[192:195], v168 offset:20480
	ds_read_b128 v[196:199], v168 offset:21504
	ds_read_b128 v[200:203], v168 offset:22528
	ds_read_b128 v[208:211], v168 offset:23552
	global_load_lds_dwordx4 v[230:231], off
	v_lshl_add_u64 v[232:233], s[36:37], 0, v[140:141]
	s_mov_b32 m0, s33
	s_nop 0
	global_load_lds_dwordx4 v[232:233], off
	s_barrier
	s_waitcnt lgkmcnt(0)
	s_setprio 1
	v_mfma_f32_16x16x32_bf16 v[60:63], v[128:131], v[172:175], 0
	v_mfma_f32_16x16x32_bf16 v[56:59], v[156:159], v[172:175], 0
	v_mfma_f32_16x16x32_bf16 v[44:47], v[128:131], v[184:187], 0
	v_mfma_f32_16x16x32_bf16 v[40:43], v[156:159], v[184:187], 0
	v_mfma_f32_16x16x32_bf16 v[28:31], v[128:131], v[192:195], 0
	v_mfma_f32_16x16x32_bf16 v[24:27], v[156:159], v[192:195], 0
	v_mfma_f32_16x16x32_bf16 v[12:15], v[128:131], v[200:203], 0
	v_mfma_f32_16x16x32_bf16 v[8:11], v[156:159], v[200:203], 0
	v_mfma_f32_16x16x32_bf16 v[60:63], v[132:135], v[180:183], v[60:63]
	v_mfma_f32_16x16x32_bf16 v[56:59], v[160:163], v[180:183], v[56:59]
	v_mfma_f32_16x16x32_bf16 v[44:47], v[132:135], v[188:191], v[44:47]
	v_mfma_f32_16x16x32_bf16 v[40:43], v[160:163], v[188:191], v[40:43]
	v_mfma_f32_16x16x32_bf16 v[28:31], v[132:135], v[196:199], v[28:31]
	v_mfma_f32_16x16x32_bf16 v[24:27], v[160:163], v[196:199], v[24:27]
	v_mfma_f32_16x16x32_bf16 v[12:15], v[132:135], v[208:211], v[12:15]
	v_mfma_f32_16x16x32_bf16 v[8:11], v[160:163], v[208:211], v[8:11]
	s_setprio 0
	s_barrier
; #define PG8_STAGE(bufoff, gbase, voff) do { _Pragma("unroll") for (int _i = 0; _i < 2; ++_i) \
;         __builtin_amdgcn_global_load_lds((const unsigned*)((const char*)(gbase) + (voff)[_i]), (PG8_LAS unsigned*)(lds + (bufoff) + ldsw + _i * 8192), 16, 0, 0); } while (0)
; #define PG8_LDA(dst, b, h) do { _Pragma("unroll") for (int m = 0; m < 4; ++m) _Pragma("unroll") for (int k = 0; k < 2; ++k) dst[m][k] = *(const PG8_LAS bf16x8*)(lds + PG8_SA(b, h) + aoff + m * 2048 + k * 1024); } while (0)
; #define PG8_LDB(dst, b, h) do { _Pragma("unroll") for (int n = 0; n < 2; ++n) _Pragma("unroll") for (int k = 0; k < 2; ++k) dst[n][k] = *(const PG8_LAS bf16x8*)(lds + PG8_SB(b, h) + boff + n * 2048 + k * 1024); } while (0)
; #define PG8_MMA(ai, bj, At, Bt) do { __builtin_amdgcn_s_setprio(1); _Pragma("unroll") for (int m = 0; m < 4; ++m) _Pragma("unroll") for (int n = 0; n < 2; ++n) _Pragma("unroll") for (int k = 0; k < 2; ++k) \
;         acc[ai][bj][m][n] = __builtin_amdgcn_mfma_f32_16x16x32_bf16(Bt[n][k], At[m][k], acc[ai][bj][m][n], 0, 0, 0); __builtin_amdgcn_s_setprio(0); } while (0)
; #define PG8_WAIT_V(n) asm volatile("s_waitcnt vmcnt(" #n ")" ::: "memory")
; #define PG8_WAIT_L(n) asm volatile("s_waitcnt lgkmcnt(" #n ")" ::: "memory")
; #define PG8_BAR __builtin_amdgcn_s_barrier()
; #define PG8_SCHED __builtin_amdgcn_sched_barrier(0)
; template <class Epi, class Sched>
; __device__ __forceinline__ void gemm_phase(PG8_LAS unsigned char* lds, const Gemm g, const Sched& S, const Epi& E) {
;     ...
;             PG8_WAIT_V(6); PG8_BAR; PG8_MMA(1, 1, At, B1); PG8_BAR;
;             PG8_LDB(B0, 1, 0); PG8_SCHED; PG8_LDA(At, 1, 0); PG8_STAGE(PG8_SA(0, 1), a2 + hstep, voffA);
;             PG8_WAIT_L(8); PG8_BAR; PG8_WAIT_L(0); PG8_MMA(0, 0, At, B0); PG8_BAR; PG8_SCHED;
;             PG8_LDB(B1, 1, 1); PG8_STAGE(PG8_SB(1, 0), b3, voffB);
;             PG8_BAR; PG8_WAIT_L(0); PG8_MMA(0, 1, At, B1); PG8_BAR;
;             PG8_LDA(At, 1, 1); PG8_STAGE(PG8_SA(1, 0), a3, voffA);
;             PG8_BAR; PG8_WAIT_L(0); PG8_MMA(1, 0, At, B0); PG8_BAR; PG8_SCHED;
	s_add_u32 s64, s34, 0x40000
	s_addc_u32 s65, s35, 0
	s_add_i32 s51, s46, s1
	v_lshl_add_u64 v[128:129], s[64:65], 0, v[138:139]
	s_mov_b32 m0, s51
	s_nop 0
	global_load_lds_dwordx4 v[128:129], off
	v_lshl_add_u64 v[128:129], s[64:65], 0, v[142:143]
	s_add_i32 m0, s51, 0x2000
	s_nop 0
	global_load_lds_dwordx4 v[128:129], off
	s_waitcnt vmcnt(6)
	s_barrier
	s_setprio 1
	v_mfma_f32_16x16x32_bf16 v[52:55], v[212:215], v[172:175], 0
	v_mfma_f32_16x16x32_bf16 v[48:51], v[220:223], v[172:175], 0
	v_mfma_f32_16x16x32_bf16 v[36:39], v[212:215], v[184:187], 0
	v_mfma_f32_16x16x32_bf16 v[32:35], v[220:223], v[184:187], 0
	v_mfma_f32_16x16x32_bf16 v[20:23], v[212:215], v[192:195], 0
	v_mfma_f32_16x16x32_bf16 v[16:19], v[220:223], v[192:195], 0
	v_mfma_f32_16x16x32_bf16 v[4:7], v[212:215], v[200:203], 0
	v_mfma_f32_16x16x32_bf16 v[0:3], v[220:223], v[200:203], 0
	v_mfma_f32_16x16x32_bf16 v[52:55], v[216:219], v[180:183], v[52:55]
	v_mfma_f32_16x16x32_bf16 v[48:51], v[224:227], v[180:183], v[48:51]
	v_mfma_f32_16x16x32_bf16 v[36:39], v[216:219], v[188:191], v[36:39]
	v_mfma_f32_16x16x32_bf16 v[32:35], v[224:227], v[188:191], v[32:35]
	v_mfma_f32_16x16x32_bf16 v[20:23], v[216:219], v[196:199], v[20:23]
	v_mfma_f32_16x16x32_bf16 v[16:19], v[224:227], v[196:199], v[16:19]
	v_mfma_f32_16x16x32_bf16 v[4:7], v[216:219], v[208:211], v[4:7]
	v_mfma_f32_16x16x32_bf16 v[0:3], v[224:227], v[208:211], v[0:3]
	s_setprio 0
	s_add_i32 s51, 0, 0x18000
	v_add_u32_e32 v144, s51, v164
	s_barrier
	ds_read_b128 v[128:131], v144
	ds_read_b128 v[132:135], v144 offset:1024
	ds_read_b128 v[156:159], v144 offset:2048
	ds_read_b128 v[160:163], v144 offset:3072
	s_add_u32 s36, s36, 0x40000
	s_addc_u32 s37, s37, 0
	s_mov_b32 m0, s38
	v_lshl_add_u64 v[212:213], s[36:37], 0, v[136:137]
	ds_read_b128 v[172:175], v168 offset:32768
	ds_read_b128 v[180:183], v168 offset:33792
	ds_read_b128 v[184:187], v168 offset:34816
	ds_read_b128 v[188:191], v168 offset:35840
	ds_read_b128 v[192:195], v168 offset:36864
	ds_read_b128 v[196:199], v168 offset:37888
	ds_read_b128 v[200:203], v168 offset:38912
	ds_read_b128 v[208:211], v168 offset:39936
	global_load_lds_dwordx4 v[212:213], off
	v_lshl_add_u64 v[212:213], s[36:37], 0, v[140:141]
	s_mov_b32 m0, s39
	s_nop 0
	global_load_lds_dwordx4 v[212:213], off
	s_waitcnt lgkmcnt(8)
	s_barrier
	s_waitcnt lgkmcnt(0)
	s_setprio 1
	v_mfma_f32_16x16x32_bf16 v[124:127], v[128:131], v[172:175], v[124:127]
	v_mfma_f32_16x16x32_bf16 v[120:123], v[156:159], v[172:175], v[120:123]
	v_mfma_f32_16x16x32_bf16 v[108:111], v[128:131], v[184:187], v[108:111]
	v_mfma_f32_16x16x32_bf16 v[104:107], v[156:159], v[184:187], v[104:107]
	v_mfma_f32_16x16x32_bf16 v[92:95], v[128:131], v[192:195], v[92:95]
	v_mfma_f32_16x16x32_bf16 v[88:91], v[156:159], v[192:195], v[88:91]
	v_mfma_f32_16x16x32_bf16 v[76:79], v[128:131], v[200:203], v[76:79]
	v_mfma_f32_16x16x32_bf16 v[72:75], v[156:159], v[200:203], v[72:75]
	v_mfma_f32_16x16x32_bf16 v[124:127], v[132:135], v[180:183], v[124:127]
	v_mfma_f32_16x16x32_bf16 v[120:123], v[160:163], v[180:183], v[120:123]
	v_mfma_f32_16x16x32_bf16 v[108:111], v[132:135], v[188:191], v[108:111]
	v_mfma_f32_16x16x32_bf16 v[104:107], v[160:163], v[188:191], v[104:107]
	v_mfma_f32_16x16x32_bf16 v[92:95], v[132:135], v[196:199], v[92:95]
	v_mfma_f32_16x16x32_bf16 v[88:91], v[160:163], v[196:199], v[88:91]
	v_mfma_f32_16x16x32_bf16 v[76:79], v[132:135], v[208:211], v[76:79]
	v_mfma_f32_16x16x32_bf16 v[72:75], v[160:163], v[208:211], v[72:75]
	s_setprio 0
	s_barrier
	s_add_i32 s36, 0, 0x1c000
	s_add_i32 s37, s51, s1
	v_add_u32_e32 v144, s36, v164
	v_lshl_add_u64 v[204:205], v[204:205], 0, s[12:13]
	s_mov_b32 m0, s37
	ds_read_b128 v[212:215], v144
	ds_read_b128 v[216:219], v144 offset:1024
	ds_read_b128 v[220:223], v144 offset:2048
	ds_read_b128 v[224:227], v144 offset:3072
	global_load_lds_dwordx4 v[204:205], off
	v_lshl_add_u64 v[204:205], v[228:229], 0, s[12:13]
	s_add_i32 m0, s37, 0x2000
	s_nop 0
	global_load_lds_dwordx4 v[204:205], off
	s_barrier
; #define PG8_STAGE(bufoff, gbase, voff) do { _Pragma("unroll") for (int _i = 0; _i < 2; ++_i) \
;         __builtin_amdgcn_global_load_lds((const unsigned*)((const char*)(gbase) + (voff)[_i]), (PG8_LAS unsigned*)(lds + (bufoff) + ldsw + _i * 8192), 16, 0, 0); } while (0)
; #define PG8_LDA(dst, b, h) do { _Pragma("unroll") for (int m = 0; m < 4; ++m) _Pragma("unroll") for (int k = 0; k < 2; ++k) dst[m][k] = *(const PG8_LAS bf16x8*)(lds + PG8_SA(b, h) + aoff + m * 2048 + k * 1024); } while (0)
; #define PG8_MMA(ai, bj, At, Bt) do { __builtin_amdgcn_s_setprio(1); _Pragma("unroll") for (int m = 0; m < 4; ++m) _Pragma("unroll") for (int n = 0; n < 2; ++n) _Pragma("unroll") for (int k = 0; k < 2; ++k) \
;         acc[ai][bj][m][n] = __builtin_amdgcn_mfma_f32_16x16x32_bf16(Bt[n][k], At[m][k], acc[ai][bj][m][n], 0, 0, 0); __builtin_amdgcn_s_setprio(0); } while (0)
; #define PG8_WAIT_V(n) asm volatile("s_waitcnt vmcnt(" #n ")" ::: "memory")
; #define PG8_WAIT_L(n) asm volatile("s_waitcnt lgkmcnt(" #n ")" ::: "memory")
; #define PG8_BAR __builtin_amdgcn_s_barrier()
; #define PG8_SCHED __builtin_amdgcn_sched_barrier(0)
; template <class Epi, class Sched>
; __device__ __forceinline__ void gemm_phase(PG8_LAS unsigned char* lds, const Gemm g, const Sched& S, const Epi& E) {
;     ...
;             PG8_BAR; PG8_WAIT_L(0); PG8_MMA(0, 1, At, B1); PG8_BAR;
;             PG8_LDA(At, 1, 1); PG8_STAGE(PG8_SA(1, 0), a3, voffA);
;             PG8_BAR; PG8_WAIT_L(0); PG8_MMA(1, 0, At, B0); PG8_BAR; PG8_SCHED;
;             PG8_STAGE(PG8_SB(1, 1), b3 + hstep, voffB);
;             PG8_WAIT_V(6); PG8_BAR; PG8_MMA(1, 1, At, B1); PG8_BAR;
	s_waitcnt lgkmcnt(0)
	s_setprio 1
	v_mfma_f32_16x16x32_bf16 v[116:119], v[212:215], v[172:175], v[116:119]
	v_mfma_f32_16x16x32_bf16 v[112:115], v[220:223], v[172:175], v[112:115]
	v_mfma_f32_16x16x32_bf16 v[100:103], v[212:215], v[184:187], v[100:103]
	v_mfma_f32_16x16x32_bf16 v[96:99], v[220:223], v[184:187], v[96:99]
	v_mfma_f32_16x16x32_bf16 v[84:87], v[212:215], v[192:195], v[84:87]
	v_mfma_f32_16x16x32_bf16 v[80:83], v[220:223], v[192:195], v[80:83]
	v_mfma_f32_16x16x32_bf16 v[68:71], v[212:215], v[200:203], v[68:71]
	v_mfma_f32_16x16x32_bf16 v[64:67], v[220:223], v[200:203], v[64:67]
	v_mfma_f32_16x16x32_bf16 v[116:119], v[216:219], v[180:183], v[116:119]
	v_mfma_f32_16x16x32_bf16 v[112:115], v[224:227], v[180:183], v[112:115]
	v_mfma_f32_16x16x32_bf16 v[100:103], v[216:219], v[188:191], v[100:103]
	v_mfma_f32_16x16x32_bf16 v[96:99], v[224:227], v[188:191], v[96:99]
	v_mfma_f32_16x16x32_bf16 v[84:87], v[216:219], v[196:199], v[84:87]
	v_mfma_f32_16x16x32_bf16 v[80:83], v[224:227], v[196:199], v[80:83]
	v_mfma_f32_16x16x32_bf16 v[68:71], v[216:219], v[208:211], v[68:71]
	v_mfma_f32_16x16x32_bf16 v[64:67], v[224:227], v[208:211], v[64:67]
	s_setprio 0
	s_mov_b32 m0, s42
	v_lshl_add_u64 v[204:205], v[230:231], 0, s[12:13]
	s_barrier
	ds_read_b128 v[172:175], v168 offset:49152
	ds_read_b128 v[180:183], v168 offset:50176
	ds_read_b128 v[184:187], v168 offset:51200
	ds_read_b128 v[188:191], v168 offset:52224
	ds_read_b128 v[192:195], v168 offset:53248
	ds_read_b128 v[196:199], v168 offset:54272
	ds_read_b128 v[200:203], v168 offset:55296
	ds_read_b128 v[208:211], v168 offset:56320
	global_load_lds_dwordx4 v[204:205], off
	v_lshl_add_u64 v[204:205], v[232:233], 0, s[12:13]
	s_mov_b32 m0, s43
	s_nop 0
	global_load_lds_dwordx4 v[204:205], off
	s_barrier
	s_waitcnt lgkmcnt(0)
	s_setprio 1
	v_mfma_f32_16x16x32_bf16 v[60:63], v[128:131], v[172:175], v[60:63]
	v_mfma_f32_16x16x32_bf16 v[56:59], v[156:159], v[172:175], v[56:59]
	v_mfma_f32_16x16x32_bf16 v[44:47], v[128:131], v[184:187], v[44:47]
	v_mfma_f32_16x16x32_bf16 v[40:43], v[156:159], v[184:187], v[40:43]
	v_mfma_f32_16x16x32_bf16 v[28:31], v[128:131], v[192:195], v[28:31]
	v_mfma_f32_16x16x32_bf16 v[24:27], v[156:159], v[192:195], v[24:27]
	v_mfma_f32_16x16x32_bf16 v[12:15], v[128:131], v[200:203], v[12:15]
	v_mfma_f32_16x16x32_bf16 v[8:11], v[156:159], v[200:203], v[8:11]
	v_mfma_f32_16x16x32_bf16 v[60:63], v[132:135], v[180:183], v[60:63]
	v_mfma_f32_16x16x32_bf16 v[56:59], v[160:163], v[180:183], v[56:59]
	v_mfma_f32_16x16x32_bf16 v[44:47], v[132:135], v[188:191], v[44:47]
	v_mfma_f32_16x16x32_bf16 v[40:43], v[160:163], v[188:191], v[40:43]
	v_mfma_f32_16x16x32_bf16 v[28:31], v[132:135], v[196:199], v[28:31]
	v_mfma_f32_16x16x32_bf16 v[24:27], v[160:163], v[196:199], v[24:27]
	v_mfma_f32_16x16x32_bf16 v[12:15], v[132:135], v[208:211], v[12:15]
	v_mfma_f32_16x16x32_bf16 v[8:11], v[160:163], v[208:211], v[8:11]
	s_setprio 0
	s_barrier
	s_add_u32 s34, s34, 0x40080
	s_addc_u32 s35, s35, 0
	s_add_i32 s36, s36, s1
	v_lshl_add_u64 v[128:129], s[34:35], 0, v[138:139]
	s_mov_b32 m0, s36
	s_nop 0
	global_load_lds_dwordx4 v[128:129], off
	v_lshl_add_u64 v[128:129], s[34:35], 0, v[142:143]
	s_add_i32 m0, s36, 0x2000
	s_nop 0
	global_load_lds_dwordx4 v[128:129], off
	s_waitcnt vmcnt(6)
	s_barrier
	s_setprio 1
	v_mfma_f32_16x16x32_bf16 v[52:55], v[212:215], v[172:175], v[52:55]
	v_mfma_f32_16x16x32_bf16 v[48:51], v[220:223], v[172:175], v[48:51]
	v_mfma_f32_16x16x32_bf16 v[36:39], v[212:215], v[184:187], v[36:39]
	v_mfma_f32_16x16x32_bf16 v[32:35], v[220:223], v[184:187], v[32:35]
	v_mfma_f32_16x16x32_bf16 v[20:23], v[212:215], v[192:195], v[20:23]
	v_mfma_f32_16x16x32_bf16 v[16:19], v[220:223], v[192:195], v[16:19]
	v_mfma_f32_16x16x32_bf16 v[4:7], v[212:215], v[200:203], v[4:7]
	v_mfma_f32_16x16x32_bf16 v[0:3], v[220:223], v[200:203], v[0:3]
	v_mfma_f32_16x16x32_bf16 v[52:55], v[216:219], v[180:183], v[52:55]
	v_mfma_f32_16x16x32_bf16 v[48:51], v[224:227], v[180:183], v[48:51]
	v_mfma_f32_16x16x32_bf16 v[36:39], v[216:219], v[188:191], v[36:39]
	v_mfma_f32_16x16x32_bf16 v[32:35], v[224:227], v[188:191], v[32:35]
	v_mfma_f32_16x16x32_bf16 v[20:23], v[216:219], v[196:199], v[20:23]
	v_mfma_f32_16x16x32_bf16 v[16:19], v[224:227], v[196:199], v[16:19]
	v_mfma_f32_16x16x32_bf16 v[4:7], v[216:219], v[208:211], v[4:7]
	v_mfma_f32_16x16x32_bf16 v[0:3], v[224:227], v[208:211], v[0:3]
	s_setprio 0
	s_add_i32 s50, s50, 2
	s_add_u32 s30, s30, 0x100
	s_addc_u32 s31, s31, 0
	s_add_u32 s48, s48, 0x100
	s_addc_u32 s49, s49, 0
	s_cmp_gt_u32 s50, 13
	s_barrier
	s_cbranch_scc1 .Lpeel_x0_LBB0152

; __device__ __forceinline__ unsigned cvt_pk_bf16(float lo, float hi) { unsigned r; asm volatile("v_cvt_pk_bf16_f32 %0, %1, %2" : "=v"(r) : "v"(lo), "v"(hi)); return r; }
; __device__ __forceinline__ float sigmoidf_(float x) { return frcp(1.0f + __expf(-x)); }
;     __device__ __forceinline__ void operator()(const f32x4 (&acc)[2][2][4][2], const Unit& u, int wr, int wc, int fr, int fq, const float (&epre)[1]) const {
;     ...
;             const int cu = (pn - 8) * 128 + wc * 32 + 8 * fq;
; #pragma unroll
;             for (int ai = 0; ai < 2; ++ai)
; #pragma unroll
;                 for (int m = 0; m < 4; ++m) { const int row = row0 + ai * 128 + m * 16;
;                     f32x4 u0, u1;
; #pragma unroll
;                     for (int j = 0; j < 4; ++j) { u0[j] = acc[ai][0][m][0][j] * sigmoidf_(acc[ai][1][m][0][j]); u1[j] = acc[ai][0][m][1][j] * sigmoidf_(acc[ai][1][m][1][j]); }
;                     u32x4 w; w.x = cvt_pk_bf16(u0[0], u0[1]); w.y = cvt_pk_bf16(u0[2], u0[3]); w.z = cvt_pk_bf16(u1[0], u1[1]); w.w = cvt_pk_bf16(u1[2], u1[3]);
;                     *(u32x4*)(U + (size_t)row * 512 + cu) = w;
;                     if (row < MP) { const int t = row & (SEQ - 1);
;                         if (t >= SEQ - (CW - 1)) { float* o = scp + ((size_t)((row >> 11) * (CW - 1) + t - (SEQ - (CW - 1)))) * MIXB + cu; __builtin_nontemporal_store(u0, (f32x4*)o); __builtin_nontemporal_store(u1, (f32x4*)(o + 4)); }
;                     } else { const int rs = row - MP; float* o = scs + ((size_t)((rs >> 2) * (CW - 1) + (CW - 1 - DS) + (rs & 3))) * MIXB + cu; *(f32x4*)o = u0; *(f32x4*)(o + 4) = u1; }
.Lpeel_x0_LBB0152:
	s_lshl_b32 s23, s6, 8
	s_lshl_b32 s6, s28, 2
	s_lshr_b64 s[6:7], s[14:15], s6
	s_add_i32 s23, s23, s41
	s_and_b32 s21, s6, 15
	v_or_b32_e32 v156, s23, v147
	s_cmp_gt_u32 s21, 7
	s_mov_b64 s[6:7], -1
	s_cbranch_scc0 .LBB0_187
	v_mul_f32_e32 v129, 0xbfb8aa3b, v112
	v_mul_f32_e32 v130, 0xbfb8aa3b, v117
	v_exp_f32_e32 v129, v129
	v_exp_f32_e32 v131, v130
	v_mul_f32_e32 v130, 0xbfb8aa3b, v113
	v_exp_f32_e32 v132, v130
	v_add_f32_e32 v129, 1.0, v129
	v_rcp_f32_e32 v130, v129
	v_add_f32_e32 v129, 1.0, v131
	v_add_f32_e32 v131, 1.0, v132
	v_mul_f32_e32 v132, 0xbfb8aa3b, v118
	v_exp_f32_e32 v132, v132
	v_mul_f32_e32 v133, 0xbfb8aa3b, v114
	v_exp_f32_e32 v133, v133
	v_mul_f32_e32 v128, 0xbfb8aa3b, v116
	v_add_f32_e32 v132, 1.0, v132
	v_rcp_f32_e32 v134, v132
	v_add_f32_e32 v132, 1.0, v133
	v_mul_f32_e32 v133, 0xbfb8aa3b, v119
	v_exp_f32_e32 v133, v133
	v_mul_f32_e32 v135, 0xbfb8aa3b, v115
	v_exp_f32_e32 v128, v128
	v_exp_f32_e32 v157, v135
	v_rcp_f32_e32 v158, v132
	v_add_f32_e32 v132, 1.0, v133
	v_add_f32_e32 v128, 1.0, v128
	v_rcp_f32_e32 v135, v132
	v_add_f32_e32 v132, 1.0, v157
	v_rcp_f32_e32 v128, v128
	v_rcp_f32_e32 v129, v129
	v_rcp_f32_e32 v131, v131
	v_rcp_f32_e32 v159, v132
	v_ashrrev_i32_e32 v157, 31, v156
	v_readlane_b32 s6, v247, 36
	v_lshlrev_b64 v[162:163], 10, v[156:157]
	v_readlane_b32 s7, v247, 37
	v_lshl_add_u32 v144, s21, 7, v166
	v_pk_mul_f32 v[132:133], v[124:125], v[128:129]
	v_lshl_add_u64 v[162:163], s[6:7], 0, v[162:163]
	v_pk_mul_f32 v[128:129], v[120:121], v[130:131]
	v_pk_mul_f32 v[134:135], v[126:127], v[134:135]
	v_pk_mul_f32 v[130:131], v[122:123], v[158:159]
	v_lshl_add_u64 v[162:163], v[144:145], 1, v[162:163]
	v_cmp_lt_i32_e32 vcc, s47, v156
	v_cvt_pk_bf16_f32 v158, v132, v133
	v_cvt_pk_bf16_f32 v159, v134, v135
	v_cvt_pk_bf16_f32 v160, v128, v129
	v_cvt_pk_bf16_f32 v161, v130, v131
	global_store_dwordx4 v[162:163], v[158:161], off
	s_and_saveexec_b64 s[6:7], vcc
	s_cbranch_execz .LBB0_156
	v_add_u32_e32 v158, 0xffffc000, v156
	v_lshrrev_b32_e32 v158, 2, v158
	v_mad_u64_u32 v[158:159], s[28:29], v158, 30, v[146:147]
	v_mov_b32_e32 v159, v145
	v_lshlrev_b64 v[158:159], 11, v[158:159]
	v_lshl_add_u64 v[158:159], s[8:9], 0, v[158:159]
	v_lshl_add_u64 v[158:159], v[144:145], 2, v[158:159]
	global_store_dwordx4 v[158:159], v[132:135], off
	global_store_dwordx4 v[158:159], v[128:131], off offset:16

; #define PG8_STAGE(bufoff, gbase, voff) do { _Pragma("unroll") for (int _i = 0; _i < 2; ++_i) \
;         __builtin_amdgcn_global_load_lds((const unsigned*)((const char*)(gbase) + (voff)[_i]), (PG8_LAS unsigned*)(lds + (bufoff) + ldsw + _i * 8192), 16, 0, 0); } while (0)
; #define PG8_LDA(dst, b, h) do { _Pragma("unroll") for (int m = 0; m < 4; ++m) _Pragma("unroll") for (int k = 0; k < 2; ++k) dst[m][k] = *(const PG8_LAS bf16x8*)(lds + PG8_SA(b, h) + aoff + m * 2048 + k * 1024); } while (0)
; #define PG8_LDB(dst, b, h) do { _Pragma("unroll") for (int n = 0; n < 2; ++n) _Pragma("unroll") for (int k = 0; k < 2; ++k) dst[n][k] = *(const PG8_LAS bf16x8*)(lds + PG8_SB(b, h) + boff + n * 2048 + k * 1024); } while (0)
; #define PG8_WAIT_V(n) asm volatile("s_waitcnt vmcnt(" #n ")" ::: "memory")
; #define PG8_WAIT_L(n) asm volatile("s_waitcnt lgkmcnt(" #n ")" ::: "memory")
; #define PG8_BAR __builtin_amdgcn_s_barrier()
; template <class Epi, class Sched>
; __device__ __forceinline__ void gemm_phase(PG8_LAS unsigned char* lds, const Gemm g, const Sched& S, const Epi& E) {
;     ...
;         for (int t = 0; t < nt; t += 2) {
;             const bool last = (t == nt - 2);
;             const char* a1 = cA + (size_t)(t + 1) * kstep;
;             const char* a2 = last ? nA : cA + (size_t)(t + 2) * kstep; const char* b2 = last ? nB : cB + (size_t)(t + 2) * kstep;
;             const char* a3 = a2 + kstep; const char* b3 = b2 + kstep;
;             if (last && has_next) S.a_ready(nxt);
;             PG8_LDB(B0, 0, 0); PG8_SCHED; PG8_LDA(At, 0, 0); PG8_STAGE(PG8_SA(1, 1), a1 + hstep, voffA);
;             PG8_WAIT_L(8); PG8_BAR; PG8_WAIT_L(0); PG8_MMA(0, 0, At, B0); PG8_BAR; PG8_SCHED;
;             PG8_LDB(B1, 0, 1); PG8_STAGE(PG8_SB(0, 0), b2, voffB);
;             PG8_BAR; PG8_WAIT_L(0); PG8_MMA(0, 1, At, B1); PG8_BAR;
;             PG8_LDA(At, 0, 1); PG8_STAGE(PG8_SA(0, 0), a2, voffA);
;             PG8_BAR; PG8_WAIT_L(0); PG8_MMA(1, 0, At, B0); PG8_BAR; PG8_SCHED;
;             PG8_STAGE(PG8_SB(0, 1), b2 + hstep, voffB);
;             PG8_WAIT_V(6); PG8_BAR; PG8_MMA(1, 1, At, B1); PG8_BAR;
;     ...
; #pragma unroll
;         for (int a = 0; a < 2; ++a)
; #pragma unroll
;             for (int b = 0; b < 2; ++b)
; #pragma unroll
;                 for (int m = 0; m < 4; ++m)
; #pragma unroll
;                     for (int n = 0; n < 2; ++n) acc[a][b][m][n] = (f32x4){0.f, 0.f, 0.f, 0.f};
.LBB0_618:
	s_ashr_i32 s19, s18, 31
	v_cmp_lt_i64_e32 vcc, s[20:21], v[158:159]
	s_lshl_b64 s[20:21], s[18:19], 19
	s_add_u32 s20, s82, s20
	s_addc_u32 s21, s83, s21
	s_and_b64 s[22:23], vcc, exec
	s_cselect_b32 s19, s21, s27
	s_cselect_b32 s45, s20, s26
	s_ashr_i32 s17, s16, 31
	s_lshl_b64 s[22:23], s[16:17], 19
	s_add_u32 s22, s12, s22
	s_addc_u32 s23, s13, s23
	s_and_b64 s[30:31], vcc, exec
	s_cselect_b32 s17, s23, s29
	s_cselect_b32 s46, s22, s28
	s_add_u32 s26, s26, 0x40080
	s_addc_u32 s27, s27, 0
	s_add_u32 s47, s28, 0x100
	s_addc_u32 s48, s29, 0
	s_mov_b32 s49, -2
	s_waitcnt lgkmcnt(0)
	ds_read_b128 v[128:131], v175
	ds_read_b128 v[132:135], v175 offset:1024
	ds_read_b128 v[136:139], v175 offset:2048
	ds_read_b128 v[140:143], v175 offset:3072
	s_add_u32 s28, s26, 0xfffc0080
	s_addc_u32 s29, s27, -1
	s_cmp_eq_u32 s49, 12
	s_cselect_b32 s31, s19, s29
	s_cselect_b32 s30, s45, s28
	s_cselect_b32 s29, s17, s48
	s_cselect_b32 s28, s46, s47
	v_lshl_add_u64 v[170:171], s[26:27], 0, v[154:155]
	s_add_i32 m0, s4, 0xc000
	ds_read_b128 v[162:165], v177
	ds_read_b128 v[166:169], v177 offset:1024
	ds_read_b128 v[182:185], v177 offset:2048
	ds_read_b128 v[186:189], v177 offset:3072
	ds_read_b128 v[190:193], v177 offset:4096
	ds_read_b128 v[194:197], v177 offset:5120
	ds_read_b128 v[198:201], v177 offset:6144
	ds_read_b128 v[202:205], v177 offset:7168
	global_load_lds_dwordx4 v[170:171], off
	v_lshl_add_u64 v[170:171], s[26:27], 0, v[156:157]
	s_add_i32 m0, s4, 0xe000
	s_nop 0
	global_load_lds_dwordx4 v[170:171], off
	s_waitcnt lgkmcnt(8)
	s_barrier
	s_waitcnt lgkmcnt(0)
	s_setprio 1
	v_mfma_f32_16x16x32_bf16 v[124:127], v[128:131], v[162:165], 0
	v_mfma_f32_16x16x32_bf16 v[120:123], v[136:139], v[162:165], 0
	v_mfma_f32_16x16x32_bf16 v[108:111], v[128:131], v[182:185], 0
	v_mfma_f32_16x16x32_bf16 v[104:107], v[136:139], v[182:185], 0
	v_mfma_f32_16x16x32_bf16 v[92:95], v[128:131], v[190:193], 0
	v_mfma_f32_16x16x32_bf16 v[88:91], v[136:139], v[190:193], 0
	v_mfma_f32_16x16x32_bf16 v[76:79], v[128:131], v[198:201], 0
	v_mfma_f32_16x16x32_bf16 v[72:75], v[136:139], v[198:201], 0
	v_mfma_f32_16x16x32_bf16 v[124:127], v[132:135], v[166:169], v[124:127]
	v_mfma_f32_16x16x32_bf16 v[120:123], v[140:143], v[166:169], v[120:123]
	v_mfma_f32_16x16x32_bf16 v[108:111], v[132:135], v[186:189], v[108:111]
	v_mfma_f32_16x16x32_bf16 v[104:107], v[140:143], v[186:189], v[104:107]
	v_mfma_f32_16x16x32_bf16 v[92:95], v[132:135], v[194:197], v[92:95]
	v_mfma_f32_16x16x32_bf16 v[88:91], v[140:143], v[194:197], v[88:91]
	v_mfma_f32_16x16x32_bf16 v[76:79], v[132:135], v[202:205], v[76:79]
	v_mfma_f32_16x16x32_bf16 v[72:75], v[140:143], v[202:205], v[72:75]
	s_setprio 0
	s_barrier
	s_add_i32 s50, s39, s3
	v_lshl_add_u64 v[170:171], s[28:29], 0, v[146:147]
	s_mov_b32 m0, s50
	ds_read_b128 v[208:211], v180
	ds_read_b128 v[212:215], v180 offset:1024
	ds_read_b128 v[216:219], v180 offset:2048
	ds_read_b128 v[220:223], v180 offset:3072
	global_load_lds_dwordx4 v[170:171], off
	v_lshl_add_u64 v[224:225], s[28:29], 0, v[150:151]
	s_add_i32 m0, s50, 0x2000
	s_nop 0
	global_load_lds_dwordx4 v[224:225], off
	s_barrier
	s_waitcnt lgkmcnt(0)
	s_setprio 1
	v_mfma_f32_16x16x32_bf16 v[116:119], v[208:211], v[162:165], 0
	v_mfma_f32_16x16x32_bf16 v[112:115], v[216:219], v[162:165], 0
	v_mfma_f32_16x16x32_bf16 v[100:103], v[208:211], v[182:185], 0
	v_mfma_f32_16x16x32_bf16 v[96:99], v[216:219], v[182:185], 0
	v_mfma_f32_16x16x32_bf16 v[84:87], v[208:211], v[190:193], 0
	v_mfma_f32_16x16x32_bf16 v[80:83], v[216:219], v[190:193], 0
	v_mfma_f32_16x16x32_bf16 v[68:71], v[208:211], v[198:201], 0
	v_mfma_f32_16x16x32_bf16 v[64:67], v[216:219], v[198:201], 0
	v_mfma_f32_16x16x32_bf16 v[116:119], v[212:215], v[166:169], v[116:119]
	v_mfma_f32_16x16x32_bf16 v[112:115], v[220:223], v[166:169], v[112:115]
	v_mfma_f32_16x16x32_bf16 v[100:103], v[212:215], v[186:189], v[100:103]
	v_mfma_f32_16x16x32_bf16 v[96:99], v[220:223], v[186:189], v[96:99]
	v_mfma_f32_16x16x32_bf16 v[84:87], v[212:215], v[194:197], v[84:87]
	v_mfma_f32_16x16x32_bf16 v[80:83], v[220:223], v[194:197], v[80:83]
	v_mfma_f32_16x16x32_bf16 v[68:71], v[212:215], v[202:205], v[68:71]
	v_mfma_f32_16x16x32_bf16 v[64:67], v[220:223], v[202:205], v[64:67]
	s_setprio 0
	s_mov_b32 m0, s4
	v_lshl_add_u64 v[226:227], s[30:31], 0, v[144:145]
	s_barrier
	ds_read_b128 v[162:165], v177 offset:16384
	ds_read_b128 v[166:169], v177 offset:17408
	ds_read_b128 v[182:185], v177 offset:18432
	ds_read_b128 v[186:189], v177 offset:19456
	ds_read_b128 v[190:193], v177 offset:20480
	ds_read_b128 v[194:197], v177 offset:21504
	ds_read_b128 v[198:201], v177 offset:22528
	ds_read_b128 v[202:205], v177 offset:23552
	global_load_lds_dwordx4 v[226:227], off
	v_lshl_add_u64 v[228:229], s[30:31], 0, v[148:149]
	s_mov_b32 m0, s5
	s_nop 0
	global_load_lds_dwordx4 v[228:229], off
	s_barrier
	s_waitcnt lgkmcnt(0)
	s_setprio 1
	v_mfma_f32_16x16x32_bf16 v[60:63], v[128:131], v[162:165], 0
	v_mfma_f32_16x16x32_bf16 v[56:59], v[136:139], v[162:165], 0
	v_mfma_f32_16x16x32_bf16 v[44:47], v[128:131], v[182:185], 0
	v_mfma_f32_16x16x32_bf16 v[40:43], v[136:139], v[182:185], 0
	v_mfma_f32_16x16x32_bf16 v[28:31], v[128:131], v[190:193], 0
	v_mfma_f32_16x16x32_bf16 v[24:27], v[136:139], v[190:193], 0
	v_mfma_f32_16x16x32_bf16 v[12:15], v[128:131], v[198:201], 0
	v_mfma_f32_16x16x32_bf16 v[8:11], v[136:139], v[198:201], 0
	v_mfma_f32_16x16x32_bf16 v[60:63], v[132:135], v[166:169], v[60:63]
	v_mfma_f32_16x16x32_bf16 v[56:59], v[140:143], v[166:169], v[56:59]
	v_mfma_f32_16x16x32_bf16 v[44:47], v[132:135], v[186:189], v[44:47]
	v_mfma_f32_16x16x32_bf16 v[40:43], v[140:143], v[186:189], v[40:43]
	v_mfma_f32_16x16x32_bf16 v[28:31], v[132:135], v[194:197], v[28:31]
	v_mfma_f32_16x16x32_bf16 v[24:27], v[140:143], v[194:197], v[24:27]
	v_mfma_f32_16x16x32_bf16 v[12:15], v[132:135], v[202:205], v[12:15]
	v_mfma_f32_16x16x32_bf16 v[8:11], v[140:143], v[202:205], v[8:11]
	s_setprio 0
	s_barrier
; #define PG8_STAGE(bufoff, gbase, voff) do { _Pragma("unroll") for (int _i = 0; _i < 2; ++_i) \
;         __builtin_amdgcn_global_load_lds((const unsigned*)((const char*)(gbase) + (voff)[_i]), (PG8_LAS unsigned*)(lds + (bufoff) + ldsw + _i * 8192), 16, 0, 0); } while (0)
; #define PG8_LDA(dst, b, h) do { _Pragma("unroll") for (int m = 0; m < 4; ++m) _Pragma("unroll") for (int k = 0; k < 2; ++k) dst[m][k] = *(const PG8_LAS bf16x8*)(lds + PG8_SA(b, h) + aoff + m * 2048 + k * 1024); } while (0)
; #define PG8_LDB(dst, b, h) do { _Pragma("unroll") for (int n = 0; n < 2; ++n) _Pragma("unroll") for (int k = 0; k < 2; ++k) dst[n][k] = *(const PG8_LAS bf16x8*)(lds + PG8_SB(b, h) + boff + n * 2048 + k * 1024); } while (0)
; #define PG8_MMA(ai, bj, At, Bt) do { __builtin_amdgcn_s_setprio(1); _Pragma("unroll") for (int m = 0; m < 4; ++m) _Pragma("unroll") for (int n = 0; n < 2; ++n) _Pragma("unroll") for (int k = 0; k < 2; ++k) \
;         acc[ai][bj][m][n] = __builtin_amdgcn_mfma_f32_16x16x32_bf16(Bt[n][k], At[m][k], acc[ai][bj][m][n], 0, 0, 0); __builtin_amdgcn_s_setprio(0); } while (0)
; #define PG8_WAIT_V(n) asm volatile("s_waitcnt vmcnt(" #n ")" ::: "memory")
; #define PG8_WAIT_L(n) asm volatile("s_waitcnt lgkmcnt(" #n ")" ::: "memory")
; #define PG8_BAR __builtin_amdgcn_s_barrier()
; #define PG8_SCHED __builtin_amdgcn_sched_barrier(0)
; template <class Epi, class Sched>
; __device__ __forceinline__ void gemm_phase(PG8_LAS unsigned char* lds, const Gemm g, const Sched& S, const Epi& E) {
;     ...
;             PG8_WAIT_V(6); PG8_BAR; PG8_MMA(1, 1, At, B1); PG8_BAR;
;             PG8_LDB(B0, 1, 0); PG8_SCHED; PG8_LDA(At, 1, 0); PG8_STAGE(PG8_SA(0, 1), a2 + hstep, voffA);
;             PG8_WAIT_L(8); PG8_BAR; PG8_WAIT_L(0); PG8_MMA(0, 0, At, B0); PG8_BAR; PG8_SCHED;
;             PG8_LDB(B1, 1, 1); PG8_STAGE(PG8_SB(1, 0), b3, voffB);
;             PG8_BAR; PG8_WAIT_L(0); PG8_MMA(0, 1, At, B1); PG8_BAR;
;             PG8_LDA(At, 1, 1); PG8_STAGE(PG8_SA(1, 0), a3, voffA);
;             PG8_BAR; PG8_WAIT_L(0); PG8_MMA(1, 0, At, B0); PG8_BAR; PG8_SCHED;
	s_add_u32 s50, s28, 0x40000
	s_addc_u32 s51, s29, 0
	s_add_i32 s60, s40, s3
	v_lshl_add_u64 v[128:129], s[50:51], 0, v[146:147]
	s_mov_b32 m0, s60
	s_nop 0
	global_load_lds_dwordx4 v[128:129], off
	v_lshl_add_u64 v[128:129], s[50:51], 0, v[150:151]
	s_add_i32 m0, s60, 0x2000
	s_nop 0
	global_load_lds_dwordx4 v[128:129], off
	s_waitcnt vmcnt(6)
	s_barrier
	s_setprio 1
	v_mfma_f32_16x16x32_bf16 v[52:55], v[208:211], v[162:165], 0
	v_mfma_f32_16x16x32_bf16 v[48:51], v[216:219], v[162:165], 0
	v_mfma_f32_16x16x32_bf16 v[36:39], v[208:211], v[182:185], 0
	v_mfma_f32_16x16x32_bf16 v[32:35], v[216:219], v[182:185], 0
	v_mfma_f32_16x16x32_bf16 v[20:23], v[208:211], v[190:193], 0
	v_mfma_f32_16x16x32_bf16 v[16:19], v[216:219], v[190:193], 0
	v_mfma_f32_16x16x32_bf16 v[4:7], v[208:211], v[198:201], 0
	v_mfma_f32_16x16x32_bf16 v[0:3], v[216:219], v[198:201], 0
	v_mfma_f32_16x16x32_bf16 v[52:55], v[212:215], v[166:169], v[52:55]
	v_mfma_f32_16x16x32_bf16 v[48:51], v[220:223], v[166:169], v[48:51]
	v_mfma_f32_16x16x32_bf16 v[36:39], v[212:215], v[186:189], v[36:39]
	v_mfma_f32_16x16x32_bf16 v[32:35], v[220:223], v[186:189], v[32:35]
	v_mfma_f32_16x16x32_bf16 v[20:23], v[212:215], v[194:197], v[20:23]
	v_mfma_f32_16x16x32_bf16 v[16:19], v[220:223], v[194:197], v[16:19]
	v_mfma_f32_16x16x32_bf16 v[4:7], v[212:215], v[202:205], v[4:7]
	v_mfma_f32_16x16x32_bf16 v[0:3], v[220:223], v[202:205], v[0:3]
	s_setprio 0
	s_add_i32 s50, 0, 0x18000
	v_add_u32_e32 v140, s50, v173
	s_barrier
	ds_read_b128 v[128:131], v140
	ds_read_b128 v[132:135], v140 offset:1024
	ds_read_b128 v[136:139], v140 offset:2048
	ds_read_b128 v[140:143], v140 offset:3072
	s_add_u32 s30, s30, 0x40000
	s_addc_u32 s31, s31, 0
	s_mov_b32 m0, s33
	v_lshl_add_u64 v[208:209], s[30:31], 0, v[144:145]
	ds_read_b128 v[162:165], v177 offset:32768
	ds_read_b128 v[166:169], v177 offset:33792
	ds_read_b128 v[182:185], v177 offset:34816
	ds_read_b128 v[186:189], v177 offset:35840
	ds_read_b128 v[190:193], v177 offset:36864
	ds_read_b128 v[194:197], v177 offset:37888
	ds_read_b128 v[198:201], v177 offset:38912
	ds_read_b128 v[202:205], v177 offset:39936
	global_load_lds_dwordx4 v[208:209], off
	v_lshl_add_u64 v[208:209], s[30:31], 0, v[148:149]
	s_mov_b32 m0, s34
	s_nop 0
	global_load_lds_dwordx4 v[208:209], off
	s_waitcnt lgkmcnt(8)
	s_barrier
	s_waitcnt lgkmcnt(0)
	s_setprio 1
	v_mfma_f32_16x16x32_bf16 v[124:127], v[128:131], v[162:165], v[124:127]
	v_mfma_f32_16x16x32_bf16 v[120:123], v[136:139], v[162:165], v[120:123]
	v_mfma_f32_16x16x32_bf16 v[108:111], v[128:131], v[182:185], v[108:111]
	v_mfma_f32_16x16x32_bf16 v[104:107], v[136:139], v[182:185], v[104:107]
	v_mfma_f32_16x16x32_bf16 v[92:95], v[128:131], v[190:193], v[92:95]
	v_mfma_f32_16x16x32_bf16 v[88:91], v[136:139], v[190:193], v[88:91]
	v_mfma_f32_16x16x32_bf16 v[76:79], v[128:131], v[198:201], v[76:79]
	v_mfma_f32_16x16x32_bf16 v[72:75], v[136:139], v[198:201], v[72:75]
	v_mfma_f32_16x16x32_bf16 v[124:127], v[132:135], v[166:169], v[124:127]
	v_mfma_f32_16x16x32_bf16 v[120:123], v[140:143], v[166:169], v[120:123]
	v_mfma_f32_16x16x32_bf16 v[108:111], v[132:135], v[186:189], v[108:111]
	v_mfma_f32_16x16x32_bf16 v[104:107], v[140:143], v[186:189], v[104:107]
	v_mfma_f32_16x16x32_bf16 v[92:95], v[132:135], v[194:197], v[92:95]
	v_mfma_f32_16x16x32_bf16 v[88:91], v[140:143], v[194:197], v[88:91]
	v_mfma_f32_16x16x32_bf16 v[76:79], v[132:135], v[202:205], v[76:79]
	v_mfma_f32_16x16x32_bf16 v[72:75], v[140:143], v[202:205], v[72:75]
	s_setprio 0
	s_barrier
	s_add_i32 s30, 0, 0x1c000
	s_add_i32 s31, s50, s3
	v_add_u32_e32 v152, s30, v173
	v_lshl_add_u64 v[170:171], v[170:171], 0, s[14:15]
	s_mov_b32 m0, s31
	ds_read_b128 v[208:211], v152
	ds_read_b128 v[212:215], v152 offset:1024
	ds_read_b128 v[216:219], v152 offset:2048
	ds_read_b128 v[220:223], v152 offset:3072
	global_load_lds_dwordx4 v[170:171], off
	v_lshl_add_u64 v[170:171], v[224:225], 0, s[14:15]
	s_add_i32 m0, s31, 0x2000
	s_nop 0
	global_load_lds_dwordx4 v[170:171], off
	s_barrier
; #define PG8_STAGE(bufoff, gbase, voff) do { _Pragma("unroll") for (int _i = 0; _i < 2; ++_i) \
;         __builtin_amdgcn_global_load_lds((const unsigned*)((const char*)(gbase) + (voff)[_i]), (PG8_LAS unsigned*)(lds + (bufoff) + ldsw + _i * 8192), 16, 0, 0); } while (0)
; #define PG8_LDA(dst, b, h) do { _Pragma("unroll") for (int m = 0; m < 4; ++m) _Pragma("unroll") for (int k = 0; k < 2; ++k) dst[m][k] = *(const PG8_LAS bf16x8*)(lds + PG8_SA(b, h) + aoff + m * 2048 + k * 1024); } while (0)
; #define PG8_MMA(ai, bj, At, Bt) do { __builtin_amdgcn_s_setprio(1); _Pragma("unroll") for (int m = 0; m < 4; ++m) _Pragma("unroll") for (int n = 0; n < 2; ++n) _Pragma("unroll") for (int k = 0; k < 2; ++k) \
;         acc[ai][bj][m][n] = __builtin_amdgcn_mfma_f32_16x16x32_bf16(Bt[n][k], At[m][k], acc[ai][bj][m][n], 0, 0, 0); __builtin_amdgcn_s_setprio(0); } while (0)
; #define PG8_WAIT_V(n) asm volatile("s_waitcnt vmcnt(" #n ")" ::: "memory")
; #define PG8_WAIT_L(n) asm volatile("s_waitcnt lgkmcnt(" #n ")" ::: "memory")
; #define PG8_BAR __builtin_amdgcn_s_barrier()
; #define PG8_SCHED __builtin_amdgcn_sched_barrier(0)
; template <class Epi, class Sched>
; __device__ __forceinline__ void gemm_phase(PG8_LAS unsigned char* lds, const Gemm g, const Sched& S, const Epi& E) {
;     ...
;             PG8_BAR; PG8_WAIT_L(0); PG8_MMA(0, 1, At, B1); PG8_BAR;
;             PG8_LDA(At, 1, 1); PG8_STAGE(PG8_SA(1, 0), a3, voffA);
;             PG8_BAR; PG8_WAIT_L(0); PG8_MMA(1, 0, At, B0); PG8_BAR; PG8_SCHED;
;             PG8_STAGE(PG8_SB(1, 1), b3 + hstep, voffB);
;             PG8_WAIT_V(6); PG8_BAR; PG8_MMA(1, 1, At, B1); PG8_BAR;
	s_waitcnt lgkmcnt(0)
	s_setprio 1
	v_mfma_f32_16x16x32_bf16 v[116:119], v[208:211], v[162:165], v[116:119]
	v_mfma_f32_16x16x32_bf16 v[112:115], v[216:219], v[162:165], v[112:115]
	v_mfma_f32_16x16x32_bf16 v[100:103], v[208:211], v[182:185], v[100:103]
	v_mfma_f32_16x16x32_bf16 v[96:99], v[216:219], v[182:185], v[96:99]
	v_mfma_f32_16x16x32_bf16 v[84:87], v[208:211], v[190:193], v[84:87]
	v_mfma_f32_16x16x32_bf16 v[80:83], v[216:219], v[190:193], v[80:83]
	v_mfma_f32_16x16x32_bf16 v[68:71], v[208:211], v[198:201], v[68:71]
	v_mfma_f32_16x16x32_bf16 v[64:67], v[216:219], v[198:201], v[64:67]
	v_mfma_f32_16x16x32_bf16 v[116:119], v[212:215], v[166:169], v[116:119]
	v_mfma_f32_16x16x32_bf16 v[112:115], v[220:223], v[166:169], v[112:115]
	v_mfma_f32_16x16x32_bf16 v[100:103], v[212:215], v[186:189], v[100:103]
	v_mfma_f32_16x16x32_bf16 v[96:99], v[220:223], v[186:189], v[96:99]
	v_mfma_f32_16x16x32_bf16 v[84:87], v[212:215], v[194:197], v[84:87]
	v_mfma_f32_16x16x32_bf16 v[80:83], v[220:223], v[194:197], v[80:83]
	v_mfma_f32_16x16x32_bf16 v[68:71], v[212:215], v[202:205], v[68:71]
	v_mfma_f32_16x16x32_bf16 v[64:67], v[220:223], v[202:205], v[64:67]
	s_setprio 0
	s_mov_b32 m0, s37
	v_lshl_add_u64 v[170:171], v[226:227], 0, s[14:15]
	s_barrier
	ds_read_b128 v[162:165], v177 offset:49152
	ds_read_b128 v[166:169], v177 offset:50176
	ds_read_b128 v[182:185], v177 offset:51200
	ds_read_b128 v[186:189], v177 offset:52224
	ds_read_b128 v[190:193], v177 offset:53248
	ds_read_b128 v[194:197], v177 offset:54272
	ds_read_b128 v[198:201], v177 offset:55296
	ds_read_b128 v[202:205], v177 offset:56320
	global_load_lds_dwordx4 v[170:171], off
	v_lshl_add_u64 v[170:171], v[228:229], 0, s[14:15]
	s_mov_b32 m0, s38
	s_nop 0
	global_load_lds_dwordx4 v[170:171], off
	s_barrier
	s_waitcnt lgkmcnt(0)
	s_setprio 1
	v_mfma_f32_16x16x32_bf16 v[60:63], v[128:131], v[162:165], v[60:63]
	v_mfma_f32_16x16x32_bf16 v[56:59], v[136:139], v[162:165], v[56:59]
	v_mfma_f32_16x16x32_bf16 v[44:47], v[128:131], v[182:185], v[44:47]
	v_mfma_f32_16x16x32_bf16 v[40:43], v[136:139], v[182:185], v[40:43]
	v_mfma_f32_16x16x32_bf16 v[28:31], v[128:131], v[190:193], v[28:31]
	v_mfma_f32_16x16x32_bf16 v[24:27], v[136:139], v[190:193], v[24:27]
	v_mfma_f32_16x16x32_bf16 v[12:15], v[128:131], v[198:201], v[12:15]
	v_mfma_f32_16x16x32_bf16 v[8:11], v[136:139], v[198:201], v[8:11]
	v_mfma_f32_16x16x32_bf16 v[60:63], v[132:135], v[166:169], v[60:63]
	v_mfma_f32_16x16x32_bf16 v[56:59], v[140:143], v[166:169], v[56:59]
	v_mfma_f32_16x16x32_bf16 v[44:47], v[132:135], v[186:189], v[44:47]
	v_mfma_f32_16x16x32_bf16 v[40:43], v[140:143], v[186:189], v[40:43]
	v_mfma_f32_16x16x32_bf16 v[28:31], v[132:135], v[194:197], v[28:31]
	v_mfma_f32_16x16x32_bf16 v[24:27], v[140:143], v[194:197], v[24:27]
	v_mfma_f32_16x16x32_bf16 v[12:15], v[132:135], v[202:205], v[12:15]
	v_mfma_f32_16x16x32_bf16 v[8:11], v[140:143], v[202:205], v[8:11]
	s_setprio 0
	s_barrier
	s_add_u32 s28, s28, 0x40080
	s_addc_u32 s29, s29, 0
	s_add_i32 s30, s30, s3
	v_lshl_add_u64 v[128:129], s[28:29], 0, v[146:147]
	s_mov_b32 m0, s30
	s_nop 0
	global_load_lds_dwordx4 v[128:129], off
	v_lshl_add_u64 v[128:129], s[28:29], 0, v[150:151]
	s_add_i32 m0, s30, 0x2000
	s_nop 0
	global_load_lds_dwordx4 v[128:129], off
	s_waitcnt vmcnt(6)
	s_barrier
	s_setprio 1
	v_mfma_f32_16x16x32_bf16 v[52:55], v[208:211], v[162:165], v[52:55]
	v_mfma_f32_16x16x32_bf16 v[48:51], v[216:219], v[162:165], v[48:51]
	v_mfma_f32_16x16x32_bf16 v[36:39], v[208:211], v[182:185], v[36:39]
	v_mfma_f32_16x16x32_bf16 v[32:35], v[216:219], v[182:185], v[32:35]
	v_mfma_f32_16x16x32_bf16 v[20:23], v[208:211], v[190:193], v[20:23]
	v_mfma_f32_16x16x32_bf16 v[16:19], v[216:219], v[190:193], v[16:19]
	v_mfma_f32_16x16x32_bf16 v[4:7], v[208:211], v[198:201], v[4:7]
	v_mfma_f32_16x16x32_bf16 v[0:3], v[216:219], v[198:201], v[0:3]
	v_mfma_f32_16x16x32_bf16 v[52:55], v[212:215], v[166:169], v[52:55]
	v_mfma_f32_16x16x32_bf16 v[48:51], v[220:223], v[166:169], v[48:51]
	v_mfma_f32_16x16x32_bf16 v[36:39], v[212:215], v[186:189], v[36:39]
	v_mfma_f32_16x16x32_bf16 v[32:35], v[220:223], v[186:189], v[32:35]
	v_mfma_f32_16x16x32_bf16 v[20:23], v[212:215], v[194:197], v[20:23]
	v_mfma_f32_16x16x32_bf16 v[16:19], v[220:223], v[194:197], v[16:19]
	v_mfma_f32_16x16x32_bf16 v[4:7], v[212:215], v[202:205], v[4:7]
	v_mfma_f32_16x16x32_bf16 v[0:3], v[220:223], v[202:205], v[0:3]
	s_setprio 0
	s_add_i32 s49, s49, 2
	s_add_u32 s26, s26, 0x100
	s_addc_u32 s27, s27, 0
	s_add_u32 s47, s47, 0x100
	s_addc_u32 s48, s48, 0
	s_cmp_gt_u32 s49, 13
	s_barrier
	s_cbranch_scc1 .Lpeel_x1_LBB0619

; __device__ __forceinline__ unsigned cvt_pk_bf16(float lo, float hi) { unsigned r; asm volatile("v_cvt_pk_bf16_f32 %0, %1, %2" : "=v"(r) : "v"(lo), "v"(hi)); return r; }
;     __device__ __forceinline__ void operator()(const f32x4 (&acc)[2][2][4][2], const Unit& u, int wr, int wc, int fr, int fq, const float (&epre)[1]) const {
;         const int row0 = u.pm * 256 + wr * 64 + fr, col0 = u.pn * 256 + wc * 32 + 8 * fq;
; #pragma unroll
;         for (int ai = 0; ai < 2; ++ai) {
;             float ssv[4];
;             f32x4 bv[4][2][2];
; #pragma unroll
;             for (int m = 0; m < 4; ++m) { const int row = row0 + ai * 128 + m * 16;
; #pragma unroll
;                 for (int bj = 0; bj < 2; ++bj) {
;                     if (BASEBF) { unpack8(*(const u32x4*)(HB + (size_t)row * DM + col0 + bj * 128), bv[m][bj][0], bv[m][bj][1]); }
;                     else { const float* bp = (row < MP ? base0 + (size_t)row * DM : base1 + (size_t)(row - MP) * DM) + col0 + bj * 128; bv[m][bj][0] = __builtin_nontemporal_load((const f32x4*)bp); bv[m][bj][1] = __builtin_nontemporal_load((const f32x4*)(bp + 4)); } } }
; #pragma unroll
;             for (int m = 0; m < 4; ++m) { const int row = row0 + ai * 128 + m * 16;
;                 float ss = 0.f;
; #pragma unroll
;                 for (int bj = 0; bj < 2; ++bj) { const f32x4 h0 = bv[m][bj][0] + acc[ai][bj][m][0], h1 = bv[m][bj][1] + acc[ai][bj][m][1];
;                     u32x4 w; w.x = cvt_pk_bf16(h0[0], h0[1]); w.y = cvt_pk_bf16(h0[2], h0[3]); w.z = cvt_pk_bf16(h1[0], h1[1]); w.w = cvt_pk_bf16(h1[2], h1[3]);
;                     *(u32x4*)(HBo + (size_t)row * DM + col0 + bj * 128) = w;
;                     ss += (h0[0] * h0[0] + h0[1] * h0[1]) + (h0[2] * h0[2] + h0[3] * h0[3]) + (h1[0] * h1[0] + h1[1] * h1[1]) + (h1[2] * h1[2] + h1[3] * h1[3]); }
.Lpeel_x1_LBB0619:
	v_lshl_add_u32 v164, s24, 8, v172
	v_ashrrev_i32_e32 v165, 31, v164
	v_add_u32_e32 v152, 0xffffc000, v164
	v_readlane_b32 s48, v247, 0
	v_lshl_or_b32 v128, s25, 8, v174
	v_lshlrev_b64 v[130:131], 12, v[152:153]
	v_readlane_b32 s49, v247, 1
	v_readlane_b32 s50, v247, 2
	v_readlane_b32 s51, v247, 3
	v_lshlrev_b64 v[132:133], 12, v[164:165]
	v_ashrrev_i32_e32 v129, 31, v128
	v_lshl_add_u64 v[130:131], s[50:51], 0, v[130:131]
	v_lshl_add_u64 v[132:133], s[48:49], 0, v[132:133]
	v_cmp_gt_i32_e32 vcc, s36, v164
	v_lshlrev_b64 v[166:167], 2, v[128:129]
	v_or_b32_e32 v232, 16, v164
	v_cndmask_b32_e32 v131, v131, v133, vcc
	v_cndmask_b32_e32 v130, v130, v132, vcc
	v_lshl_add_u64 v[130:131], v[130:131], 0, v[166:167]
	global_load_dwordx4 v[182:185], v[130:131], off nt
	global_load_dwordx4 v[186:189], v[130:131], off offset:16 nt
	global_load_dwordx4 v[190:193], v[130:131], off offset:512 nt
	global_load_dwordx4 v[194:197], v[130:131], off offset:528 nt
	v_add_u32_e32 v152, 0xffffc010, v164
	v_ashrrev_i32_e32 v233, 31, v232
	v_lshlrev_b64 v[130:131], 12, v[152:153]
	v_lshlrev_b64 v[132:133], 12, v[232:233]
	v_lshl_add_u64 v[130:131], s[50:51], 0, v[130:131]
	v_lshl_add_u64 v[132:133], s[48:49], 0, v[132:133]
	v_cmp_gt_i32_e32 vcc, s36, v232
	v_or_b32_e32 v170, 32, v164
	v_ashrrev_i32_e32 v171, 31, v170
	v_cndmask_b32_e32 v131, v131, v133, vcc
	v_cndmask_b32_e32 v130, v130, v132, vcc
	v_lshl_add_u64 v[130:131], v[130:131], 0, v[166:167]
	global_load_dwordx4 v[198:201], v[130:131], off nt
	global_load_dwordx4 v[202:205], v[130:131], off offset:16 nt
	global_load_dwordx4 v[208:211], v[130:131], off offset:528 nt
	global_load_dwordx4 v[212:215], v[130:131], off offset:512 nt
	v_lshlrev_b64 v[132:133], 11, v[164:165]
	v_add_u32_e32 v152, 0xffffc020, v164
	v_lshlrev_b64 v[162:163], 1, v[128:129]
	v_lshlrev_b64 v[128:129], 12, v[170:171]
	v_lshl_add_u64 v[132:133], s[84:85], 0, v[132:133]
	v_lshlrev_b64 v[136:137], 12, v[152:153]
	v_lshl_add_u64 v[128:129], s[48:49], 0, v[128:129]
	v_lshl_add_u64 v[234:235], v[132:133], 0, v[162:163]
	v_lshl_add_u64 v[132:133], s[50:51], 0, v[136:137]
	v_cmp_gt_i32_e32 vcc, s36, v170
	v_or_b32_e32 v168, 48, v164
	v_ashrrev_i32_e32 v169, 31, v168
	v_cndmask_b32_e32 v129, v133, v129, vcc
	v_cndmask_b32_e32 v128, v132, v128, vcc
	v_lshl_add_u64 v[128:129], v[128:129], 0, v[166:167]
	global_load_dwordx4 v[216:219], v[128:129], off offset:16 nt
	global_load_dwordx4 v[220:223], v[128:129], off nt
	global_load_dwordx4 v[224:227], v[128:129], off offset:528 nt
	global_load_dwordx4 v[228:231], v[128:129], off offset:512 nt
	v_add_u32_e32 v152, 0xffffc030, v164
	v_lshlrev_b64 v[134:135], 12, v[168:169]
	v_lshlrev_b64 v[136:137], 12, v[152:153]
	v_lshl_add_u64 v[134:135], s[48:49], 0, v[134:135]
	v_lshl_add_u64 v[130:131], s[50:51], 0, v[136:137]
	v_cmp_gt_i32_e32 vcc, s36, v168
	v_readlane_b32 s52, v247, 4
	v_readlane_b32 s53, v247, 5
	v_cndmask_b32_e32 v131, v131, v135, vcc
	v_cndmask_b32_e32 v130, v130, v134, vcc
	v_lshl_add_u64 v[132:133], v[130:131], 0, v[166:167]
	global_load_dwordx4 v[136:139], v[132:133], off offset:16 nt
	global_load_dwordx4 v[140:143], v[132:133], off nt
	global_load_dwordx4 v[128:131], v[132:133], off offset:528 nt
	s_nop 0
	global_load_dwordx4 v[132:135], v[132:133], off offset:512 nt
	v_readlane_b32 s54, v247, 6
	v_readlane_b32 s55, v247, 7
	v_readlane_b32 s56, v247, 8
	v_readlane_b32 s57, v247, 9
	v_readlane_b32 s58, v247, 10
	v_readlane_b32 s59, v247, 11
	v_readlane_b32 s60, v247, 12
	v_readlane_b32 s61, v247, 13
	v_readlane_b32 s62, v247, 14
	v_readlane_b32 s63, v247, 15
	s_waitcnt vmcnt(0)
	v_pk_add_f32 v[126:127], v[126:127], v[184:185]
	v_pk_add_f32 v[124:125], v[124:125], v[182:183]
	v_pk_add_f32 v[120:121], v[120:121], v[186:187]
	v_pk_add_f32 v[184:185], v[112:113], v[194:195]
	v_cvt_pk_bf16_f32 v112, v124, v125
	v_cvt_pk_bf16_f32 v113, v126, v127
	v_mul_f32_e32 v125, v125, v125
	v_mul_f32_e32 v127, v127, v127
	v_pk_add_f32 v[122:123], v[122:123], v[188:189]
	v_pk_add_f32 v[182:183], v[114:115], v[196:197]
	v_cvt_pk_bf16_f32 v114, v120, v121
	v_mul_f32_e32 v121, v121, v121
	v_fmac_f32_e32 v125, v124, v124
	v_fmac_f32_e32 v127, v126, v126
	v_cvt_pk_bf16_f32 v115, v122, v123
	v_mul_f32_e32 v123, v123, v123
	global_store_dwordx4 v[234:235], v[112:115], off
	v_fmac_f32_e32 v121, v120, v120
	v_fmac_f32_e32 v123, v122, v122
	v_add_f32_e32 v113, v125, v127
	v_add_f32_e32 v113, v113, v121
	v_pk_add_f32 v[118:119], v[118:119], v[192:193]
	v_pk_add_f32 v[116:117], v[116:117], v[190:191]
	v_add_f32_e32 v120, v123, v113
	v_cvt_pk_bf16_f32 v112, v116, v117
	v_cvt_pk_bf16_f32 v113, v118, v119
	v_cvt_pk_bf16_f32 v114, v184, v185
	v_cvt_pk_bf16_f32 v115, v182, v183
	global_store_dwordx4 v[234:235], v[112:115], off offset:256
	v_pk_add_f32 v[110:111], v[110:111], v[200:201]
	v_pk_add_f32 v[108:109], v[108:109], v[198:199]
	v_mul_f32_e32 v112, v117, v117
	v_mul_f32_e32 v113, v119, v119
	v_fmac_f32_e32 v112, v116, v116
	v_fmac_f32_e32 v113, v118, v118
	v_add_f32_e32 v112, v112, v113
	v_mul_f32_e32 v113, v185, v185
	v_fmac_f32_e32 v113, v184, v184
	v_add_f32_e32 v112, v112, v113
	v_mul_f32_e32 v113, v183, v183
	v_fmac_f32_e32 v113, v182, v182
	v_add_f32_e32 v112, v113, v112
	v_add_f32_e32 v118, v120, v112
	v_lshlrev_b64 v[112:113], 11, v[232:233]
	v_lshl_add_u64 v[112:113], s[84:85], 0, v[112:113]
	v_pk_add_f32 v[116:117], v[104:105], v[202:203]
	v_cvt_pk_bf16_f32 v104, v108, v109
	v_cvt_pk_bf16_f32 v105, v110, v111
	v_lshl_add_u64 v[112:113], v[112:113], 0, v[162:163]
	v_pk_add_f32 v[114:115], v[106:107], v[204:205]
; __device__ __forceinline__ unsigned cvt_pk_bf16(float lo, float hi) { unsigned r; asm volatile("v_cvt_pk_bf16_f32 %0, %1, %2" : "=v"(r) : "v"(lo), "v"(hi)); return r; }
;     __device__ __forceinline__ void operator()(const f32x4 (&acc)[2][2][4][2], const Unit& u, int wr, int wc, int fr, int fq, const float (&epre)[1]) const {
;     ...
;             for (int m = 0; m < 4; ++m) { const int row = row0 + ai * 128 + m * 16;
;                 float ss = 0.f;
; #pragma unroll
;                 for (int bj = 0; bj < 2; ++bj) { const f32x4 h0 = bv[m][bj][0] + acc[ai][bj][m][0], h1 = bv[m][bj][1] + acc[ai][bj][m][1];
;                     u32x4 w; w.x = cvt_pk_bf16(h0[0], h0[1]); w.y = cvt_pk_bf16(h0[2], h0[3]); w.z = cvt_pk_bf16(h1[0], h1[1]); w.w = cvt_pk_bf16(h1[2], h1[3]);
;                     *(u32x4*)(HBo + (size_t)row * DM + col0 + bj * 128) = w;
;                     ss += (h0[0] * h0[0] + h0[1] * h0[1]) + (h0[2] * h0[2] + h0[3] * h0[3]) + (h1[0] * h1[0] + h1[1] * h1[1]) + (h1[2] * h1[2] + h1[3] * h1[3]); }
;                 ssv[m] = ss;
;             }
; #pragma unroll
;             for (int m = 0; m < 4; ++m) ssv[m] += __shfl_xor(ssv[m], 16);
; #pragma unroll
;             for (int m = 0; m < 4; ++m) ssv[m] += __shfl_xor(ssv[m], 32);
;             if (fq == 0) {
; #pragma unroll
;                 for (int m = 0; m < 4; ++m) atomicAdd(sumsq + row0 + ai * 128 + m * 16, ssv[m]); }
	v_cvt_pk_bf16_f32 v106, v116, v117
	v_pk_add_f32 v[102:103], v[102:103], v[214:215]
	v_cvt_pk_bf16_f32 v107, v114, v115
	global_store_dwordx4 v[112:113], v[104:107], off
	v_pk_add_f32 v[100:101], v[100:101], v[212:213]
	v_pk_add_f32 v[94:95], v[94:95], v[222:223]
	v_mul_f32_e32 v104, v109, v109
	v_mul_f32_e32 v105, v111, v111
	v_fmac_f32_e32 v104, v108, v108
	v_fmac_f32_e32 v105, v110, v110
	v_add_f32_e32 v104, v104, v105
	v_mul_f32_e32 v105, v117, v117
	v_fmac_f32_e32 v105, v116, v116
	v_add_f32_e32 v104, v104, v105
	v_mul_f32_e32 v105, v115, v115
	v_fmac_f32_e32 v105, v114, v114
	v_pk_add_f32 v[106:107], v[96:97], v[208:209]
	v_cvt_pk_bf16_f32 v96, v100, v101
	v_cvt_pk_bf16_f32 v97, v102, v103
	v_add_f32_e32 v108, v105, v104
	v_pk_add_f32 v[104:105], v[98:99], v[210:211]
	v_cvt_pk_bf16_f32 v98, v106, v107
	v_pk_add_f32 v[92:93], v[92:93], v[220:221]
	v_cvt_pk_bf16_f32 v99, v104, v105
	global_store_dwordx4 v[112:113], v[96:99], off offset:256
	v_pk_add_f32 v[86:87], v[86:87], v[230:231]
	v_pk_add_f32 v[84:85], v[84:85], v[228:229]
	v_mul_f32_e32 v96, v101, v101
	v_mul_f32_e32 v97, v103, v103
	v_fmac_f32_e32 v96, v100, v100
	v_fmac_f32_e32 v97, v102, v102
	v_add_f32_e32 v96, v96, v97
	v_mul_f32_e32 v97, v107, v107
	v_fmac_f32_e32 v97, v106, v106
	v_add_f32_e32 v96, v96, v97
	v_mul_f32_e32 v97, v105, v105
	v_fmac_f32_e32 v97, v104, v104
	v_add_f32_e32 v96, v97, v96
	v_add_f32_e32 v102, v108, v96
	v_lshlrev_b64 v[96:97], 11, v[170:171]
	v_lshl_add_u64 v[96:97], s[84:85], 0, v[96:97]
	v_pk_add_f32 v[100:101], v[88:89], v[216:217]
	v_cvt_pk_bf16_f32 v88, v92, v93
	v_cvt_pk_bf16_f32 v89, v94, v95
	v_lshl_add_u64 v[96:97], v[96:97], 0, v[162:163]
	v_pk_add_f32 v[98:99], v[90:91], v[218:219]
	v_cvt_pk_bf16_f32 v90, v100, v101
	v_pk_add_f32 v[78:79], v[78:79], v[142:143]
	v_cvt_pk_bf16_f32 v91, v98, v99
	global_store_dwordx4 v[96:97], v[88:91], off
	v_pk_add_f32 v[76:77], v[76:77], v[140:141]
	v_pk_add_f32 v[70:71], v[70:71], v[134:135]
	v_mul_f32_e32 v88, v93, v93
	v_mul_f32_e32 v89, v95, v95
	v_fmac_f32_e32 v88, v92, v92
	v_fmac_f32_e32 v89, v94, v94
	v_add_f32_e32 v88, v88, v89
	v_mul_f32_e32 v89, v101, v101
	v_fmac_f32_e32 v89, v100, v100
	v_add_f32_e32 v88, v88, v89
	v_mul_f32_e32 v89, v99, v99
	v_fmac_f32_e32 v89, v98, v98
	v_pk_add_f32 v[90:91], v[80:81], v[224:225]
	v_cvt_pk_bf16_f32 v80, v84, v85
	v_cvt_pk_bf16_f32 v81, v86, v87
	v_add_f32_e32 v92, v89, v88
	v_pk_add_f32 v[88:89], v[82:83], v[226:227]
	v_cvt_pk_bf16_f32 v82, v90, v91
	v_pk_add_f32 v[68:69], v[68:69], v[132:133]
	v_cvt_pk_bf16_f32 v83, v88, v89
	global_store_dwordx4 v[96:97], v[80:83], off offset:256
	s_nop 1
	v_mul_f32_e32 v80, v85, v85
	v_mul_f32_e32 v81, v87, v87
	v_fmac_f32_e32 v80, v84, v84
	v_fmac_f32_e32 v81, v86, v86
	v_add_f32_e32 v80, v80, v81
	v_mul_f32_e32 v81, v91, v91
	v_fmac_f32_e32 v81, v90, v90
	v_add_f32_e32 v80, v80, v81
	v_mul_f32_e32 v81, v89, v89
	v_fmac_f32_e32 v81, v88, v88
	v_add_f32_e32 v80, v81, v80
	v_add_f32_e32 v87, v92, v80
	v_lshlrev_b64 v[80:81], 11, v[168:169]
	v_lshl_add_u64 v[80:81], s[84:85], 0, v[80:81]
	v_pk_add_f32 v[82:83], v[74:75], v[138:139]
	v_pk_add_f32 v[84:85], v[72:73], v[136:137]
	v_cvt_pk_bf16_f32 v72, v76, v77
	v_cvt_pk_bf16_f32 v73, v78, v79
	v_lshl_add_u64 v[80:81], v[80:81], 0, v[162:163]
	v_cvt_pk_bf16_f32 v74, v84, v85
	v_cvt_pk_bf16_f32 v75, v82, v83
	global_store_dwordx4 v[80:81], v[72:75], off
	s_nop 1
	v_mul_f32_e32 v72, v77, v77
	v_mul_f32_e32 v73, v79, v79
	v_pk_add_f32 v[74:75], v[64:65], v[128:129]
	v_mul_f32_e32 v64, v69, v69
	v_mul_f32_e32 v65, v71, v71
	v_fmac_f32_e32 v72, v76, v76
	v_fmac_f32_e32 v73, v78, v78
	v_fmac_f32_e32 v64, v68, v68
	v_fmac_f32_e32 v65, v70, v70
	v_add_f32_e32 v72, v72, v73
	v_mul_f32_e32 v73, v85, v85
	v_add_f32_e32 v64, v64, v65
	v_mul_f32_e32 v65, v75, v75
	v_fmac_f32_e32 v73, v84, v84
	v_pk_add_f32 v[76:77], v[66:67], v[130:131]
	v_fmac_f32_e32 v65, v74, v74
	v_add_f32_e32 v72, v72, v73
	v_mul_f32_e32 v73, v83, v83
	v_add_f32_e32 v64, v64, v65
	v_mul_f32_e32 v65, v77, v77
	v_fmac_f32_e32 v73, v82, v82
	v_fmac_f32_e32 v65, v76, v76
	v_add_f32_e32 v73, v73, v72
	v_add_f32_e32 v64, v65, v64
	v_and_b32_e32 v65, 64, v181
	v_cvt_pk_bf16_f32 v72, v68, v69
	v_add_f32_e32 v67, v73, v64
	v_xor_b32_e32 v64, 16, v181
	v_add_u32_e32 v68, 64, v65
	v_cmp_lt_i32_e32 vcc, v64, v68
	v_cvt_pk_bf16_f32 v73, v70, v71
	v_cvt_pk_bf16_f32 v74, v74, v75
	v_cvt_pk_bf16_f32 v75, v76, v77
	global_store_dwordx4 v[80:81], v[72:75], off offset:256
	v_lshl_add_u64 v[80:81], v[164:165], 2, s[10:11]
	v_cndmask_b32_e32 v64, v181, v64, vcc
	v_lshlrev_b32_e32 v86, 2, v64
	ds_bpermute_b32 v69, v86, v67
	ds_bpermute_b32 v64, v86, v118
	ds_bpermute_b32 v65, v86, v102
	ds_bpermute_b32 v66, v86, v87
	s_waitcnt lgkmcnt(0)
	v_add_f32_e32 v67, v67, v69
	v_xor_b32_e32 v69, 32, v181
	v_cmp_lt_i32_e32 vcc, v69, v68
	v_add_f32_e32 v64, v118, v64
	v_add_f32_e32 v65, v102, v65
	v_cndmask_b32_e32 v68, v181, v69, vcc
	v_add_f32_e32 v66, v87, v66
	v_lshlrev_b32_e32 v87, 2, v68
	ds_bpermute_b32 v68, v87, v64
	ds_bpermute_b32 v69, v87, v65
	ds_bpermute_b32 v70, v87, v66
	ds_bpermute_b32 v71, v87, v67
	s_and_saveexec_b64 s[24:25], s[6:7]
	s_cbranch_execz .LBB0_622
	s_waitcnt lgkmcnt(3)
	v_add_f32_e32 v64, v64, v68
	s_waitcnt lgkmcnt(0)
	v_add_f32_e32 v67, v67, v71
	v_add_f32_e32 v66, v66, v70
	v_add_f32_e32 v65, v65, v69
	global_atomic_add_f32 v[80:81], v64, off
	global_atomic_add_f32 v[80:81], v65, off offset:64
	global_atomic_add_f32 v[80:81], v66, off offset:128
	global_atomic_add_f32 v[80:81], v67, off offset:192

; #define PG8_STAGE(bufoff, gbase, voff) do { _Pragma("unroll") for (int _i = 0; _i < 2; ++_i) \
;         __builtin_amdgcn_global_load_lds((const unsigned*)((const char*)(gbase) + (voff)[_i]), (PG8_LAS unsigned*)(lds + (bufoff) + ldsw + _i * 8192), 16, 0, 0); } while (0)
; #define PG8_LDA(dst, b, h) do { _Pragma("unroll") for (int m = 0; m < 4; ++m) _Pragma("unroll") for (int k = 0; k < 2; ++k) dst[m][k] = *(const PG8_LAS bf16x8*)(lds + PG8_SA(b, h) + aoff + m * 2048 + k * 1024); } while (0)
; #define PG8_LDB(dst, b, h) do { _Pragma("unroll") for (int n = 0; n < 2; ++n) _Pragma("unroll") for (int k = 0; k < 2; ++k) dst[n][k] = *(const PG8_LAS bf16x8*)(lds + PG8_SB(b, h) + boff + n * 2048 + k * 1024); } while (0)
; #define PG8_MMA(ai, bj, At, Bt) do { __builtin_amdgcn_s_setprio(1); _Pragma("unroll") for (int m = 0; m < 4; ++m) _Pragma("unroll") for (int n = 0; n < 2; ++n) _Pragma("unroll") for (int k = 0; k < 2; ++k) \
;         acc[ai][bj][m][n] = __builtin_amdgcn_mfma_f32_16x16x32_bf16(Bt[n][k], At[m][k], acc[ai][bj][m][n], 0, 0, 0); __builtin_amdgcn_s_setprio(0); } while (0)
; template <class Epi, class Sched>
; __device__ __forceinline__ void gemm_phase(PG8_LAS unsigned char* lds, const Gemm g, const Sched& S, const Epi& E) {
;     ...
;         const bool has_next = S.next(ui + 1, nxt);
;         const char* nA = has_next ? (const char*)g.A + (size_t)nxt.pm * tstep : cA; const char* nB = has_next ? (const char*)g.Bt + (size_t)nxt.pn * tstep : cB;
;         for (int t = 0; t < nt; t += 2) {
;             const bool last = (t == nt - 2);
;             const char* a1 = cA + (size_t)(t + 1) * kstep;
;             const char* a2 = last ? nA : cA + (size_t)(t + 2) * kstep; const char* b2 = last ? nB : cB + (size_t)(t + 2) * kstep;
;             const char* a3 = a2 + kstep; const char* b3 = b2 + kstep;
;             if (last && has_next) S.a_ready(nxt);
;             PG8_LDB(B0, 0, 0); PG8_SCHED; PG8_LDA(At, 0, 0); PG8_STAGE(PG8_SA(1, 1), a1 + hstep, voffA);
;             PG8_WAIT_L(8); PG8_BAR; PG8_WAIT_L(0); PG8_MMA(0, 0, At, B0); PG8_BAR; PG8_SCHED;
;             PG8_LDB(B1, 0, 1); PG8_STAGE(PG8_SB(0, 0), b2, voffB);
;             PG8_BAR; PG8_WAIT_L(0); PG8_MMA(0, 1, At, B1); PG8_BAR;
;             PG8_LDA(At, 0, 1); PG8_STAGE(PG8_SA(0, 0), a2, voffA);
;             PG8_BAR; PG8_WAIT_L(0); PG8_MMA(1, 0, At, B0); PG8_BAR; PG8_SCHED;
.LBB0_701:
	s_ashr_i32 s13, s12, 31
	s_lshl_b64 s[14:15], s[12:13], 19
	s_add_u32 s14, s84, s14
	s_addc_u32 s15, s85, s15
	s_and_b64 s[18:19], s[16:17], exec
	s_cselect_b32 s13, s15, s25
	s_cselect_b32 s21, s14, s24
	s_ashr_i32 s9, s8, 31
	s_lshl_b64 s[18:19], s[8:9], 19
	s_add_u32 s18, s1, s18
	s_addc_u32 s19, s3, s19
	s_and_b64 s[28:29], s[16:17], exec
	s_cselect_b32 s9, s19, s27
	s_cselect_b32 s42, s18, s26
	s_add_u32 s24, s24, 0x40080
	s_addc_u32 s25, s25, 0
	s_add_u32 s43, s26, 0x100
	s_addc_u32 s44, s27, 0
	s_mov_b32 s45, -2
	ds_read_b128 v[158:161], v146
	ds_read_b128 v[162:165], v146 offset:1024
	ds_read_b128 v[166:169], v146 offset:2048
	ds_read_b128 v[170:173], v146 offset:3072
	s_add_u32 s26, s24, 0xfffc0080
	s_addc_u32 s27, s25, -1
	s_cmp_eq_u32 s45, 12
	s_cselect_b32 s29, s13, s27
	s_cselect_b32 s28, s21, s26
	s_cselect_b32 s27, s9, s44
	s_cselect_b32 s26, s42, s43
	v_lshl_add_u64 v[174:175], s[24:25], 0, v[136:137]
	s_add_i32 m0, s5, 0xc000
	ds_read_b128 v[180:183], v147
	ds_read_b128 v[184:187], v147 offset:1024
	ds_read_b128 v[188:191], v147 offset:2048
	ds_read_b128 v[192:195], v147 offset:3072
	ds_read_b128 v[196:199], v147 offset:4096
	ds_read_b128 v[200:203], v147 offset:5120
	ds_read_b128 v[208:211], v147 offset:6144
	ds_read_b128 v[212:215], v147 offset:7168
	global_load_lds_dwordx4 v[174:175], off
	v_lshl_add_u64 v[174:175], s[24:25], 0, v[138:139]
	s_add_i32 m0, s5, 0xe000
	s_nop 0
	global_load_lds_dwordx4 v[174:175], off
	s_waitcnt lgkmcnt(8)
	s_barrier
	s_waitcnt lgkmcnt(0)
	s_setprio 1
	v_mfma_f32_16x16x32_bf16 v[124:127], v[158:161], v[180:183], 0
	v_mfma_f32_16x16x32_bf16 v[116:119], v[166:169], v[180:183], 0
	v_mfma_f32_16x16x32_bf16 v[108:111], v[158:161], v[188:191], 0
	v_mfma_f32_16x16x32_bf16 v[100:103], v[166:169], v[188:191], 0
	v_mfma_f32_16x16x32_bf16 v[92:95], v[158:161], v[196:199], 0
	v_mfma_f32_16x16x32_bf16 v[84:87], v[166:169], v[196:199], 0
	v_mfma_f32_16x16x32_bf16 v[76:79], v[158:161], v[208:211], 0
	v_mfma_f32_16x16x32_bf16 v[68:71], v[166:169], v[208:211], 0
	v_mfma_f32_16x16x32_bf16 v[124:127], v[162:165], v[184:187], v[124:127]
	v_mfma_f32_16x16x32_bf16 v[116:119], v[170:173], v[184:187], v[116:119]
	v_mfma_f32_16x16x32_bf16 v[108:111], v[162:165], v[192:195], v[108:111]
	v_mfma_f32_16x16x32_bf16 v[100:103], v[170:173], v[192:195], v[100:103]
	v_mfma_f32_16x16x32_bf16 v[92:95], v[162:165], v[200:203], v[92:95]
	v_mfma_f32_16x16x32_bf16 v[84:87], v[170:173], v[200:203], v[84:87]
	v_mfma_f32_16x16x32_bf16 v[76:79], v[162:165], v[212:215], v[76:79]
	v_mfma_f32_16x16x32_bf16 v[68:71], v[170:173], v[212:215], v[68:71]
	s_setprio 0
	s_barrier
	s_add_i32 s46, s38, s4
	v_lshl_add_u64 v[174:175], s[26:27], 0, v[130:131]
	s_mov_b32 m0, s46
	ds_read_b128 v[216:219], v148
	ds_read_b128 v[220:223], v148 offset:1024
	ds_read_b128 v[224:227], v148 offset:2048
	ds_read_b128 v[228:231], v148 offset:3072
	global_load_lds_dwordx4 v[174:175], off
	v_lshl_add_u64 v[204:205], s[26:27], 0, v[134:135]
	s_add_i32 m0, s46, 0x2000
	s_nop 0
	global_load_lds_dwordx4 v[204:205], off
	s_barrier
	s_waitcnt lgkmcnt(0)
	s_setprio 1
	v_mfma_f32_16x16x32_bf16 v[120:123], v[216:219], v[180:183], 0
	v_mfma_f32_16x16x32_bf16 v[112:115], v[224:227], v[180:183], 0
	v_mfma_f32_16x16x32_bf16 v[104:107], v[216:219], v[188:191], 0
	v_mfma_f32_16x16x32_bf16 v[96:99], v[224:227], v[188:191], 0
	v_mfma_f32_16x16x32_bf16 v[88:91], v[216:219], v[196:199], 0
	v_mfma_f32_16x16x32_bf16 v[80:83], v[224:227], v[196:199], 0
	v_mfma_f32_16x16x32_bf16 v[72:75], v[216:219], v[208:211], 0
	v_mfma_f32_16x16x32_bf16 v[64:67], v[224:227], v[208:211], 0
	v_mfma_f32_16x16x32_bf16 v[120:123], v[220:223], v[184:187], v[120:123]
	v_mfma_f32_16x16x32_bf16 v[112:115], v[228:231], v[184:187], v[112:115]
	v_mfma_f32_16x16x32_bf16 v[104:107], v[220:223], v[192:195], v[104:107]
	v_mfma_f32_16x16x32_bf16 v[96:99], v[228:231], v[192:195], v[96:99]
	v_mfma_f32_16x16x32_bf16 v[88:91], v[220:223], v[200:203], v[88:91]
	v_mfma_f32_16x16x32_bf16 v[80:83], v[228:231], v[200:203], v[80:83]
	v_mfma_f32_16x16x32_bf16 v[72:75], v[220:223], v[212:215], v[72:75]
	v_mfma_f32_16x16x32_bf16 v[64:67], v[228:231], v[212:215], v[64:67]
	s_setprio 0
	s_mov_b32 m0, s5
	v_lshl_add_u64 v[232:233], s[28:29], 0, v[128:129]
	s_barrier
	ds_read_b128 v[180:183], v147 offset:16384
	ds_read_b128 v[184:187], v147 offset:17408
	ds_read_b128 v[188:191], v147 offset:18432
	ds_read_b128 v[192:195], v147 offset:19456
	ds_read_b128 v[196:199], v147 offset:20480
	ds_read_b128 v[200:203], v147 offset:21504
	ds_read_b128 v[208:211], v147 offset:22528
	ds_read_b128 v[212:215], v147 offset:23552
	global_load_lds_dwordx4 v[232:233], off
	v_lshl_add_u64 v[234:235], s[28:29], 0, v[132:133]
	s_mov_b32 m0, s23
	s_nop 0
	global_load_lds_dwordx4 v[234:235], off
	s_barrier
	s_waitcnt lgkmcnt(0)
	s_setprio 1
	v_mfma_f32_16x16x32_bf16 v[60:63], v[158:161], v[180:183], 0
	v_mfma_f32_16x16x32_bf16 v[52:55], v[166:169], v[180:183], 0
	v_mfma_f32_16x16x32_bf16 v[44:47], v[158:161], v[188:191], 0
	v_mfma_f32_16x16x32_bf16 v[36:39], v[166:169], v[188:191], 0
	v_mfma_f32_16x16x32_bf16 v[28:31], v[158:161], v[196:199], 0
	v_mfma_f32_16x16x32_bf16 v[20:23], v[166:169], v[196:199], 0
	v_mfma_f32_16x16x32_bf16 v[12:15], v[158:161], v[208:211], 0
	v_mfma_f32_16x16x32_bf16 v[4:7], v[166:169], v[208:211], 0
	v_mfma_f32_16x16x32_bf16 v[60:63], v[162:165], v[184:187], v[60:63]
	v_mfma_f32_16x16x32_bf16 v[52:55], v[170:173], v[184:187], v[52:55]
	v_mfma_f32_16x16x32_bf16 v[44:47], v[162:165], v[192:195], v[44:47]
	v_mfma_f32_16x16x32_bf16 v[36:39], v[170:173], v[192:195], v[36:39]
	v_mfma_f32_16x16x32_bf16 v[28:31], v[162:165], v[200:203], v[28:31]
	v_mfma_f32_16x16x32_bf16 v[20:23], v[170:173], v[200:203], v[20:23]
	v_mfma_f32_16x16x32_bf16 v[12:15], v[162:165], v[212:215], v[12:15]
	v_mfma_f32_16x16x32_bf16 v[4:7], v[170:173], v[212:215], v[4:7]
	s_setprio 0
	s_barrier
; #define PG8_STAGE(bufoff, gbase, voff) do { _Pragma("unroll") for (int _i = 0; _i < 2; ++_i) \
;         __builtin_amdgcn_global_load_lds((const unsigned*)((const char*)(gbase) + (voff)[_i]), (PG8_LAS unsigned*)(lds + (bufoff) + ldsw + _i * 8192), 16, 0, 0); } while (0)
; #define PG8_LDA(dst, b, h) do { _Pragma("unroll") for (int m = 0; m < 4; ++m) _Pragma("unroll") for (int k = 0; k < 2; ++k) dst[m][k] = *(const PG8_LAS bf16x8*)(lds + PG8_SA(b, h) + aoff + m * 2048 + k * 1024); } while (0)
; #define PG8_LDB(dst, b, h) do { _Pragma("unroll") for (int n = 0; n < 2; ++n) _Pragma("unroll") for (int k = 0; k < 2; ++k) dst[n][k] = *(const PG8_LAS bf16x8*)(lds + PG8_SB(b, h) + boff + n * 2048 + k * 1024); } while (0)
; #define PG8_MMA(ai, bj, At, Bt) do { __builtin_amdgcn_s_setprio(1); _Pragma("unroll") for (int m = 0; m < 4; ++m) _Pragma("unroll") for (int n = 0; n < 2; ++n) _Pragma("unroll") for (int k = 0; k < 2; ++k) \
;         acc[ai][bj][m][n] = __builtin_amdgcn_mfma_f32_16x16x32_bf16(Bt[n][k], At[m][k], acc[ai][bj][m][n], 0, 0, 0); __builtin_amdgcn_s_setprio(0); } while (0)
; #define PG8_WAIT_V(n) asm volatile("s_waitcnt vmcnt(" #n ")" ::: "memory")
; #define PG8_WAIT_L(n) asm volatile("s_waitcnt lgkmcnt(" #n ")" ::: "memory")
; #define PG8_BAR __builtin_amdgcn_s_barrier()
; #define PG8_SCHED __builtin_amdgcn_sched_barrier(0)
; template <class Epi, class Sched>
; __device__ __forceinline__ void gemm_phase(PG8_LAS unsigned char* lds, const Gemm g, const Sched& S, const Epi& E) {
;     ...
;             PG8_STAGE(PG8_SB(0, 1), b2 + hstep, voffB);
;             PG8_WAIT_V(6); PG8_BAR; PG8_MMA(1, 1, At, B1); PG8_BAR;
;             PG8_LDB(B0, 1, 0); PG8_SCHED; PG8_LDA(At, 1, 0); PG8_STAGE(PG8_SA(0, 1), a2 + hstep, voffA);
;             PG8_WAIT_L(8); PG8_BAR; PG8_WAIT_L(0); PG8_MMA(0, 0, At, B0); PG8_BAR; PG8_SCHED;
;             PG8_LDB(B1, 1, 1); PG8_STAGE(PG8_SB(1, 0), b3, voffB);
	s_add_u32 s46, s26, 0x40000
	s_addc_u32 s47, s27, 0
	s_add_i32 s48, s39, s4
	v_lshl_add_u64 v[158:159], s[46:47], 0, v[130:131]
	s_mov_b32 m0, s48
	s_nop 0
	global_load_lds_dwordx4 v[158:159], off
	v_lshl_add_u64 v[158:159], s[46:47], 0, v[134:135]
	s_add_i32 m0, s48, 0x2000
	s_nop 0
	global_load_lds_dwordx4 v[158:159], off
	s_waitcnt vmcnt(6)
	s_barrier
	s_setprio 1
	v_mfma_f32_16x16x32_bf16 v[56:59], v[216:219], v[180:183], 0
	v_mfma_f32_16x16x32_bf16 v[48:51], v[224:227], v[180:183], 0
	v_mfma_f32_16x16x32_bf16 v[40:43], v[216:219], v[188:191], 0
	v_mfma_f32_16x16x32_bf16 v[32:35], v[224:227], v[188:191], 0
	v_mfma_f32_16x16x32_bf16 v[24:27], v[216:219], v[196:199], 0
	v_mfma_f32_16x16x32_bf16 v[16:19], v[224:227], v[196:199], 0
	v_mfma_f32_16x16x32_bf16 v[8:11], v[216:219], v[208:211], 0
	v_mfma_f32_16x16x32_bf16 v[0:3], v[224:227], v[208:211], 0
	v_mfma_f32_16x16x32_bf16 v[56:59], v[220:223], v[184:187], v[56:59]
	v_mfma_f32_16x16x32_bf16 v[48:51], v[228:231], v[184:187], v[48:51]
	v_mfma_f32_16x16x32_bf16 v[40:43], v[220:223], v[192:195], v[40:43]
	v_mfma_f32_16x16x32_bf16 v[32:35], v[228:231], v[192:195], v[32:35]
	v_mfma_f32_16x16x32_bf16 v[24:27], v[220:223], v[200:203], v[24:27]
	v_mfma_f32_16x16x32_bf16 v[16:19], v[228:231], v[200:203], v[16:19]
	v_mfma_f32_16x16x32_bf16 v[8:11], v[220:223], v[212:215], v[8:11]
	v_mfma_f32_16x16x32_bf16 v[0:3], v[228:231], v[212:215], v[0:3]
	s_setprio 0
	s_add_i32 s46, 0, 0x18000
	v_add_u32_e32 v157, s46, v144
	s_barrier
	ds_read_b128 v[158:161], v157
	ds_read_b128 v[162:165], v157 offset:1024
	ds_read_b128 v[166:169], v157 offset:2048
	ds_read_b128 v[170:173], v157 offset:3072
	s_add_u32 s28, s28, 0x40000
	s_addc_u32 s29, s29, 0
	s_mov_b32 m0, s30
	v_lshl_add_u64 v[216:217], s[28:29], 0, v[128:129]
	ds_read_b128 v[180:183], v147 offset:32768
	ds_read_b128 v[184:187], v147 offset:33792
	ds_read_b128 v[188:191], v147 offset:34816
	ds_read_b128 v[192:195], v147 offset:35840
	ds_read_b128 v[196:199], v147 offset:36864
	ds_read_b128 v[200:203], v147 offset:37888
	ds_read_b128 v[208:211], v147 offset:38912
	ds_read_b128 v[212:215], v147 offset:39936
	global_load_lds_dwordx4 v[216:217], off
	v_lshl_add_u64 v[216:217], s[28:29], 0, v[132:133]
	s_mov_b32 m0, s31
	s_nop 0
	global_load_lds_dwordx4 v[216:217], off
	s_waitcnt lgkmcnt(8)
	s_barrier
	s_waitcnt lgkmcnt(0)
	s_setprio 1
	v_mfma_f32_16x16x32_bf16 v[124:127], v[158:161], v[180:183], v[124:127]
	v_mfma_f32_16x16x32_bf16 v[116:119], v[166:169], v[180:183], v[116:119]
	v_mfma_f32_16x16x32_bf16 v[108:111], v[158:161], v[188:191], v[108:111]
	v_mfma_f32_16x16x32_bf16 v[100:103], v[166:169], v[188:191], v[100:103]
	v_mfma_f32_16x16x32_bf16 v[92:95], v[158:161], v[196:199], v[92:95]
	v_mfma_f32_16x16x32_bf16 v[84:87], v[166:169], v[196:199], v[84:87]
	v_mfma_f32_16x16x32_bf16 v[76:79], v[158:161], v[208:211], v[76:79]
	v_mfma_f32_16x16x32_bf16 v[68:71], v[166:169], v[208:211], v[68:71]
	v_mfma_f32_16x16x32_bf16 v[124:127], v[162:165], v[184:187], v[124:127]
	v_mfma_f32_16x16x32_bf16 v[116:119], v[170:173], v[184:187], v[116:119]
	v_mfma_f32_16x16x32_bf16 v[108:111], v[162:165], v[192:195], v[108:111]
	v_mfma_f32_16x16x32_bf16 v[100:103], v[170:173], v[192:195], v[100:103]
	v_mfma_f32_16x16x32_bf16 v[92:95], v[162:165], v[200:203], v[92:95]
	v_mfma_f32_16x16x32_bf16 v[84:87], v[170:173], v[200:203], v[84:87]
	v_mfma_f32_16x16x32_bf16 v[76:79], v[162:165], v[212:215], v[76:79]
	v_mfma_f32_16x16x32_bf16 v[68:71], v[170:173], v[212:215], v[68:71]
	s_setprio 0
	s_barrier
	s_add_i32 s28, 0, 0x1c000
	s_add_i32 s29, s46, s4
	v_add_u32_e32 v157, s28, v144
	v_lshl_add_u64 v[174:175], v[174:175], 0, s[6:7]
	s_mov_b32 m0, s29
	ds_read_b128 v[216:219], v157
	ds_read_b128 v[220:223], v157 offset:1024
	ds_read_b128 v[224:227], v157 offset:2048
	ds_read_b128 v[228:231], v157 offset:3072
	global_load_lds_dwordx4 v[174:175], off
	v_lshl_add_u64 v[174:175], v[204:205], 0, s[6:7]
	s_add_i32 m0, s29, 0x2000
	s_nop 0
	global_load_lds_dwordx4 v[174:175], off
	s_barrier
; #define PG8_STAGE(bufoff, gbase, voff) do { _Pragma("unroll") for (int _i = 0; _i < 2; ++_i) \
;         __builtin_amdgcn_global_load_lds((const unsigned*)((const char*)(gbase) + (voff)[_i]), (PG8_LAS unsigned*)(lds + (bufoff) + ldsw + _i * 8192), 16, 0, 0); } while (0)
; #define PG8_LDA(dst, b, h) do { _Pragma("unroll") for (int m = 0; m < 4; ++m) _Pragma("unroll") for (int k = 0; k < 2; ++k) dst[m][k] = *(const PG8_LAS bf16x8*)(lds + PG8_SA(b, h) + aoff + m * 2048 + k * 1024); } while (0)
; #define PG8_LDB(dst, b, h) do { _Pragma("unroll") for (int n = 0; n < 2; ++n) _Pragma("unroll") for (int k = 0; k < 2; ++k) dst[n][k] = *(const PG8_LAS bf16x8*)(lds + PG8_SB(b, h) + boff + n * 2048 + k * 1024); } while (0)
; #define PG8_MMA(ai, bj, At, Bt) do { __builtin_amdgcn_s_setprio(1); _Pragma("unroll") for (int m = 0; m < 4; ++m) _Pragma("unroll") for (int n = 0; n < 2; ++n) _Pragma("unroll") for (int k = 0; k < 2; ++k) \
;         acc[ai][bj][m][n] = __builtin_amdgcn_mfma_f32_16x16x32_bf16(Bt[n][k], At[m][k], acc[ai][bj][m][n], 0, 0, 0); __builtin_amdgcn_s_setprio(0); } while (0)
; #define PG8_WAIT_V(n) asm volatile("s_waitcnt vmcnt(" #n ")" ::: "memory")
; #define PG8_WAIT_L(n) asm volatile("s_waitcnt lgkmcnt(" #n ")" ::: "memory")
; #define PG8_BAR __builtin_amdgcn_s_barrier()
; #define PG8_SCHED __builtin_amdgcn_sched_barrier(0)
; template <class Epi, class Sched>
; __device__ __forceinline__ void gemm_phase(PG8_LAS unsigned char* lds, const Gemm g, const Sched& S, const Epi& E) {
;     ...
;             PG8_LDB(B1, 1, 1); PG8_STAGE(PG8_SB(1, 0), b3, voffB);
;             PG8_BAR; PG8_WAIT_L(0); PG8_MMA(0, 1, At, B1); PG8_BAR;
;             PG8_LDA(At, 1, 1); PG8_STAGE(PG8_SA(1, 0), a3, voffA);
;             PG8_BAR; PG8_WAIT_L(0); PG8_MMA(1, 0, At, B0); PG8_BAR; PG8_SCHED;
;             PG8_STAGE(PG8_SB(1, 1), b3 + hstep, voffB);
;             PG8_WAIT_V(6); PG8_BAR; PG8_MMA(1, 1, At, B1); PG8_BAR;
	s_waitcnt lgkmcnt(0)
	s_setprio 1
	v_mfma_f32_16x16x32_bf16 v[120:123], v[216:219], v[180:183], v[120:123]
	v_mfma_f32_16x16x32_bf16 v[112:115], v[224:227], v[180:183], v[112:115]
	v_mfma_f32_16x16x32_bf16 v[104:107], v[216:219], v[188:191], v[104:107]
	v_mfma_f32_16x16x32_bf16 v[96:99], v[224:227], v[188:191], v[96:99]
	v_mfma_f32_16x16x32_bf16 v[88:91], v[216:219], v[196:199], v[88:91]
	v_mfma_f32_16x16x32_bf16 v[80:83], v[224:227], v[196:199], v[80:83]
	v_mfma_f32_16x16x32_bf16 v[72:75], v[216:219], v[208:211], v[72:75]
	v_mfma_f32_16x16x32_bf16 v[64:67], v[224:227], v[208:211], v[64:67]
	v_mfma_f32_16x16x32_bf16 v[120:123], v[220:223], v[184:187], v[120:123]
	v_mfma_f32_16x16x32_bf16 v[112:115], v[228:231], v[184:187], v[112:115]
	v_mfma_f32_16x16x32_bf16 v[104:107], v[220:223], v[192:195], v[104:107]
	v_mfma_f32_16x16x32_bf16 v[96:99], v[228:231], v[192:195], v[96:99]
	v_mfma_f32_16x16x32_bf16 v[88:91], v[220:223], v[200:203], v[88:91]
	v_mfma_f32_16x16x32_bf16 v[80:83], v[228:231], v[200:203], v[80:83]
	v_mfma_f32_16x16x32_bf16 v[72:75], v[220:223], v[212:215], v[72:75]
	v_mfma_f32_16x16x32_bf16 v[64:67], v[228:231], v[212:215], v[64:67]
	s_setprio 0
	s_mov_b32 m0, s34
	v_lshl_add_u64 v[174:175], v[232:233], 0, s[6:7]
	s_barrier
	ds_read_b128 v[180:183], v147 offset:49152
	ds_read_b128 v[184:187], v147 offset:50176
	ds_read_b128 v[188:191], v147 offset:51200
	ds_read_b128 v[192:195], v147 offset:52224
	ds_read_b128 v[196:199], v147 offset:53248
	ds_read_b128 v[200:203], v147 offset:54272
	ds_read_b128 v[208:211], v147 offset:55296
	ds_read_b128 v[212:215], v147 offset:56320
	global_load_lds_dwordx4 v[174:175], off
	v_lshl_add_u64 v[174:175], v[234:235], 0, s[6:7]
	s_mov_b32 m0, s35
	s_nop 0
	global_load_lds_dwordx4 v[174:175], off
	s_barrier
	s_waitcnt lgkmcnt(0)
	s_setprio 1
	v_mfma_f32_16x16x32_bf16 v[60:63], v[158:161], v[180:183], v[60:63]
	v_mfma_f32_16x16x32_bf16 v[52:55], v[166:169], v[180:183], v[52:55]
	v_mfma_f32_16x16x32_bf16 v[44:47], v[158:161], v[188:191], v[44:47]
	v_mfma_f32_16x16x32_bf16 v[36:39], v[166:169], v[188:191], v[36:39]
	v_mfma_f32_16x16x32_bf16 v[28:31], v[158:161], v[196:199], v[28:31]
	v_mfma_f32_16x16x32_bf16 v[20:23], v[166:169], v[196:199], v[20:23]
	v_mfma_f32_16x16x32_bf16 v[12:15], v[158:161], v[208:211], v[12:15]
	v_mfma_f32_16x16x32_bf16 v[4:7], v[166:169], v[208:211], v[4:7]
	v_mfma_f32_16x16x32_bf16 v[60:63], v[162:165], v[184:187], v[60:63]
	v_mfma_f32_16x16x32_bf16 v[52:55], v[170:173], v[184:187], v[52:55]
	v_mfma_f32_16x16x32_bf16 v[44:47], v[162:165], v[192:195], v[44:47]
	v_mfma_f32_16x16x32_bf16 v[36:39], v[170:173], v[192:195], v[36:39]
	v_mfma_f32_16x16x32_bf16 v[28:31], v[162:165], v[200:203], v[28:31]
	v_mfma_f32_16x16x32_bf16 v[20:23], v[170:173], v[200:203], v[20:23]
	v_mfma_f32_16x16x32_bf16 v[12:15], v[162:165], v[212:215], v[12:15]
	v_mfma_f32_16x16x32_bf16 v[4:7], v[170:173], v[212:215], v[4:7]
	s_setprio 0
	s_barrier
	s_add_u32 s26, s26, 0x40080
	s_addc_u32 s27, s27, 0
	s_add_i32 s28, s28, s4
	v_lshl_add_u64 v[158:159], s[26:27], 0, v[130:131]
	s_mov_b32 m0, s28
	s_nop 0
	global_load_lds_dwordx4 v[158:159], off
	v_lshl_add_u64 v[158:159], s[26:27], 0, v[134:135]
	s_add_i32 m0, s28, 0x2000
	s_nop 0
	global_load_lds_dwordx4 v[158:159], off
	s_waitcnt vmcnt(6)
	s_barrier
	s_setprio 1
	v_mfma_f32_16x16x32_bf16 v[56:59], v[216:219], v[180:183], v[56:59]
	v_mfma_f32_16x16x32_bf16 v[48:51], v[224:227], v[180:183], v[48:51]
	v_mfma_f32_16x16x32_bf16 v[40:43], v[216:219], v[188:191], v[40:43]
	v_mfma_f32_16x16x32_bf16 v[32:35], v[224:227], v[188:191], v[32:35]
	v_mfma_f32_16x16x32_bf16 v[24:27], v[216:219], v[196:199], v[24:27]
	v_mfma_f32_16x16x32_bf16 v[16:19], v[224:227], v[196:199], v[16:19]
	v_mfma_f32_16x16x32_bf16 v[8:11], v[216:219], v[208:211], v[8:11]
	v_mfma_f32_16x16x32_bf16 v[0:3], v[224:227], v[208:211], v[0:3]
	v_mfma_f32_16x16x32_bf16 v[56:59], v[220:223], v[184:187], v[56:59]
	v_mfma_f32_16x16x32_bf16 v[48:51], v[228:231], v[184:187], v[48:51]
	v_mfma_f32_16x16x32_bf16 v[40:43], v[220:223], v[192:195], v[40:43]
	v_mfma_f32_16x16x32_bf16 v[32:35], v[228:231], v[192:195], v[32:35]
	v_mfma_f32_16x16x32_bf16 v[24:27], v[220:223], v[200:203], v[24:27]
	v_mfma_f32_16x16x32_bf16 v[16:19], v[228:231], v[200:203], v[16:19]
	v_mfma_f32_16x16x32_bf16 v[8:11], v[220:223], v[212:215], v[8:11]
	v_mfma_f32_16x16x32_bf16 v[0:3], v[228:231], v[212:215], v[0:3]
	s_setprio 0
	s_add_i32 s45, s45, 2
	s_add_u32 s24, s24, 0x100
	s_addc_u32 s25, s25, 0
	s_add_u32 s43, s43, 0x100
	s_addc_u32 s44, s44, 0
	s_cmp_gt_u32 s45, 13
	s_barrier
	s_cbranch_scc1 .Lpeel_x2_LBB0702

; __device__ __forceinline__ unsigned cvt_pk_bf16(float lo, float hi) { unsigned r; asm volatile("v_cvt_pk_bf16_f32 %0, %1, %2" : "=v"(r) : "v"(lo), "v"(hi)); return r; }
; __device__ __forceinline__ float frcp(float x) { return __builtin_amdgcn_rcpf(x); }
;     __device__ __forceinline__ void operator()(const f32x4 (&acc)[2][2][4][2], const Unit& u, int wr, int wc, int fr, int fq, const float (&epre)[8]) const {
;         const int row0 = u.pm * 256 + wr * 64 + fr, col0 = u.pn * 128 + wc * 32 + 8 * fq;
; #pragma unroll
;         for (int ai = 0; ai < 2; ++ai)
; #pragma unroll
;             for (int m = 0; m < 4; ++m) { const int row = row0 + ai * 128 + m * 16;
;                 const float rstd = rsqrtf(epre[ai * 4 + m] * (1.0f / DM) + EPS), c1 = -1.44269504f * rstd, c2 = rstd * rstd;
;                 f32x4 av[2];
; #pragma unroll
;                 for (int n = 0; n < 2; ++n) { const f32x4 g = acc[ai][0][m][n], t = g * c1; f32x4 e;
; #pragma unroll
;                     for (int j = 0; j < 4; ++j) e[j] = __builtin_amdgcn_exp2f(t[j]);
;                     const f32x4 d = e + 1.0f; f32x4 r;
; #pragma unroll
;                     for (int j = 0; j < 4; ++j) r[j] = frcp(d[j]);
;                     av[n] = (g * acc[ai][1][m][n]) * (r * c2); }
;                 u32x4 w; w.x = cvt_pk_bf16(av[0][0], av[0][1]); w.y = cvt_pk_bf16(av[0][2], av[0][3]); w.z = cvt_pk_bf16(av[1][0], av[1][1]); w.w = cvt_pk_bf16(av[1][2], av[1][3]);
;                 *(u32x4*)(ACT + (size_t)row * DFF + col0) = w; }
.Lpeel_x2_LBB0702:
	s_waitcnt vmcnt(0)
	v_fmamk_f32 v156, v156, 0x3a800000, v149
	v_mul_f32_e32 v157, 0x4b800000, v156
	v_cmp_gt_f32_e32 vcc, s40, v156
	v_pk_mul_f32 v[122:123], v[126:127], v[122:123]
	v_pk_mul_f32 v[120:121], v[124:125], v[120:121]
	v_cndmask_b32_e32 v156, v156, v157, vcc
	v_rsq_f32_e32 v157, v156
	v_pk_mul_f32 v[114:115], v[118:119], v[114:115]
	v_pk_mul_f32 v[112:113], v[116:117], v[112:113]
	v_lshl_or_b32 v158, s22, 7, v145
	v_mul_f32_e32 v160, 0x45800000, v157
	v_cndmask_b32_e32 v157, v157, v160, vcc
	v_mul_f32_e32 v160, 0xbfb8aa3b, v157
	v_pk_mul_f32 v[166:167], v[160:161], v[124:125] op_sel_hi:[0,1]
	v_mul_f32_e32 v162, v157, v157
	v_exp_f32_e32 v157, v166
	v_pk_mul_f32 v[164:165], v[160:161], v[126:127] op_sel_hi:[0,1]
	v_exp_f32_e32 v161, v167
	v_exp_f32_e32 v163, v164
	v_exp_f32_e32 v167, v165
	v_add_f32_e32 v157, 1.0, v157
	v_rcp_f32_e32 v164, v157
	v_add_f32_e32 v157, 1.0, v161
	v_rcp_f32_e32 v165, v157
	v_add_f32_e32 v157, 1.0, v163
	v_rcp_f32_e32 v166, v157
	v_add_f32_e32 v157, 1.0, v167
	v_rcp_f32_e32 v167, v157
	v_pk_mul_f32 v[124:125], v[162:163], v[164:165] op_sel_hi:[0,1]
	v_pk_mul_f32 v[120:121], v[124:125], v[120:121]
	v_pk_mul_f32 v[124:125], v[160:161], v[118:119] op_sel_hi:[0,1]
	v_pk_mul_f32 v[126:127], v[162:163], v[166:167] op_sel_hi:[0,1]
	v_pk_mul_f32 v[122:123], v[126:127], v[122:123]
	v_pk_mul_f32 v[126:127], v[160:161], v[116:117] op_sel_hi:[0,1]
	v_exp_f32_e32 v126, v126
	v_exp_f32_e32 v127, v127
	v_exp_f32_e32 v157, v124
	v_exp_f32_e32 v160, v125
	v_add_f32_e32 v124, 1.0, v126
	v_add_f32_e32 v125, 1.0, v127
	v_add_f32_e32 v126, 1.0, v157
	v_add_f32_e32 v127, 1.0, v160
	v_rcp_f32_e32 v126, v126
	v_rcp_f32_e32 v127, v127
	v_rcp_f32_e32 v124, v124
	v_rcp_f32_e32 v125, v125
	v_lshl_add_u32 v156, s20, 8, v143
	v_pk_mul_f32 v[118:119], v[162:163], v[126:127] op_sel_hi:[0,1]
	v_pk_mul_f32 v[114:115], v[118:119], v[114:115]
	v_pk_mul_f32 v[116:117], v[162:163], v[124:125] op_sel_hi:[0,1]
	v_pk_mul_f32 v[112:113], v[116:117], v[112:113]
	v_cvt_pk_bf16_f32 v116, v120, v121
	v_cvt_pk_bf16_f32 v117, v122, v123
	v_ashrrev_i32_e32 v159, 31, v158
	v_cvt_pk_bf16_f32 v118, v112, v113
	v_cvt_pk_bf16_f32 v119, v114, v115
	v_fmamk_f32 v114, v155, 0x3a800000, v149
	v_mul_f32_e32 v115, 0x4b800000, v114
	v_cmp_gt_f32_e32 vcc, s40, v114
	v_mov_b64_e32 v[112:113], s[82:83]
	v_mad_i64_i32 v[120:121], s[20:21], v156, s41, v[112:113]
	v_cndmask_b32_e32 v114, v114, v115, vcc
	v_rsq_f32_e32 v122, v114
	v_lshlrev_b64 v[114:115], 1, v[158:159]
	v_lshl_add_u64 v[120:121], v[120:121], 0, v[114:115]
	global_store_dwordx4 v[120:121], v[116:119], off
	v_pk_mul_f32 v[106:107], v[110:111], v[106:107]
	v_pk_mul_f32 v[104:105], v[108:109], v[104:105]
	v_mul_f32_e32 v116, 0x45800000, v122
	v_cndmask_b32_e32 v117, v122, v116, vcc
	v_mul_f32_e32 v116, 0xbfb8aa3b, v117
	v_pk_mul_f32 v[122:123], v[116:117], v[108:109] op_sel_hi:[0,1]
	v_mul_f32_e32 v118, v117, v117
	v_pk_mul_f32 v[120:121], v[116:117], v[110:111] op_sel_hi:[0,1]
	v_exp_f32_e32 v117, v122
	v_exp_f32_e32 v119, v123
	v_exp_f32_e32 v122, v120
	v_exp_f32_e32 v123, v121
	v_add_f32_e32 v117, 1.0, v117
	v_rcp_f32_e32 v120, v117
	v_add_f32_e32 v117, 1.0, v119
	v_rcp_f32_e32 v121, v117
	v_add_f32_e32 v117, 1.0, v122
	v_rcp_f32_e32 v122, v117
	v_add_f32_e32 v117, 1.0, v123
	v_rcp_f32_e32 v123, v117
	v_pk_mul_f32 v[108:109], v[118:119], v[120:121] op_sel_hi:[0,1]
	v_pk_mul_f32 v[104:105], v[108:109], v[104:105]
	v_pk_mul_f32 v[108:109], v[116:117], v[102:103] op_sel_hi:[0,1]
	v_pk_mul_f32 v[110:111], v[118:119], v[122:123] op_sel_hi:[0,1]
	v_pk_mul_f32 v[106:107], v[110:111], v[106:107]
	v_pk_mul_f32 v[110:111], v[116:117], v[100:101] op_sel_hi:[0,1]
	v_exp_f32_e32 v110, v110
	v_exp_f32_e32 v111, v111
	v_exp_f32_e32 v116, v108
	v_exp_f32_e32 v117, v109
	v_add_f32_e32 v108, 1.0, v110
	v_add_f32_e32 v109, 1.0, v111
	v_add_f32_e32 v110, 1.0, v116
	v_add_f32_e32 v111, 1.0, v117
	v_rcp_f32_e32 v108, v108
	v_rcp_f32_e32 v109, v109
	v_rcp_f32_e32 v110, v110
	v_rcp_f32_e32 v111, v111
	v_pk_mul_f32 v[98:99], v[102:103], v[98:99]
	v_pk_mul_f32 v[96:97], v[100:101], v[96:97]
	v_pk_mul_f32 v[100:101], v[118:119], v[108:109] op_sel_hi:[0,1]
	v_pk_mul_f32 v[102:103], v[118:119], v[110:111] op_sel_hi:[0,1]
	v_pk_mul_f32 v[102:103], v[102:103], v[98:99]
	v_pk_mul_f32 v[98:99], v[100:101], v[96:97]
	v_fmamk_f32 v101, v154, 0x3a800000, v149
	v_cvt_pk_bf16_f32 v96, v104, v105
	v_cvt_pk_bf16_f32 v97, v106, v107
	v_cvt_pk_bf16_f32 v98, v98, v99
	v_cvt_pk_bf16_f32 v99, v102, v103
	v_mul_f32_e32 v102, 0x4b800000, v101
	v_cmp_gt_f32_e32 vcc, s40, v101
	v_or_b32_e32 v100, 16, v156
	v_pk_mul_f32 v[90:91], v[94:95], v[90:91]
	v_cndmask_b32_e32 v101, v101, v102, vcc
	v_rsq_f32_e32 v102, v101
	v_mad_i64_i32 v[100:101], s[20:21], v100, s41, v[112:113]
	v_lshl_add_u64 v[100:101], v[100:101], 0, v[114:115]
	global_store_dwordx4 v[100:101], v[96:99], off
	v_pk_mul_f32 v[88:89], v[92:93], v[88:89]
	v_pk_mul_f32 v[82:83], v[86:87], v[82:83]
	v_mul_f32_e32 v96, 0x45800000, v102
	v_cndmask_b32_e32 v97, v102, v96, vcc
	v_mul_f32_e32 v96, 0xbfb8aa3b, v97
	v_pk_mul_f32 v[102:103], v[96:97], v[92:93] op_sel_hi:[0,1]
	v_mul_f32_e32 v98, v97, v97
	v_pk_mul_f32 v[100:101], v[96:97], v[94:95] op_sel_hi:[0,1]
	v_exp_f32_e32 v97, v102
	v_exp_f32_e32 v99, v103
	v_exp_f32_e32 v102, v100
	v_exp_f32_e32 v103, v101
	v_add_f32_e32 v97, 1.0, v97
	v_rcp_f32_e32 v100, v97
	v_add_f32_e32 v97, 1.0, v99
	v_rcp_f32_e32 v101, v97
	v_add_f32_e32 v97, 1.0, v102
	v_rcp_f32_e32 v102, v97
	v_add_f32_e32 v97, 1.0, v103
	v_rcp_f32_e32 v103, v97
	v_pk_mul_f32 v[92:93], v[98:99], v[100:101] op_sel_hi:[0,1]
	v_pk_mul_f32 v[88:89], v[92:93], v[88:89]
; __device__ __forceinline__ unsigned cvt_pk_bf16(float lo, float hi) { unsigned r; asm volatile("v_cvt_pk_bf16_f32 %0, %1, %2" : "=v"(r) : "v"(lo), "v"(hi)); return r; }
; __device__ __forceinline__ float frcp(float x) { return __builtin_amdgcn_rcpf(x); }
;     __device__ __forceinline__ void operator()(const f32x4 (&acc)[2][2][4][2], const Unit& u, int wr, int wc, int fr, int fq, const float (&epre)[8]) const {
;     ...
;         for (int ai = 0; ai < 2; ++ai)
; #pragma unroll
;             for (int m = 0; m < 4; ++m) { const int row = row0 + ai * 128 + m * 16;
;                 const float rstd = rsqrtf(epre[ai * 4 + m] * (1.0f / DM) + EPS), c1 = -1.44269504f * rstd, c2 = rstd * rstd;
;                 f32x4 av[2];
; #pragma unroll
;                 for (int n = 0; n < 2; ++n) { const f32x4 g = acc[ai][0][m][n], t = g * c1; f32x4 e;
; #pragma unroll
;                     for (int j = 0; j < 4; ++j) e[j] = __builtin_amdgcn_exp2f(t[j]);
;                     const f32x4 d = e + 1.0f; f32x4 r;
; #pragma unroll
;                     for (int j = 0; j < 4; ++j) r[j] = frcp(d[j]);
;                     av[n] = (g * acc[ai][1][m][n]) * (r * c2); }
;                 u32x4 w; w.x = cvt_pk_bf16(av[0][0], av[0][1]); w.y = cvt_pk_bf16(av[0][2], av[0][3]); w.z = cvt_pk_bf16(av[1][0], av[1][1]); w.w = cvt_pk_bf16(av[1][2], av[1][3]);
;                 *(u32x4*)(ACT + (size_t)row * DFF + col0) = w; }
	v_pk_mul_f32 v[92:93], v[96:97], v[86:87] op_sel_hi:[0,1]
	v_pk_mul_f32 v[94:95], v[98:99], v[102:103] op_sel_hi:[0,1]
	v_pk_mul_f32 v[90:91], v[94:95], v[90:91]
	v_pk_mul_f32 v[94:95], v[96:97], v[84:85] op_sel_hi:[0,1]
	v_exp_f32_e32 v94, v94
	v_exp_f32_e32 v95, v95
	v_exp_f32_e32 v96, v92
	v_exp_f32_e32 v97, v93
	v_add_f32_e32 v92, 1.0, v94
	v_add_f32_e32 v93, 1.0, v95
	v_add_f32_e32 v94, 1.0, v96
	v_add_f32_e32 v95, 1.0, v97
	v_rcp_f32_e32 v92, v92
	v_rcp_f32_e32 v93, v93
	v_rcp_f32_e32 v94, v94
	v_rcp_f32_e32 v95, v95
	v_pk_mul_f32 v[80:81], v[84:85], v[80:81]
	v_pk_mul_f32 v[84:85], v[98:99], v[92:93] op_sel_hi:[0,1]
	v_pk_mul_f32 v[74:75], v[78:79], v[74:75]
	v_pk_mul_f32 v[86:87], v[98:99], v[94:95] op_sel_hi:[0,1]
	v_pk_mul_f32 v[86:87], v[86:87], v[82:83]
	v_pk_mul_f32 v[82:83], v[84:85], v[80:81]
	v_fmamk_f32 v85, v153, 0x3a800000, v149
	v_cvt_pk_bf16_f32 v80, v88, v89
	v_cvt_pk_bf16_f32 v81, v90, v91
	v_cvt_pk_bf16_f32 v82, v82, v83
	v_cvt_pk_bf16_f32 v83, v86, v87
	v_mul_f32_e32 v86, 0x4b800000, v85
	v_cmp_gt_f32_e32 vcc, s40, v85
	v_or_b32_e32 v84, 32, v156
	v_pk_mul_f32 v[72:73], v[76:77], v[72:73]
	v_cndmask_b32_e32 v85, v85, v86, vcc
	v_rsq_f32_e32 v86, v85
	v_mad_i64_i32 v[84:85], s[20:21], v84, s41, v[112:113]
	v_lshl_add_u64 v[84:85], v[84:85], 0, v[114:115]
	global_store_dwordx4 v[84:85], v[80:83], off
	v_pk_mul_f32 v[66:67], v[70:71], v[66:67]
	v_pk_mul_f32 v[64:65], v[68:69], v[64:65]
	v_mul_f32_e32 v80, 0x45800000, v86
	v_cndmask_b32_e32 v81, v86, v80, vcc
	v_mul_f32_e32 v80, 0xbfb8aa3b, v81
	v_pk_mul_f32 v[86:87], v[80:81], v[76:77] op_sel_hi:[0,1]
	v_mul_f32_e32 v82, v81, v81
	v_pk_mul_f32 v[84:85], v[80:81], v[78:79] op_sel_hi:[0,1]
	v_exp_f32_e32 v81, v86
	v_exp_f32_e32 v83, v87
	v_exp_f32_e32 v86, v84
	v_exp_f32_e32 v87, v85
	v_add_f32_e32 v81, 1.0, v81
	v_rcp_f32_e32 v84, v81
	v_add_f32_e32 v81, 1.0, v83
	v_rcp_f32_e32 v85, v81
	v_add_f32_e32 v81, 1.0, v86
	v_rcp_f32_e32 v86, v81
	v_add_f32_e32 v81, 1.0, v87
	v_rcp_f32_e32 v87, v81
	v_pk_mul_f32 v[76:77], v[82:83], v[84:85] op_sel_hi:[0,1]
	v_pk_mul_f32 v[72:73], v[76:77], v[72:73]
	v_pk_mul_f32 v[76:77], v[80:81], v[70:71] op_sel_hi:[0,1]
	v_pk_mul_f32 v[78:79], v[82:83], v[86:87] op_sel_hi:[0,1]
	v_pk_mul_f32 v[74:75], v[78:79], v[74:75]
	v_pk_mul_f32 v[78:79], v[80:81], v[68:69] op_sel_hi:[0,1]
	v_exp_f32_e32 v78, v78
	v_exp_f32_e32 v79, v79
	v_exp_f32_e32 v80, v76
	v_exp_f32_e32 v81, v77
	v_add_f32_e32 v76, 1.0, v78
	v_add_f32_e32 v77, 1.0, v79
	v_add_f32_e32 v78, 1.0, v80
	v_add_f32_e32 v79, 1.0, v81
	v_rcp_f32_e32 v76, v76
	v_rcp_f32_e32 v77, v77
	v_rcp_f32_e32 v78, v78
	v_rcp_f32_e32 v79, v79
	v_pk_mul_f32 v[58:59], v[62:63], v[58:59]
	v_pk_mul_f32 v[68:69], v[82:83], v[76:77] op_sel_hi:[0,1]
	v_pk_mul_f32 v[56:57], v[60:61], v[56:57]
	v_pk_mul_f32 v[70:71], v[82:83], v[78:79] op_sel_hi:[0,1]
	v_pk_mul_f32 v[70:71], v[70:71], v[66:67]
	v_pk_mul_f32 v[66:67], v[68:69], v[64:65]
	v_cvt_pk_bf16_f32 v64, v72, v73
	v_cvt_pk_bf16_f32 v65, v74, v75
	v_or_b32_e32 v68, 48, v156
	v_cvt_pk_bf16_f32 v66, v66, v67
	v_cvt_pk_bf16_f32 v67, v70, v71
	v_fmamk_f32 v70, v152, 0x3a800000, v149
	v_mul_f32_e32 v71, 0x4b800000, v70
	v_cmp_gt_f32_e32 vcc, s40, v70
	v_mad_i64_i32 v[68:69], s[20:21], v68, s41, v[112:113]
	s_nop 0
	v_cndmask_b32_e32 v70, v70, v71, vcc
	v_rsq_f32_e32 v70, v70
	v_lshl_add_u64 v[68:69], v[68:69], 0, v[114:115]
	global_store_dwordx4 v[68:69], v[64:67], off
	v_pk_mul_f32 v[50:51], v[54:55], v[50:51]
	v_pk_mul_f32 v[48:49], v[52:53], v[48:49]
	v_mul_f32_e32 v64, 0x45800000, v70
	v_cndmask_b32_e32 v66, v70, v64, vcc
	v_add_u32_e32 v65, 0x80, v156
	v_mul_f32_e32 v64, 0xbfb8aa3b, v66
	v_pk_mul_f32 v[70:71], v[64:65], v[60:61] op_sel_hi:[0,1]
	v_exp_f32_e32 v67, v70
	v_pk_mul_f32 v[68:69], v[64:65], v[62:63] op_sel_hi:[0,1]
	v_exp_f32_e32 v70, v71
	v_exp_f32_e32 v71, v68
	v_exp_f32_e32 v72, v69
	v_add_f32_e32 v67, 1.0, v67
	v_rcp_f32_e32 v68, v67
	v_add_f32_e32 v67, 1.0, v70
	v_rcp_f32_e32 v69, v67
	v_add_f32_e32 v67, 1.0, v71
	v_rcp_f32_e32 v70, v67
	v_add_f32_e32 v67, 1.0, v72
	v_rcp_f32_e32 v71, v67
	v_mul_f32_e32 v66, v66, v66
	v_pk_mul_f32 v[60:61], v[66:67], v[68:69] op_sel_hi:[0,1]
	v_pk_mul_f32 v[56:57], v[60:61], v[56:57]
	v_pk_mul_f32 v[62:63], v[66:67], v[70:71] op_sel_hi:[0,1]
	v_pk_mul_f32 v[58:59], v[62:63], v[58:59]
	v_pk_mul_f32 v[60:61], v[64:65], v[54:55] op_sel_hi:[0,1]
	v_pk_mul_f32 v[62:63], v[64:65], v[52:53] op_sel_hi:[0,1]
	v_exp_f32_e32 v62, v62
	v_exp_f32_e32 v63, v63
	v_exp_f32_e32 v64, v60
	v_exp_f32_e32 v67, v61
	v_add_f32_e32 v60, 1.0, v62
	v_add_f32_e32 v61, 1.0, v63
	v_add_f32_e32 v62, 1.0, v64
	v_add_f32_e32 v63, 1.0, v67
	v_rcp_f32_e32 v60, v60
	v_rcp_f32_e32 v61, v61
	v_rcp_f32_e32 v62, v62
	v_rcp_f32_e32 v63, v63
	v_pk_mul_f32 v[42:43], v[46:47], v[42:43]
	v_pk_mul_f32 v[52:53], v[66:67], v[60:61] op_sel_hi:[0,1]
	v_pk_mul_f32 v[40:41], v[44:45], v[40:41]
	v_pk_mul_f32 v[54:55], v[66:67], v[62:63] op_sel_hi:[0,1]
	v_pk_mul_f32 v[54:55], v[54:55], v[50:51]
	v_pk_mul_f32 v[50:51], v[52:53], v[48:49]
	v_fmamk_f32 v52, v151, 0x3a800000, v149
	v_mul_f32_e32 v53, 0x4b800000, v52
	v_cmp_gt_f32_e32 vcc, s40, v52
	v_cvt_pk_bf16_f32 v48, v56, v57
	v_cvt_pk_bf16_f32 v49, v58, v59
	v_cvt_pk_bf16_f32 v50, v50, v51
	v_cvt_pk_bf16_f32 v51, v54, v55
	v_pk_mul_f32 v[34:35], v[38:39], v[34:35]
	s_nop 0
	v_cndmask_b32_e32 v52, v52, v53, vcc
	v_rsq_f32_e32 v54, v52
	v_mad_i64_i32 v[52:53], s[20:21], v65, s41, v[112:113]
	v_lshl_add_u64 v[52:53], v[52:53], 0, v[114:115]
	global_store_dwordx4 v[52:53], v[48:51], off
	v_pk_mul_f32 v[32:33], v[36:37], v[32:33]
	v_pk_mul_f32 v[26:27], v[30:31], v[26:27]
	v_mul_f32_e32 v48, 0x45800000, v54
; __device__ __forceinline__ unsigned cvt_pk_bf16(float lo, float hi) { unsigned r; asm volatile("v_cvt_pk_bf16_f32 %0, %1, %2" : "=v"(r) : "v"(lo), "v"(hi)); return r; }
; __device__ __forceinline__ float frcp(float x) { return __builtin_amdgcn_rcpf(x); }
;     __device__ __forceinline__ void preload(const Unit& u, int wr, int fr, float (&pre)[8]) const { const int row0 = u.pm * 256 + wr * 64 + fr;
; #pragma unroll
;         for (int ai = 0; ai < 2; ++ai)
; #pragma unroll
;             for (int m = 0; m < 4; ++m) pre[ai * 4 + m] = sumsq[row0 + ai * 128 + m * 16]; }
;     __device__ __forceinline__ void operator()(const f32x4 (&acc)[2][2][4][2], const Unit& u, int wr, int wc, int fr, int fq, const float (&epre)[8]) const {
;     ...
;             for (int m = 0; m < 4; ++m) { const int row = row0 + ai * 128 + m * 16;
;                 const float rstd = rsqrtf(epre[ai * 4 + m] * (1.0f / DM) + EPS), c1 = -1.44269504f * rstd, c2 = rstd * rstd;
;                 f32x4 av[2];
; #pragma unroll
;                 for (int n = 0; n < 2; ++n) { const f32x4 g = acc[ai][0][m][n], t = g * c1; f32x4 e;
; #pragma unroll
;                     for (int j = 0; j < 4; ++j) e[j] = __builtin_amdgcn_exp2f(t[j]);
;                     const f32x4 d = e + 1.0f; f32x4 r;
; #pragma unroll
;                     for (int j = 0; j < 4; ++j) r[j] = frcp(d[j]);
;                     av[n] = (g * acc[ai][1][m][n]) * (r * c2); }
;                 u32x4 w; w.x = cvt_pk_bf16(av[0][0], av[0][1]); w.y = cvt_pk_bf16(av[0][2], av[0][3]); w.z = cvt_pk_bf16(av[1][0], av[1][1]); w.w = cvt_pk_bf16(av[1][2], av[1][3]);
;                 *(u32x4*)(ACT + (size_t)row * DFF + col0) = w; }
	v_cndmask_b32_e32 v49, v54, v48, vcc
	v_mul_f32_e32 v48, 0xbfb8aa3b, v49
	v_pk_mul_f32 v[54:55], v[48:49], v[44:45] op_sel_hi:[0,1]
	v_mul_f32_e32 v50, v49, v49
	v_pk_mul_f32 v[52:53], v[48:49], v[46:47] op_sel_hi:[0,1]
	v_exp_f32_e32 v49, v54
	v_exp_f32_e32 v51, v55
	v_exp_f32_e32 v54, v52
	v_exp_f32_e32 v55, v53
	v_add_f32_e32 v49, 1.0, v49
	v_rcp_f32_e32 v52, v49
	v_add_f32_e32 v49, 1.0, v51
	v_rcp_f32_e32 v53, v49
	v_add_f32_e32 v49, 1.0, v54
	v_rcp_f32_e32 v54, v49
	v_add_f32_e32 v49, 1.0, v55
	v_rcp_f32_e32 v55, v49
	v_pk_mul_f32 v[44:45], v[50:51], v[52:53] op_sel_hi:[0,1]
	v_pk_mul_f32 v[40:41], v[44:45], v[40:41]
	v_pk_mul_f32 v[44:45], v[48:49], v[38:39] op_sel_hi:[0,1]
	v_pk_mul_f32 v[46:47], v[50:51], v[54:55] op_sel_hi:[0,1]
	v_pk_mul_f32 v[42:43], v[46:47], v[42:43]
	v_pk_mul_f32 v[46:47], v[48:49], v[36:37] op_sel_hi:[0,1]
	v_exp_f32_e32 v46, v46
	v_exp_f32_e32 v47, v47
	v_exp_f32_e32 v48, v44
	v_exp_f32_e32 v49, v45
	v_add_f32_e32 v44, 1.0, v46
	v_add_f32_e32 v45, 1.0, v47
	v_add_f32_e32 v46, 1.0, v48
	v_add_f32_e32 v47, 1.0, v49
	v_rcp_f32_e32 v44, v44
	v_rcp_f32_e32 v45, v45
	v_rcp_f32_e32 v46, v46
	v_rcp_f32_e32 v47, v47
	v_pk_mul_f32 v[24:25], v[28:29], v[24:25]
	v_pk_mul_f32 v[36:37], v[50:51], v[44:45] op_sel_hi:[0,1]
	v_pk_mul_f32 v[18:19], v[22:23], v[18:19]
	v_pk_mul_f32 v[38:39], v[50:51], v[46:47] op_sel_hi:[0,1]
	v_pk_mul_f32 v[38:39], v[38:39], v[34:35]
	v_pk_mul_f32 v[34:35], v[36:37], v[32:33]
	v_fmamk_f32 v37, v150, 0x3a800000, v149
	v_cvt_pk_bf16_f32 v32, v40, v41
	v_cvt_pk_bf16_f32 v33, v42, v43
	v_cvt_pk_bf16_f32 v34, v34, v35
	v_cvt_pk_bf16_f32 v35, v38, v39
	v_mul_f32_e32 v38, 0x4b800000, v37
	v_cmp_gt_f32_e32 vcc, s40, v37
	v_add_u32_e32 v36, 0x90, v156
	v_pk_mul_f32 v[16:17], v[20:21], v[16:17]
	v_cndmask_b32_e32 v37, v37, v38, vcc
	v_rsq_f32_e32 v38, v37
	v_mad_i64_i32 v[36:37], s[20:21], v36, s41, v[112:113]
	v_lshl_add_u64 v[36:37], v[36:37], 0, v[114:115]
	global_store_dwordx4 v[36:37], v[32:35], off
	v_pk_mul_f32 v[10:11], v[14:15], v[10:11]
	v_pk_mul_f32 v[8:9], v[12:13], v[8:9]
	v_mul_f32_e32 v32, 0x45800000, v38
	v_cndmask_b32_e32 v33, v38, v32, vcc
	v_mul_f32_e32 v32, 0xbfb8aa3b, v33
	v_pk_mul_f32 v[38:39], v[32:33], v[28:29] op_sel_hi:[0,1]
	v_mul_f32_e32 v34, v33, v33
	v_pk_mul_f32 v[36:37], v[32:33], v[30:31] op_sel_hi:[0,1]
	v_exp_f32_e32 v33, v38
	v_exp_f32_e32 v35, v39
	v_exp_f32_e32 v38, v36
	v_exp_f32_e32 v39, v37
	v_add_f32_e32 v33, 1.0, v33
	v_rcp_f32_e32 v36, v33
	v_add_f32_e32 v33, 1.0, v35
	v_rcp_f32_e32 v37, v33
	v_add_f32_e32 v33, 1.0, v38
	v_rcp_f32_e32 v38, v33
	v_add_f32_e32 v33, 1.0, v39
	v_rcp_f32_e32 v39, v33
	v_pk_mul_f32 v[28:29], v[34:35], v[36:37] op_sel_hi:[0,1]
	v_pk_mul_f32 v[24:25], v[28:29], v[24:25]
	v_pk_mul_f32 v[28:29], v[32:33], v[22:23] op_sel_hi:[0,1]
	v_pk_mul_f32 v[30:31], v[34:35], v[38:39] op_sel_hi:[0,1]
	v_pk_mul_f32 v[26:27], v[30:31], v[26:27]
	v_pk_mul_f32 v[30:31], v[32:33], v[20:21] op_sel_hi:[0,1]
	v_exp_f32_e32 v30, v30
	v_exp_f32_e32 v31, v31
	v_exp_f32_e32 v32, v28
	v_exp_f32_e32 v33, v29
	v_add_f32_e32 v28, 1.0, v30
	v_add_f32_e32 v29, 1.0, v31
	v_add_f32_e32 v30, 1.0, v32
	v_add_f32_e32 v31, 1.0, v33
	v_rcp_f32_e32 v28, v28
	v_rcp_f32_e32 v29, v29
	v_rcp_f32_e32 v30, v30
	v_rcp_f32_e32 v31, v31
	v_pk_mul_f32 v[2:3], v[6:7], v[2:3]
	v_pk_mul_f32 v[20:21], v[34:35], v[28:29] op_sel_hi:[0,1]
	v_pk_mul_f32 v[0:1], v[4:5], v[0:1]
	v_pk_mul_f32 v[22:23], v[34:35], v[30:31] op_sel_hi:[0,1]
	v_pk_mul_f32 v[22:23], v[22:23], v[18:19]
	v_pk_mul_f32 v[18:19], v[20:21], v[16:17]
	v_fmamk_f32 v21, v142, 0x3a800000, v149
	v_cvt_pk_bf16_f32 v16, v24, v25
	v_cvt_pk_bf16_f32 v17, v26, v27
	v_cvt_pk_bf16_f32 v18, v18, v19
	v_cvt_pk_bf16_f32 v19, v22, v23
	v_mul_f32_e32 v22, 0x4b800000, v21
	v_cmp_gt_f32_e32 vcc, s40, v21
	v_add_u32_e32 v20, 0xa0, v156
	s_nop 0
	v_cndmask_b32_e32 v21, v21, v22, vcc
	v_rsq_f32_e32 v22, v21
	v_mad_i64_i32 v[20:21], s[20:21], v20, s41, v[112:113]
	v_lshl_add_u64 v[20:21], v[20:21], 0, v[114:115]
	global_store_dwordx4 v[20:21], v[16:19], off
	s_nop 1
	v_mul_f32_e32 v16, 0x45800000, v22
	v_cndmask_b32_e32 v17, v22, v16, vcc
	v_mul_f32_e32 v16, 0xbfb8aa3b, v17
	v_pk_mul_f32 v[22:23], v[16:17], v[12:13] op_sel_hi:[0,1]
	v_mul_f32_e32 v18, v17, v17
	v_pk_mul_f32 v[20:21], v[16:17], v[14:15] op_sel_hi:[0,1]
	v_exp_f32_e32 v17, v22
	v_exp_f32_e32 v19, v23
	v_exp_f32_e32 v22, v20
	v_exp_f32_e32 v23, v21
	v_add_f32_e32 v17, 1.0, v17
	v_rcp_f32_e32 v20, v17
	v_add_f32_e32 v17, 1.0, v19
	v_rcp_f32_e32 v21, v17
	v_add_f32_e32 v17, 1.0, v22
	v_rcp_f32_e32 v22, v17
	v_add_f32_e32 v17, 1.0, v23
	v_rcp_f32_e32 v23, v17
	v_pk_mul_f32 v[12:13], v[18:19], v[20:21] op_sel_hi:[0,1]
	v_pk_mul_f32 v[8:9], v[12:13], v[8:9]
	v_pk_mul_f32 v[12:13], v[16:17], v[6:7] op_sel_hi:[0,1]
	v_pk_mul_f32 v[14:15], v[18:19], v[22:23] op_sel_hi:[0,1]
	v_pk_mul_f32 v[10:11], v[14:15], v[10:11]
	v_pk_mul_f32 v[14:15], v[16:17], v[4:5] op_sel_hi:[0,1]
	v_exp_f32_e32 v14, v14
	v_exp_f32_e32 v15, v15
	v_exp_f32_e32 v16, v12
	v_exp_f32_e32 v17, v13
	v_add_f32_e32 v12, 1.0, v14
	v_add_f32_e32 v13, 1.0, v15
	v_add_f32_e32 v14, 1.0, v16
	v_add_f32_e32 v15, 1.0, v17
	v_rcp_f32_e32 v12, v12
	v_rcp_f32_e32 v13, v13
	v_rcp_f32_e32 v14, v14
	v_rcp_f32_e32 v15, v15
	s_and_b64 vcc, s[16:17], exec
	v_pk_mul_f32 v[4:5], v[18:19], v[12:13] op_sel_hi:[0,1]
	v_pk_mul_f32 v[6:7], v[18:19], v[14:15] op_sel_hi:[0,1]
	v_pk_mul_f32 v[6:7], v[6:7], v[2:3]
	v_pk_mul_f32 v[2:3], v[4:5], v[0:1]
	v_add_u32_e32 v4, 0xb0, v156
	v_mad_i64_i32 v[4:5], s[20:21], v4, s41, v[112:113]
	v_lshl_add_u64 v[4:5], v[4:5], 0, v[114:115]
	s_mov_b64 s[20:21], -1
	v_cvt_pk_bf16_f32 v0, v8, v9
	v_cvt_pk_bf16_f32 v1, v10, v11
	v_cvt_pk_bf16_f32 v2, v2, v3
	v_cvt_pk_bf16_f32 v3, v6, v7
	global_store_dwordx4 v[4:5], v[0:3], off
	s_cbranch_vccz .LBB0_695
	s_nop 0
	v_lshl_add_u32 v0, s12, 8, v143
	v_ashrrev_i32_e32 v1, 31, v0
	v_lshl_add_u64 v[0:1], v[0:1], 2, s[10:11]
	global_load_dword v156, v[0:1], off
	global_load_dword v155, v[0:1], off offset:64
	global_load_dword v154, v[0:1], off offset:128
	global_load_dword v153, v[0:1], off offset:192
	global_load_dword v152, v[0:1], off offset:512
	global_load_dword v151, v[0:1], off offset:576
	global_load_dword v150, v[0:1], off offset:640
	global_load_dword v142, v[0:1], off offset:704
	s_mov_b64 s[20:21], 0
	s_branch .LBB0_695

; #define PG8_STAGE(bufoff, gbase, voff) do { _Pragma("unroll") for (int _i = 0; _i < 2; ++_i) \
;         __builtin_amdgcn_global_load_lds((const unsigned*)((const char*)(gbase) + (voff)[_i]), (PG8_LAS unsigned*)(lds + (bufoff) + ldsw + _i * 8192), 16, 0, 0); } while (0)
; #define PG8_LDA(dst, b, h) do { _Pragma("unroll") for (int m = 0; m < 4; ++m) _Pragma("unroll") for (int k = 0; k < 2; ++k) dst[m][k] = *(const PG8_LAS bf16x8*)(lds + PG8_SA(b, h) + aoff + m * 2048 + k * 1024); } while (0)
; #define PG8_LDB(dst, b, h) do { _Pragma("unroll") for (int n = 0; n < 2; ++n) _Pragma("unroll") for (int k = 0; k < 2; ++k) dst[n][k] = *(const PG8_LAS bf16x8*)(lds + PG8_SB(b, h) + boff + n * 2048 + k * 1024); } while (0)
; #define PG8_MMA(ai, bj, At, Bt) do { __builtin_amdgcn_s_setprio(1); _Pragma("unroll") for (int m = 0; m < 4; ++m) _Pragma("unroll") for (int n = 0; n < 2; ++n) _Pragma("unroll") for (int k = 0; k < 2; ++k) \
;         acc[ai][bj][m][n] = __builtin_amdgcn_mfma_f32_16x16x32_bf16(Bt[n][k], At[m][k], acc[ai][bj][m][n], 0, 0, 0); __builtin_amdgcn_s_setprio(0); } while (0)
; #define PG8_WAIT_V(n) asm volatile("s_waitcnt vmcnt(" #n ")" ::: "memory")
; #define PG8_WAIT_L(n) asm volatile("s_waitcnt lgkmcnt(" #n ")" ::: "memory")
; #define PG8_BAR __builtin_amdgcn_s_barrier()
; #define PG8_SCHED __builtin_amdgcn_sched_barrier(0)
; template <class Epi, class Sched>
; __device__ __forceinline__ void gemm_phase(PG8_LAS unsigned char* lds, const Gemm g, const Sched& S, const Epi& E) {
;     ...
;             PG8_LDB(B0, 0, 0); PG8_SCHED; PG8_LDA(At, 0, 0); PG8_STAGE(PG8_SA(1, 1), a1 + hstep, voffA);
;             PG8_WAIT_L(8); PG8_BAR; PG8_WAIT_L(0); PG8_MMA(0, 0, At, B0); PG8_BAR; PG8_SCHED;
;             PG8_LDB(B1, 0, 1); PG8_STAGE(PG8_SB(0, 0), b2, voffB);
;             PG8_BAR; PG8_WAIT_L(0); PG8_MMA(0, 1, At, B1); PG8_BAR;
;             PG8_LDA(At, 0, 1); PG8_STAGE(PG8_SA(0, 0), a2, voffA);
;             PG8_BAR; PG8_WAIT_L(0); PG8_MMA(1, 0, At, B0); PG8_BAR; PG8_SCHED;
;             PG8_STAGE(PG8_SB(0, 1), b2 + hstep, voffB);
;             PG8_WAIT_V(6); PG8_BAR; PG8_MMA(1, 1, At, B1); PG8_BAR;
.LBB0_779:
	s_add_u32 s48, s28, 0x100
	s_addc_u32 s49, s29, 0
	s_mov_b32 s50, -2
	s_waitcnt lgkmcnt(0)
	ds_read_b128 v[144:147], v188
	ds_read_b128 v[148:151], v188 offset:1024
	ds_read_b128 v[152:155], v188 offset:2048
	ds_read_b128 v[156:159], v188 offset:3072
	s_add_u32 s28, s26, 0x100
	s_addc_u32 s29, s27, 0
	s_cmp_eq_u32 s50, 40
	s_cselect_b32 s35, s11, s29
	s_cselect_b32 s34, s10, s28
	s_cselect_b32 s31, s13, s49
	s_cselect_b32 s30, s12, s48
	v_lshl_add_u64 v[184:185], s[26:27], 0, v[136:137]
	s_add_i32 m0, s33, 0xc000
	ds_read_b128 v[160:163], v189
	ds_read_b128 v[164:167], v189 offset:1024
	ds_read_b128 v[168:171], v189 offset:2048
	ds_read_b128 v[172:175], v189 offset:3072
	ds_read_b128 v[180:183], v189 offset:4096
	ds_read_b128 v[192:195], v189 offset:5120
	ds_read_b128 v[196:199], v189 offset:6144
	ds_read_b128 v[200:203], v189 offset:7168
	global_load_lds_dwordx4 v[184:185], off
	v_lshl_add_u64 v[184:185], s[26:27], 0, v[138:139]
	s_add_i32 m0, s33, 0xe000
	s_nop 0
	global_load_lds_dwordx4 v[184:185], off
	s_waitcnt lgkmcnt(8)
	s_barrier
	s_waitcnt lgkmcnt(0)
	s_setprio 1
	v_mfma_f32_16x16x32_bf16 v[124:127], v[144:147], v[160:163], 0
	v_mfma_f32_16x16x32_bf16 v[120:123], v[152:155], v[160:163], 0
	v_mfma_f32_16x16x32_bf16 v[108:111], v[144:147], v[168:171], 0
	v_mfma_f32_16x16x32_bf16 v[104:107], v[152:155], v[168:171], 0
	v_mfma_f32_16x16x32_bf16 v[92:95], v[144:147], v[180:183], 0
	v_mfma_f32_16x16x32_bf16 v[88:91], v[152:155], v[180:183], 0
	v_mfma_f32_16x16x32_bf16 v[76:79], v[144:147], v[196:199], 0
	v_mfma_f32_16x16x32_bf16 v[72:75], v[152:155], v[196:199], 0
	v_mfma_f32_16x16x32_bf16 v[124:127], v[148:151], v[164:167], v[124:127]
	v_mfma_f32_16x16x32_bf16 v[120:123], v[156:159], v[164:167], v[120:123]
	v_mfma_f32_16x16x32_bf16 v[108:111], v[148:151], v[172:175], v[108:111]
	v_mfma_f32_16x16x32_bf16 v[104:107], v[156:159], v[172:175], v[104:107]
	v_mfma_f32_16x16x32_bf16 v[92:95], v[148:151], v[192:195], v[92:95]
	v_mfma_f32_16x16x32_bf16 v[88:91], v[156:159], v[192:195], v[88:91]
	v_mfma_f32_16x16x32_bf16 v[76:79], v[148:151], v[200:203], v[76:79]
	v_mfma_f32_16x16x32_bf16 v[72:75], v[156:159], v[200:203], v[72:75]
	s_setprio 0
	s_barrier
	s_add_i32 s26, s42, s5
	v_lshl_add_u64 v[184:185], s[30:31], 0, v[130:131]
	s_mov_b32 m0, s26
	ds_read_b128 v[208:211], v190
	ds_read_b128 v[212:215], v190 offset:1024
	ds_read_b128 v[216:219], v190 offset:2048
	ds_read_b128 v[220:223], v190 offset:3072
	global_load_lds_dwordx4 v[184:185], off
	v_lshl_add_u64 v[204:205], s[30:31], 0, v[134:135]
	s_add_i32 m0, s26, 0x2000
	s_nop 0
	global_load_lds_dwordx4 v[204:205], off
	s_barrier
	s_waitcnt lgkmcnt(0)
	s_setprio 1
	v_mfma_f32_16x16x32_bf16 v[116:119], v[208:211], v[160:163], 0
	v_mfma_f32_16x16x32_bf16 v[112:115], v[216:219], v[160:163], 0
	v_mfma_f32_16x16x32_bf16 v[100:103], v[208:211], v[168:171], 0
	v_mfma_f32_16x16x32_bf16 v[96:99], v[216:219], v[168:171], 0
	v_mfma_f32_16x16x32_bf16 v[84:87], v[208:211], v[180:183], 0
	v_mfma_f32_16x16x32_bf16 v[80:83], v[216:219], v[180:183], 0
	v_mfma_f32_16x16x32_bf16 v[68:71], v[208:211], v[196:199], 0
	v_mfma_f32_16x16x32_bf16 v[64:67], v[216:219], v[196:199], 0
	v_mfma_f32_16x16x32_bf16 v[116:119], v[212:215], v[164:167], v[116:119]
	v_mfma_f32_16x16x32_bf16 v[112:115], v[220:223], v[164:167], v[112:115]
	v_mfma_f32_16x16x32_bf16 v[100:103], v[212:215], v[172:175], v[100:103]
	v_mfma_f32_16x16x32_bf16 v[96:99], v[220:223], v[172:175], v[96:99]
	v_mfma_f32_16x16x32_bf16 v[84:87], v[212:215], v[192:195], v[84:87]
	v_mfma_f32_16x16x32_bf16 v[80:83], v[220:223], v[192:195], v[80:83]
	v_mfma_f32_16x16x32_bf16 v[68:71], v[212:215], v[200:203], v[68:71]
	v_mfma_f32_16x16x32_bf16 v[64:67], v[220:223], v[200:203], v[64:67]
	s_setprio 0
	s_mov_b32 m0, s33
	v_lshl_add_u64 v[224:225], s[34:35], 0, v[128:129]
	s_barrier
	ds_read_b128 v[160:163], v189 offset:16384
	ds_read_b128 v[164:167], v189 offset:17408
	ds_read_b128 v[168:171], v189 offset:18432
	ds_read_b128 v[172:175], v189 offset:19456
	ds_read_b128 v[180:183], v189 offset:20480
	ds_read_b128 v[192:195], v189 offset:21504
	ds_read_b128 v[196:199], v189 offset:22528
	ds_read_b128 v[200:203], v189 offset:23552
	global_load_lds_dwordx4 v[224:225], off
	v_lshl_add_u64 v[226:227], s[34:35], 0, v[132:133]
	s_mov_b32 m0, s36
	s_nop 0
	global_load_lds_dwordx4 v[226:227], off
	s_barrier
	s_waitcnt lgkmcnt(0)
	s_setprio 1
	v_mfma_f32_16x16x32_bf16 v[60:63], v[144:147], v[160:163], 0
	v_mfma_f32_16x16x32_bf16 v[56:59], v[152:155], v[160:163], 0
	v_mfma_f32_16x16x32_bf16 v[44:47], v[144:147], v[168:171], 0
	v_mfma_f32_16x16x32_bf16 v[40:43], v[152:155], v[168:171], 0
	v_mfma_f32_16x16x32_bf16 v[28:31], v[144:147], v[180:183], 0
	v_mfma_f32_16x16x32_bf16 v[24:27], v[152:155], v[180:183], 0
	v_mfma_f32_16x16x32_bf16 v[12:15], v[144:147], v[196:199], 0
	v_mfma_f32_16x16x32_bf16 v[8:11], v[152:155], v[196:199], 0
	v_mfma_f32_16x16x32_bf16 v[60:63], v[148:151], v[164:167], v[60:63]
	v_mfma_f32_16x16x32_bf16 v[56:59], v[156:159], v[164:167], v[56:59]
	v_mfma_f32_16x16x32_bf16 v[44:47], v[148:151], v[172:175], v[44:47]
	v_mfma_f32_16x16x32_bf16 v[40:43], v[156:159], v[172:175], v[40:43]
	v_mfma_f32_16x16x32_bf16 v[28:31], v[148:151], v[192:195], v[28:31]
	v_mfma_f32_16x16x32_bf16 v[24:27], v[156:159], v[192:195], v[24:27]
	v_mfma_f32_16x16x32_bf16 v[12:15], v[148:151], v[200:203], v[12:15]
	v_mfma_f32_16x16x32_bf16 v[8:11], v[156:159], v[200:203], v[8:11]
	s_setprio 0
	s_barrier
	s_add_u32 s26, s30, 0xb0000
	s_addc_u32 s27, s31, 0
	s_add_i32 s51, s43, s5
	v_lshl_add_u64 v[144:145], s[26:27], 0, v[130:131]
	s_mov_b32 m0, s51
	s_nop 0
	global_load_lds_dwordx4 v[144:145], off
	v_lshl_add_u64 v[144:145], s[26:27], 0, v[134:135]
	s_add_i32 m0, s51, 0x2000
	s_nop 0
	global_load_lds_dwordx4 v[144:145], off
	s_waitcnt vmcnt(6)
	s_barrier
; #define PG8_STAGE(bufoff, gbase, voff) do { _Pragma("unroll") for (int _i = 0; _i < 2; ++_i) \
;         __builtin_amdgcn_global_load_lds((const unsigned*)((const char*)(gbase) + (voff)[_i]), (PG8_LAS unsigned*)(lds + (bufoff) + ldsw + _i * 8192), 16, 0, 0); } while (0)
; #define PG8_LDA(dst, b, h) do { _Pragma("unroll") for (int m = 0; m < 4; ++m) _Pragma("unroll") for (int k = 0; k < 2; ++k) dst[m][k] = *(const PG8_LAS bf16x8*)(lds + PG8_SA(b, h) + aoff + m * 2048 + k * 1024); } while (0)
; #define PG8_LDB(dst, b, h) do { _Pragma("unroll") for (int n = 0; n < 2; ++n) _Pragma("unroll") for (int k = 0; k < 2; ++k) dst[n][k] = *(const PG8_LAS bf16x8*)(lds + PG8_SB(b, h) + boff + n * 2048 + k * 1024); } while (0)
; #define PG8_MMA(ai, bj, At, Bt) do { __builtin_amdgcn_s_setprio(1); _Pragma("unroll") for (int m = 0; m < 4; ++m) _Pragma("unroll") for (int n = 0; n < 2; ++n) _Pragma("unroll") for (int k = 0; k < 2; ++k) \
;         acc[ai][bj][m][n] = __builtin_amdgcn_mfma_f32_16x16x32_bf16(Bt[n][k], At[m][k], acc[ai][bj][m][n], 0, 0, 0); __builtin_amdgcn_s_setprio(0); } while (0)
; #define PG8_WAIT_V(n) asm volatile("s_waitcnt vmcnt(" #n ")" ::: "memory")
; #define PG8_WAIT_L(n) asm volatile("s_waitcnt lgkmcnt(" #n ")" ::: "memory")
; #define PG8_BAR __builtin_amdgcn_s_barrier()
; #define PG8_SCHED __builtin_amdgcn_sched_barrier(0)
; template <class Epi, class Sched>
; __device__ __forceinline__ void gemm_phase(PG8_LAS unsigned char* lds, const Gemm g, const Sched& S, const Epi& E) {
;     ...
;             PG8_WAIT_V(6); PG8_BAR; PG8_MMA(1, 1, At, B1); PG8_BAR;
;             PG8_LDB(B0, 1, 0); PG8_SCHED; PG8_LDA(At, 1, 0); PG8_STAGE(PG8_SA(0, 1), a2 + hstep, voffA);
;             PG8_WAIT_L(8); PG8_BAR; PG8_WAIT_L(0); PG8_MMA(0, 0, At, B0); PG8_BAR; PG8_SCHED;
;             PG8_LDB(B1, 1, 1); PG8_STAGE(PG8_SB(1, 0), b3, voffB);
	s_setprio 1
	v_mfma_f32_16x16x32_bf16 v[52:55], v[208:211], v[160:163], 0
	v_mfma_f32_16x16x32_bf16 v[48:51], v[216:219], v[160:163], 0
	v_mfma_f32_16x16x32_bf16 v[36:39], v[208:211], v[168:171], 0
	v_mfma_f32_16x16x32_bf16 v[32:35], v[216:219], v[168:171], 0
	v_mfma_f32_16x16x32_bf16 v[20:23], v[208:211], v[180:183], 0
	v_mfma_f32_16x16x32_bf16 v[16:19], v[216:219], v[180:183], 0
	v_mfma_f32_16x16x32_bf16 v[4:7], v[208:211], v[196:199], 0
	v_mfma_f32_16x16x32_bf16 v[0:3], v[216:219], v[196:199], 0
	v_mfma_f32_16x16x32_bf16 v[52:55], v[212:215], v[164:167], v[52:55]
	v_mfma_f32_16x16x32_bf16 v[48:51], v[220:223], v[164:167], v[48:51]
	v_mfma_f32_16x16x32_bf16 v[36:39], v[212:215], v[172:175], v[36:39]
	v_mfma_f32_16x16x32_bf16 v[32:35], v[220:223], v[172:175], v[32:35]
	v_mfma_f32_16x16x32_bf16 v[20:23], v[212:215], v[192:195], v[20:23]
	v_mfma_f32_16x16x32_bf16 v[16:19], v[220:223], v[192:195], v[16:19]
	v_mfma_f32_16x16x32_bf16 v[4:7], v[212:215], v[200:203], v[4:7]
	v_mfma_f32_16x16x32_bf16 v[0:3], v[220:223], v[200:203], v[0:3]
	s_setprio 0
	s_add_i32 s51, 0, 0x18000
	v_add_u32_e32 v156, s51, v186
	s_barrier
	ds_read_b128 v[144:147], v156
	ds_read_b128 v[148:151], v156 offset:1024
	ds_read_b128 v[152:155], v156 offset:2048
	ds_read_b128 v[156:159], v156 offset:3072
	s_add_u32 s26, s34, 0xb0000
	s_addc_u32 s27, s35, 0
	s_mov_b32 m0, s37
	v_lshl_add_u64 v[208:209], s[26:27], 0, v[128:129]
	ds_read_b128 v[160:163], v189 offset:32768
	ds_read_b128 v[164:167], v189 offset:33792
	ds_read_b128 v[168:171], v189 offset:34816
	ds_read_b128 v[172:175], v189 offset:35840
	ds_read_b128 v[180:183], v189 offset:36864
	ds_read_b128 v[192:195], v189 offset:37888
	ds_read_b128 v[196:199], v189 offset:38912
	ds_read_b128 v[200:203], v189 offset:39936
	global_load_lds_dwordx4 v[208:209], off
	v_lshl_add_u64 v[208:209], s[26:27], 0, v[132:133]
	s_mov_b32 m0, s38
	s_nop 0
	global_load_lds_dwordx4 v[208:209], off
	s_waitcnt lgkmcnt(8)
	s_barrier
	s_waitcnt lgkmcnt(0)
	s_setprio 1
	v_mfma_f32_16x16x32_bf16 v[124:127], v[144:147], v[160:163], v[124:127]
	v_mfma_f32_16x16x32_bf16 v[120:123], v[152:155], v[160:163], v[120:123]
	v_mfma_f32_16x16x32_bf16 v[108:111], v[144:147], v[168:171], v[108:111]
	v_mfma_f32_16x16x32_bf16 v[104:107], v[152:155], v[168:171], v[104:107]
	v_mfma_f32_16x16x32_bf16 v[92:95], v[144:147], v[180:183], v[92:95]
	v_mfma_f32_16x16x32_bf16 v[88:91], v[152:155], v[180:183], v[88:91]
	v_mfma_f32_16x16x32_bf16 v[76:79], v[144:147], v[196:199], v[76:79]
	v_mfma_f32_16x16x32_bf16 v[72:75], v[152:155], v[196:199], v[72:75]
	v_mfma_f32_16x16x32_bf16 v[124:127], v[148:151], v[164:167], v[124:127]
	v_mfma_f32_16x16x32_bf16 v[120:123], v[156:159], v[164:167], v[120:123]
	v_mfma_f32_16x16x32_bf16 v[108:111], v[148:151], v[172:175], v[108:111]
	v_mfma_f32_16x16x32_bf16 v[104:107], v[156:159], v[172:175], v[104:107]
	v_mfma_f32_16x16x32_bf16 v[92:95], v[148:151], v[192:195], v[92:95]
	v_mfma_f32_16x16x32_bf16 v[88:91], v[156:159], v[192:195], v[88:91]
	v_mfma_f32_16x16x32_bf16 v[76:79], v[148:151], v[200:203], v[76:79]
	v_mfma_f32_16x16x32_bf16 v[72:75], v[156:159], v[200:203], v[72:75]
	s_setprio 0
	s_barrier
	s_add_i32 s34, 0, 0x1c000
	s_add_i32 s26, s51, s5
	v_add_u32_e32 v207, s34, v186
	v_lshl_add_u64 v[184:185], v[184:185], 0, s[16:17]
	s_mov_b32 m0, s26
	ds_read_b128 v[208:211], v207
	ds_read_b128 v[212:215], v207 offset:1024
	ds_read_b128 v[216:219], v207 offset:2048
	ds_read_b128 v[220:223], v207 offset:3072
	global_load_lds_dwordx4 v[184:185], off
	v_lshl_add_u64 v[184:185], v[204:205], 0, s[16:17]
	s_add_i32 m0, s26, 0x2000
	s_nop 0
	global_load_lds_dwordx4 v[184:185], off
	s_barrier
; #define PG8_STAGE(bufoff, gbase, voff) do { _Pragma("unroll") for (int _i = 0; _i < 2; ++_i) \
;         __builtin_amdgcn_global_load_lds((const unsigned*)((const char*)(gbase) + (voff)[_i]), (PG8_LAS unsigned*)(lds + (bufoff) + ldsw + _i * 8192), 16, 0, 0); } while (0)
; #define PG8_LDA(dst, b, h) do { _Pragma("unroll") for (int m = 0; m < 4; ++m) _Pragma("unroll") for (int k = 0; k < 2; ++k) dst[m][k] = *(const PG8_LAS bf16x8*)(lds + PG8_SA(b, h) + aoff + m * 2048 + k * 1024); } while (0)
; #define PG8_LDB(dst, b, h) do { _Pragma("unroll") for (int n = 0; n < 2; ++n) _Pragma("unroll") for (int k = 0; k < 2; ++k) dst[n][k] = *(const PG8_LAS bf16x8*)(lds + PG8_SB(b, h) + boff + n * 2048 + k * 1024); } while (0)
; #define PG8_MMA(ai, bj, At, Bt) do { __builtin_amdgcn_s_setprio(1); _Pragma("unroll") for (int m = 0; m < 4; ++m) _Pragma("unroll") for (int n = 0; n < 2; ++n) _Pragma("unroll") for (int k = 0; k < 2; ++k) \
;         acc[ai][bj][m][n] = __builtin_amdgcn_mfma_f32_16x16x32_bf16(Bt[n][k], At[m][k], acc[ai][bj][m][n], 0, 0, 0); __builtin_amdgcn_s_setprio(0); } while (0)
; #define PG8_WAIT_V(n) asm volatile("s_waitcnt vmcnt(" #n ")" ::: "memory")
; #define PG8_WAIT_L(n) asm volatile("s_waitcnt lgkmcnt(" #n ")" ::: "memory")
; #define PG8_BAR __builtin_amdgcn_s_barrier()
; #define PG8_SCHED __builtin_amdgcn_sched_barrier(0)
; template <class Epi, class Sched>
; __device__ __forceinline__ void gemm_phase(PG8_LAS unsigned char* lds, const Gemm g, const Sched& S, const Epi& E) {
;     ...
;             PG8_LDB(B1, 1, 1); PG8_STAGE(PG8_SB(1, 0), b3, voffB);
;             PG8_BAR; PG8_WAIT_L(0); PG8_MMA(0, 1, At, B1); PG8_BAR;
;             PG8_LDA(At, 1, 1); PG8_STAGE(PG8_SA(1, 0), a3, voffA);
;             PG8_BAR; PG8_WAIT_L(0); PG8_MMA(1, 0, At, B0); PG8_BAR; PG8_SCHED;
;             PG8_STAGE(PG8_SB(1, 1), b3 + hstep, voffB);
;             PG8_WAIT_V(6); PG8_BAR; PG8_MMA(1, 1, At, B1); PG8_BAR;
	s_waitcnt lgkmcnt(0)
	s_setprio 1
	v_mfma_f32_16x16x32_bf16 v[116:119], v[208:211], v[160:163], v[116:119]
	v_mfma_f32_16x16x32_bf16 v[112:115], v[216:219], v[160:163], v[112:115]
	v_mfma_f32_16x16x32_bf16 v[100:103], v[208:211], v[168:171], v[100:103]
	v_mfma_f32_16x16x32_bf16 v[96:99], v[216:219], v[168:171], v[96:99]
	v_mfma_f32_16x16x32_bf16 v[84:87], v[208:211], v[180:183], v[84:87]
	v_mfma_f32_16x16x32_bf16 v[80:83], v[216:219], v[180:183], v[80:83]
	v_mfma_f32_16x16x32_bf16 v[68:71], v[208:211], v[196:199], v[68:71]
	v_mfma_f32_16x16x32_bf16 v[64:67], v[216:219], v[196:199], v[64:67]
	v_mfma_f32_16x16x32_bf16 v[116:119], v[212:215], v[164:167], v[116:119]
	v_mfma_f32_16x16x32_bf16 v[112:115], v[220:223], v[164:167], v[112:115]
	v_mfma_f32_16x16x32_bf16 v[100:103], v[212:215], v[172:175], v[100:103]
	v_mfma_f32_16x16x32_bf16 v[96:99], v[220:223], v[172:175], v[96:99]
	v_mfma_f32_16x16x32_bf16 v[84:87], v[212:215], v[192:195], v[84:87]
	v_mfma_f32_16x16x32_bf16 v[80:83], v[220:223], v[192:195], v[80:83]
	v_mfma_f32_16x16x32_bf16 v[68:71], v[212:215], v[200:203], v[68:71]
	v_mfma_f32_16x16x32_bf16 v[64:67], v[220:223], v[200:203], v[64:67]
	s_setprio 0
	s_mov_b32 m0, s40
	v_lshl_add_u64 v[184:185], v[224:225], 0, s[16:17]
	s_barrier
	ds_read_b128 v[160:163], v189 offset:49152
	ds_read_b128 v[164:167], v189 offset:50176
	ds_read_b128 v[168:171], v189 offset:51200
	ds_read_b128 v[172:175], v189 offset:52224
	ds_read_b128 v[180:183], v189 offset:53248
	ds_read_b128 v[192:195], v189 offset:54272
	ds_read_b128 v[196:199], v189 offset:55296
	ds_read_b128 v[200:203], v189 offset:56320
	global_load_lds_dwordx4 v[184:185], off
	v_lshl_add_u64 v[184:185], v[226:227], 0, s[16:17]
	s_mov_b32 m0, s41
	s_nop 0
	global_load_lds_dwordx4 v[184:185], off
	s_barrier
	s_waitcnt lgkmcnt(0)
	s_setprio 1
	v_mfma_f32_16x16x32_bf16 v[60:63], v[144:147], v[160:163], v[60:63]
	v_mfma_f32_16x16x32_bf16 v[56:59], v[152:155], v[160:163], v[56:59]
	v_mfma_f32_16x16x32_bf16 v[44:47], v[144:147], v[168:171], v[44:47]
	v_mfma_f32_16x16x32_bf16 v[40:43], v[152:155], v[168:171], v[40:43]
	v_mfma_f32_16x16x32_bf16 v[28:31], v[144:147], v[180:183], v[28:31]
	v_mfma_f32_16x16x32_bf16 v[24:27], v[152:155], v[180:183], v[24:27]
	v_mfma_f32_16x16x32_bf16 v[12:15], v[144:147], v[196:199], v[12:15]
	v_mfma_f32_16x16x32_bf16 v[8:11], v[152:155], v[196:199], v[8:11]
	v_mfma_f32_16x16x32_bf16 v[60:63], v[148:151], v[164:167], v[60:63]
	v_mfma_f32_16x16x32_bf16 v[56:59], v[156:159], v[164:167], v[56:59]
	v_mfma_f32_16x16x32_bf16 v[44:47], v[148:151], v[172:175], v[44:47]
	v_mfma_f32_16x16x32_bf16 v[40:43], v[156:159], v[172:175], v[40:43]
	v_mfma_f32_16x16x32_bf16 v[28:31], v[148:151], v[192:195], v[28:31]
	v_mfma_f32_16x16x32_bf16 v[24:27], v[156:159], v[192:195], v[24:27]
	v_mfma_f32_16x16x32_bf16 v[12:15], v[148:151], v[200:203], v[12:15]
	v_mfma_f32_16x16x32_bf16 v[8:11], v[156:159], v[200:203], v[8:11]
	s_setprio 0
	s_barrier
	s_add_u32 s26, s30, 0xb0080
	s_addc_u32 s27, s31, 0
	s_add_i32 s30, s34, s5
	v_lshl_add_u64 v[144:145], s[26:27], 0, v[130:131]
	s_mov_b32 m0, s30
	s_nop 0
	global_load_lds_dwordx4 v[144:145], off
	v_lshl_add_u64 v[144:145], s[26:27], 0, v[134:135]
	s_add_i32 m0, s30, 0x2000
	s_nop 0
	global_load_lds_dwordx4 v[144:145], off
	s_waitcnt vmcnt(6)
	s_barrier
	s_setprio 1
	v_mfma_f32_16x16x32_bf16 v[52:55], v[208:211], v[160:163], v[52:55]
	v_mfma_f32_16x16x32_bf16 v[48:51], v[216:219], v[160:163], v[48:51]
	v_mfma_f32_16x16x32_bf16 v[36:39], v[208:211], v[168:171], v[36:39]
	v_mfma_f32_16x16x32_bf16 v[32:35], v[216:219], v[168:171], v[32:35]
	v_mfma_f32_16x16x32_bf16 v[20:23], v[208:211], v[180:183], v[20:23]
	v_mfma_f32_16x16x32_bf16 v[16:19], v[216:219], v[180:183], v[16:19]
	v_mfma_f32_16x16x32_bf16 v[4:7], v[208:211], v[196:199], v[4:7]
	v_mfma_f32_16x16x32_bf16 v[0:3], v[216:219], v[196:199], v[0:3]
	v_mfma_f32_16x16x32_bf16 v[52:55], v[212:215], v[164:167], v[52:55]
	v_mfma_f32_16x16x32_bf16 v[48:51], v[220:223], v[164:167], v[48:51]
	v_mfma_f32_16x16x32_bf16 v[36:39], v[212:215], v[172:175], v[36:39]
	v_mfma_f32_16x16x32_bf16 v[32:35], v[220:223], v[172:175], v[32:35]
	v_mfma_f32_16x16x32_bf16 v[20:23], v[212:215], v[192:195], v[20:23]
	v_mfma_f32_16x16x32_bf16 v[16:19], v[220:223], v[192:195], v[16:19]
	v_mfma_f32_16x16x32_bf16 v[4:7], v[212:215], v[200:203], v[4:7]
	v_mfma_f32_16x16x32_bf16 v[0:3], v[220:223], v[200:203], v[0:3]
	s_setprio 0
	s_add_i32 s50, s50, 2
	s_add_u32 s48, s48, 0x100
	s_addc_u32 s49, s49, 0
	s_cmp_gt_u32 s50, 41
	s_mov_b64 s[26:27], s[28:29]
	s_barrier
	s_cbranch_scc1 .Lpeel_x3_LBB0780

; __device__ __forceinline__ unsigned cvt_pk_bf16(float lo, float hi) { unsigned r; asm volatile("v_cvt_pk_bf16_f32 %0, %1, %2" : "=v"(r) : "v"(lo), "v"(hi)); return r; }
;     __device__ __forceinline__ void operator()(const f32x4 (&acc)[2][2][4][2], const Unit& u, int wr, int wc, int fr, int fq, const float (&epre)[1]) const {
;         const int row0 = u.pm * 256 + wr * 64 + fr, col0 = u.pn * 256 + wc * 32 + 8 * fq;
; #pragma unroll
;         for (int ai = 0; ai < 2; ++ai) {
;             float ssv[4];
;             f32x4 bv[4][2][2];
; #pragma unroll
;             for (int m = 0; m < 4; ++m) { const int row = row0 + ai * 128 + m * 16;
; #pragma unroll
;                 for (int bj = 0; bj < 2; ++bj) {
;                     if (BASEBF) { unpack8(*(const u32x4*)(HB + (size_t)row * DM + col0 + bj * 128), bv[m][bj][0], bv[m][bj][1]); }
;                     else { const float* bp = (row < MP ? base0 + (size_t)row * DM : base1 + (size_t)(row - MP) * DM) + col0 + bj * 128; bv[m][bj][0] = __builtin_nontemporal_load((const f32x4*)bp); bv[m][bj][1] = __builtin_nontemporal_load((const f32x4*)(bp + 4)); } } }
; #pragma unroll
;             for (int m = 0; m < 4; ++m) { const int row = row0 + ai * 128 + m * 16;
;                 float ss = 0.f;
; #pragma unroll
;                 for (int bj = 0; bj < 2; ++bj) { const f32x4 h0 = bv[m][bj][0] + acc[ai][bj][m][0], h1 = bv[m][bj][1] + acc[ai][bj][m][1];
;                     u32x4 w; w.x = cvt_pk_bf16(h0[0], h0[1]); w.y = cvt_pk_bf16(h0[2], h0[3]); w.z = cvt_pk_bf16(h1[0], h1[1]); w.w = cvt_pk_bf16(h1[2], h1[3]);
;                     *(u32x4*)(HBo + (size_t)row * DM + col0 + bj * 128) = w;
;                     ss += (h0[0] * h0[0] + h0[1] * h0[1]) + (h0[2] * h0[2] + h0[3] * h0[3]) + (h1[0] * h1[0] + h1[1] * h1[1]) + (h1[2] * h1[2] + h1[3] * h1[3]); }
;                 ssv[m] = ss;
;             }
.Lpeel_x3_LBB0780:
	v_lshl_or_b32 v144, s47, 8, v187
	v_lshl_add_u32 v150, s46, 8, v177
	v_ashrrev_i32_e32 v145, 31, v144
	v_ashrrev_i32_e32 v151, 31, v150
	v_lshlrev_b64 v[144:145], 1, v[144:145]
	v_lshl_add_u64 v[146:147], s[84:85], 0, v[144:145]
	v_lshlrev_b64 v[148:149], 11, v[150:151]
	v_lshl_add_u64 v[152:153], v[146:147], 0, v[148:149]
	global_load_dwordx4 v[154:157], v[152:153], off
	global_load_dwordx4 v[158:161], v[152:153], off offset:256
	v_or_b32_e32 v152, 16, v150
	v_ashrrev_i32_e32 v153, 31, v152
	v_lshlrev_b64 v[184:185], 11, v[152:153]
	v_lshl_add_u64 v[152:153], v[146:147], 0, v[184:185]
	global_load_dwordx4 v[164:167], v[152:153], off
	global_load_dwordx4 v[168:171], v[152:153], off offset:256
	v_or_b32_e32 v152, 32, v150
	v_ashrrev_i32_e32 v153, 31, v152
	v_lshlrev_b64 v[162:163], 11, v[152:153]
	v_lshl_add_u64 v[152:153], v[146:147], 0, v[162:163]
	global_load_dwordx4 v[172:175], v[152:153], off
	global_load_dwordx4 v[192:195], v[152:153], off offset:256
	v_or_b32_e32 v152, 48, v150
	v_ashrrev_i32_e32 v153, 31, v152
	v_lshlrev_b64 v[152:153], 11, v[152:153]
	v_lshl_add_u64 v[180:181], v[146:147], 0, v[152:153]
	global_load_dwordx4 v[196:199], v[180:181], off
	global_load_dwordx4 v[200:203], v[180:181], off offset:256
	s_waitcnt vmcnt(0)
	v_lshlrev_b32_e32 v204, 16, v154
	v_and_b32_e32 v205, 0xffff0000, v154
	v_lshlrev_b32_e32 v208, 16, v155
	v_and_b32_e32 v209, 0xffff0000, v155
	v_lshlrev_b32_e32 v210, 16, v156
	v_and_b32_e32 v211, 0xffff0000, v156
	v_lshlrev_b32_e32 v226, 16, v166
	v_and_b32_e32 v227, 0xffff0000, v166
	v_lshlrev_b32_e32 v228, 16, v167
	v_and_b32_e32 v229, 0xffff0000, v167
	v_lshlrev_b32_e32 v234, 16, v170
	v_and_b32_e32 v235, 0xffff0000, v170
	v_lshlrev_b32_e32 v236, 16, v171
	v_and_b32_e32 v237, 0xffff0000, v171
	v_lshlrev_b32_e32 v212, 16, v157
	v_lshlrev_b32_e32 v166, 16, v196
	v_and_b32_e32 v167, 0xffff0000, v196
	v_lshlrev_b32_e32 v170, 16, v197
	v_and_b32_e32 v171, 0xffff0000, v197
	v_lshl_add_u64 v[196:197], s[84:85], 0, v[148:149]
	v_and_b32_e32 v213, 0xffff0000, v157
	v_lshlrev_b32_e32 v238, 16, v172
	v_and_b32_e32 v239, 0xffff0000, v172
	v_lshlrev_b32_e32 v240, 16, v173
	v_and_b32_e32 v241, 0xffff0000, v173
	v_lshlrev_b32_e32 v172, 16, v194
	v_and_b32_e32 v173, 0xffff0000, v194
	v_lshlrev_b32_e32 v180, 16, v195
	v_and_b32_e32 v181, 0xffff0000, v195
	v_pk_add_f32 v[126:127], v[126:127], v[208:209]
	v_pk_add_f32 v[124:125], v[124:125], v[204:205]
	v_pk_add_f32 v[194:195], v[120:121], v[210:211]
	v_cvt_pk_bf16_f32 v120, v124, v125
	v_cvt_pk_bf16_f32 v121, v126, v127
	v_lshl_add_u64 v[196:197], v[196:197], 0, v[144:145]
	v_lshlrev_b32_e32 v242, 16, v174
	v_and_b32_e32 v243, 0xffff0000, v174
	v_lshlrev_b32_e32 v244, 16, v175
	v_and_b32_e32 v245, 0xffff0000, v175
	v_lshlrev_b32_e32 v174, 16, v192
	v_and_b32_e32 v175, 0xffff0000, v192
	v_lshlrev_b32_e32 v182, 16, v193
	v_and_b32_e32 v183, 0xffff0000, v193
	v_pk_add_f32 v[192:193], v[122:123], v[212:213]
	v_cvt_pk_bf16_f32 v122, v194, v195
	v_lshlrev_b32_e32 v214, 16, v158
	v_cvt_pk_bf16_f32 v123, v192, v193
	global_store_dwordx4 v[196:197], v[120:123], off
	v_and_b32_e32 v215, 0xffff0000, v158
	v_lshlrev_b32_e32 v216, 16, v159
	v_mul_f32_e32 v120, v125, v125
	v_mul_f32_e32 v121, v127, v127
	v_fmac_f32_e32 v120, v124, v124
	v_fmac_f32_e32 v121, v126, v126
	v_add_f32_e32 v120, v120, v121
	v_mul_f32_e32 v121, v195, v195
	v_fmac_f32_e32 v121, v194, v194
	v_and_b32_e32 v217, 0xffff0000, v159
	v_lshlrev_b32_e32 v218, 16, v160
	v_and_b32_e32 v219, 0xffff0000, v160
	v_add_f32_e32 v120, v121, v120
	v_mul_f32_e32 v121, v193, v193
	v_lshlrev_b32_e32 v220, 16, v161
	v_and_b32_e32 v221, 0xffff0000, v161
	v_fmac_f32_e32 v121, v192, v192
	v_pk_add_f32 v[118:119], v[118:119], v[216:217]
	v_pk_add_f32 v[116:117], v[116:117], v[214:215]
	v_pk_add_f32 v[122:123], v[112:113], v[218:219]
	v_cvt_pk_bf16_f32 v112, v116, v117
	v_cvt_pk_bf16_f32 v113, v118, v119
	v_add_f32_e32 v124, v121, v120
	v_pk_add_f32 v[120:121], v[114:115], v[220:221]
	v_cvt_pk_bf16_f32 v114, v122, v123
	v_lshlrev_b32_e32 v222, 16, v164
	v_cvt_pk_bf16_f32 v115, v120, v121
	global_store_dwordx4 v[196:197], v[112:115], off offset:256
	v_and_b32_e32 v223, 0xffff0000, v164
	v_lshlrev_b32_e32 v224, 16, v165
	v_mul_f32_e32 v112, v117, v117
	v_mul_f32_e32 v113, v119, v119
	v_fmac_f32_e32 v112, v116, v116
	v_fmac_f32_e32 v113, v118, v118
	v_add_f32_e32 v112, v112, v113
	v_mul_f32_e32 v113, v123, v123
	v_fmac_f32_e32 v113, v122, v122
	v_add_f32_e32 v112, v113, v112
	v_mul_f32_e32 v113, v121, v121
	v_and_b32_e32 v225, 0xffff0000, v165
	v_fmac_f32_e32 v113, v120, v120
	v_lshl_add_u64 v[116:117], s[84:85], 0, v[184:185]
	v_add_f32_e32 v112, v113, v112
	v_pk_add_f32 v[110:111], v[110:111], v[224:225]
	v_pk_add_f32 v[108:109], v[108:109], v[222:223]
	v_pk_add_f32 v[114:115], v[104:105], v[226:227]
	v_cvt_pk_bf16_f32 v104, v108, v109
	v_cvt_pk_bf16_f32 v105, v110, v111
	v_lshl_add_u64 v[116:117], v[116:117], 0, v[144:145]
	v_add_f32_e32 v118, v124, v112
	v_pk_add_f32 v[112:113], v[106:107], v[228:229]
	v_cvt_pk_bf16_f32 v106, v114, v115
	v_lshlrev_b32_e32 v230, 16, v168
	v_cvt_pk_bf16_f32 v107, v112, v113
	global_store_dwordx4 v[116:117], v[104:107], off
	v_and_b32_e32 v231, 0xffff0000, v168
	v_lshlrev_b32_e32 v232, 16, v169
	v_mul_f32_e32 v104, v109, v109
	v_mul_f32_e32 v105, v111, v111
	v_fmac_f32_e32 v104, v108, v108
	v_fmac_f32_e32 v105, v110, v110
	v_add_f32_e32 v104, v104, v105
	v_mul_f32_e32 v105, v115, v115
	v_fmac_f32_e32 v105, v114, v114
	v_and_b32_e32 v233, 0xffff0000, v169
; __device__ __forceinline__ unsigned cvt_pk_bf16(float lo, float hi) { unsigned r; asm volatile("v_cvt_pk_bf16_f32 %0, %1, %2" : "=v"(r) : "v"(lo), "v"(hi)); return r; }
;     __device__ __forceinline__ void operator()(const f32x4 (&acc)[2][2][4][2], const Unit& u, int wr, int wc, int fr, int fq, const float (&epre)[1]) const {
;     ...
;             for (int m = 0; m < 4; ++m) { const int row = row0 + ai * 128 + m * 16;
;                 float ss = 0.f;
; #pragma unroll
;                 for (int bj = 0; bj < 2; ++bj) { const f32x4 h0 = bv[m][bj][0] + acc[ai][bj][m][0], h1 = bv[m][bj][1] + acc[ai][bj][m][1];
;                     u32x4 w; w.x = cvt_pk_bf16(h0[0], h0[1]); w.y = cvt_pk_bf16(h0[2], h0[3]); w.z = cvt_pk_bf16(h1[0], h1[1]); w.w = cvt_pk_bf16(h1[2], h1[3]);
;                     *(u32x4*)(HBo + (size_t)row * DM + col0 + bj * 128) = w;
;                     ss += (h0[0] * h0[0] + h0[1] * h0[1]) + (h0[2] * h0[2] + h0[3] * h0[3]) + (h1[0] * h1[0] + h1[1] * h1[1]) + (h1[2] * h1[2] + h1[3] * h1[3]); }
;                 ssv[m] = ss;
;             }
; #pragma unroll
;             for (int m = 0; m < 4; ++m) ssv[m] += __shfl_xor(ssv[m], 16);
; #pragma unroll
;             for (int m = 0; m < 4; ++m) ssv[m] += __shfl_xor(ssv[m], 32);
;             if (fq == 0) {
; #pragma unroll
;                 for (int m = 0; m < 4; ++m) atomicAdd(sumsq + row0 + ai * 128 + m * 16, ssv[m]); }
	v_add_f32_e32 v104, v105, v104
	v_mul_f32_e32 v105, v113, v113
	v_fmac_f32_e32 v105, v112, v112
	v_pk_add_f32 v[102:103], v[102:103], v[232:233]
	v_pk_add_f32 v[100:101], v[100:101], v[230:231]
	v_pk_add_f32 v[106:107], v[96:97], v[234:235]
	v_cvt_pk_bf16_f32 v96, v100, v101
	v_cvt_pk_bf16_f32 v97, v102, v103
	v_add_f32_e32 v108, v105, v104
	v_pk_add_f32 v[104:105], v[98:99], v[236:237]
	v_cvt_pk_bf16_f32 v98, v106, v107
	v_pk_add_f32 v[94:95], v[94:95], v[240:241]
	v_cvt_pk_bf16_f32 v99, v104, v105
	global_store_dwordx4 v[116:117], v[96:99], off offset:256
	v_pk_add_f32 v[92:93], v[92:93], v[238:239]
	v_pk_add_f32 v[86:87], v[86:87], v[182:183]
	v_mul_f32_e32 v96, v101, v101
	v_mul_f32_e32 v97, v103, v103
	v_fmac_f32_e32 v96, v100, v100
	v_fmac_f32_e32 v97, v102, v102
	v_add_f32_e32 v96, v96, v97
	v_mul_f32_e32 v97, v107, v107
	v_fmac_f32_e32 v97, v106, v106
	v_add_f32_e32 v96, v97, v96
	v_mul_f32_e32 v97, v105, v105
	v_fmac_f32_e32 v97, v104, v104
	v_lshl_add_u64 v[100:101], s[84:85], 0, v[162:163]
	v_add_f32_e32 v96, v97, v96
	v_pk_add_f32 v[98:99], v[88:89], v[242:243]
	v_cvt_pk_bf16_f32 v88, v92, v93
	v_cvt_pk_bf16_f32 v89, v94, v95
	v_lshl_add_u64 v[100:101], v[100:101], 0, v[144:145]
	v_add_f32_e32 v102, v108, v96
	v_pk_add_f32 v[96:97], v[90:91], v[244:245]
	v_cvt_pk_bf16_f32 v90, v98, v99
	v_pk_add_f32 v[84:85], v[84:85], v[174:175]
	v_cvt_pk_bf16_f32 v91, v96, v97
	global_store_dwordx4 v[100:101], v[88:91], off
	v_lshlrev_b32_e32 v164, 16, v198
	v_and_b32_e32 v165, 0xffff0000, v198
	v_mul_f32_e32 v88, v93, v93
	v_mul_f32_e32 v89, v95, v95
	v_fmac_f32_e32 v88, v92, v92
	v_fmac_f32_e32 v89, v94, v94
	v_add_f32_e32 v88, v88, v89
	v_mul_f32_e32 v89, v99, v99
	v_fmac_f32_e32 v89, v98, v98
	v_add_f32_e32 v88, v89, v88
	v_mul_f32_e32 v89, v97, v97
	v_fmac_f32_e32 v89, v96, v96
	v_pk_add_f32 v[90:91], v[80:81], v[172:173]
	v_cvt_pk_bf16_f32 v80, v84, v85
	v_cvt_pk_bf16_f32 v81, v86, v87
	v_add_f32_e32 v92, v89, v88
	v_pk_add_f32 v[88:89], v[82:83], v[180:181]
	v_cvt_pk_bf16_f32 v82, v90, v91
	v_lshlrev_b32_e32 v168, 16, v199
	v_cvt_pk_bf16_f32 v83, v88, v89
	global_store_dwordx4 v[100:101], v[80:83], off offset:256
	v_and_b32_e32 v169, 0xffff0000, v199
	v_lshlrev_b32_e32 v156, 16, v200
	v_mul_f32_e32 v80, v85, v85
	v_mul_f32_e32 v81, v87, v87
	v_fmac_f32_e32 v80, v84, v84
	v_fmac_f32_e32 v81, v86, v86
	v_add_f32_e32 v80, v80, v81
	v_mul_f32_e32 v81, v91, v91
	v_fmac_f32_e32 v81, v90, v90
	v_add_f32_e32 v80, v81, v80
	v_mul_f32_e32 v81, v89, v89
	v_fmac_f32_e32 v81, v88, v88
	v_lshl_add_u64 v[84:85], s[84:85], 0, v[152:153]
	v_and_b32_e32 v157, 0xffff0000, v200
	v_lshlrev_b32_e32 v160, 16, v201
	v_and_b32_e32 v161, 0xffff0000, v201
	v_add_f32_e32 v80, v81, v80
	v_pk_add_f32 v[78:79], v[78:79], v[170:171]
	v_pk_add_f32 v[76:77], v[76:77], v[166:167]
	v_pk_add_f32 v[82:83], v[72:73], v[164:165]
	v_cvt_pk_bf16_f32 v72, v76, v77
	v_cvt_pk_bf16_f32 v73, v78, v79
	v_lshl_add_u64 v[84:85], v[84:85], 0, v[144:145]
	v_lshlrev_b32_e32 v158, 16, v203
	v_and_b32_e32 v159, 0xffff0000, v203
	v_add_f32_e32 v86, v92, v80
	v_pk_add_f32 v[80:81], v[74:75], v[168:169]
	v_cvt_pk_bf16_f32 v74, v82, v83
	v_pk_add_f32 v[70:71], v[70:71], v[160:161]
	v_cvt_pk_bf16_f32 v75, v80, v81
	global_store_dwordx4 v[84:85], v[72:75], off
	v_pk_add_f32 v[68:69], v[68:69], v[156:157]
	v_lshlrev_b32_e32 v154, 16, v202
	v_mul_f32_e32 v73, v79, v79
	v_and_b32_e32 v155, 0xffff0000, v202
	v_mul_f32_e32 v72, v77, v77
	v_fmac_f32_e32 v73, v78, v78
	v_pk_add_f32 v[78:79], v[66:67], v[158:159]
	v_mul_f32_e32 v66, v69, v69
	v_mul_f32_e32 v67, v71, v71
	v_fmac_f32_e32 v72, v76, v76
	v_pk_add_f32 v[64:65], v[64:65], v[154:155]
	v_fmac_f32_e32 v66, v68, v68
	v_fmac_f32_e32 v67, v70, v70
	v_add_f32_e32 v72, v72, v73
	v_mul_f32_e32 v73, v83, v83
	v_add_f32_e32 v66, v66, v67
	v_mul_f32_e32 v67, v65, v65
	v_fmac_f32_e32 v73, v82, v82
	v_fmac_f32_e32 v67, v64, v64
	v_add_f32_e32 v72, v73, v72
	v_mul_f32_e32 v73, v81, v81
	v_add_f32_e32 v66, v67, v66
	v_mul_f32_e32 v67, v79, v79
	v_fmac_f32_e32 v73, v80, v80
	v_fmac_f32_e32 v67, v78, v78
	v_add_f32_e32 v72, v73, v72
	v_add_f32_e32 v66, v67, v66
	v_and_b32_e32 v67, 64, v191
	v_cvt_pk_bf16_f32 v74, v68, v69
	v_add_f32_e32 v69, v72, v66
	v_xor_b32_e32 v66, 16, v191
	v_add_u32_e32 v72, 64, v67
	v_cmp_lt_i32_e32 vcc, v66, v72
	v_cvt_pk_bf16_f32 v75, v70, v71
	v_xor_b32_e32 v70, 32, v191
	v_cvt_pk_bf16_f32 v76, v64, v65
	v_lshl_add_u64 v[64:65], v[150:151], 2, s[14:15]
	v_cndmask_b32_e32 v66, v191, v66, vcc
	v_lshlrev_b32_e32 v94, 2, v66
	ds_bpermute_b32 v66, v94, v118
	ds_bpermute_b32 v67, v94, v102
	ds_bpermute_b32 v68, v94, v86
	ds_bpermute_b32 v73, v94, v69
	v_cmp_lt_i32_e32 vcc, v70, v72
	s_waitcnt lgkmcnt(0)
	v_add_f32_e32 v66, v118, v66
	v_add_f32_e32 v67, v102, v67
	v_cndmask_b32_e32 v70, v191, v70, vcc
	v_add_f32_e32 v68, v86, v68
	v_add_f32_e32 v69, v69, v73
	v_lshlrev_b32_e32 v95, 2, v70
	ds_bpermute_b32 v70, v95, v66
	ds_bpermute_b32 v71, v95, v67
	ds_bpermute_b32 v72, v95, v68
	ds_bpermute_b32 v73, v95, v69
	v_cvt_pk_bf16_f32 v77, v78, v79
	global_store_dwordx4 v[84:85], v[74:77], off offset:256
	s_and_saveexec_b64 s[26:27], s[6:7]
	s_cbranch_execz .LBB0_783
	s_waitcnt lgkmcnt(3)
	v_add_f32_e32 v66, v66, v70
	s_waitcnt lgkmcnt(0)
	v_add_f32_e32 v69, v69, v73
	v_add_f32_e32 v68, v68, v72
	v_add_f32_e32 v67, v67, v71
	global_atomic_add_f32 v[64:65], v66, off
	global_atomic_add_f32 v[64:65], v67, off offset:64
	global_atomic_add_f32 v[64:65], v68, off offset:128
	global_atomic_add_f32 v[64:65], v69, off offset:192

; #define PG8_STAGE(bufoff, gbase, voff) do { _Pragma("unroll") for (int _i = 0; _i < 2; ++_i) \
;         __builtin_amdgcn_global_load_lds((const unsigned*)((const char*)(gbase) + (voff)[_i]), (PG8_LAS unsigned*)(lds + (bufoff) + ldsw + _i * 8192), 16, 0, 0); } while (0)
; #define PG8_LDA(dst, b, h) do { _Pragma("unroll") for (int m = 0; m < 4; ++m) _Pragma("unroll") for (int k = 0; k < 2; ++k) dst[m][k] = *(const PG8_LAS bf16x8*)(lds + PG8_SA(b, h) + aoff + m * 2048 + k * 1024); } while (0)
; #define PG8_LDB(dst, b, h) do { _Pragma("unroll") for (int n = 0; n < 2; ++n) _Pragma("unroll") for (int k = 0; k < 2; ++k) dst[n][k] = *(const PG8_LAS bf16x8*)(lds + PG8_SB(b, h) + boff + n * 2048 + k * 1024); } while (0)
; #define PG8_MMA(ai, bj, At, Bt) do { __builtin_amdgcn_s_setprio(1); _Pragma("unroll") for (int m = 0; m < 4; ++m) _Pragma("unroll") for (int n = 0; n < 2; ++n) _Pragma("unroll") for (int k = 0; k < 2; ++k) \
;         acc[ai][bj][m][n] = __builtin_amdgcn_mfma_f32_16x16x32_bf16(Bt[n][k], At[m][k], acc[ai][bj][m][n], 0, 0, 0); __builtin_amdgcn_s_setprio(0); } while (0)
; template <class Epi, class Sched>
; __device__ __forceinline__ void gemm_phase(PG8_LAS unsigned char* lds, const Gemm g, const Sched& S, const Epi& E) {
;     ...
;         const bool has_next = S.next(ui + 1, nxt);
;         const char* nA = has_next ? (const char*)g.A + (size_t)nxt.pm * tstep : cA; const char* nB = has_next ? (const char*)g.Bt + (size_t)nxt.pn * tstep : cB;
;         for (int t = 0; t < nt; t += 2) {
;             const bool last = (t == nt - 2);
;             const char* a1 = cA + (size_t)(t + 1) * kstep;
;             const char* a2 = last ? nA : cA + (size_t)(t + 2) * kstep; const char* b2 = last ? nB : cB + (size_t)(t + 2) * kstep;
;             const char* a3 = a2 + kstep; const char* b3 = b2 + kstep;
;             if (last && has_next) S.a_ready(nxt);
;             PG8_LDB(B0, 0, 0); PG8_SCHED; PG8_LDA(At, 0, 0); PG8_STAGE(PG8_SA(1, 1), a1 + hstep, voffA);
;             PG8_WAIT_L(8); PG8_BAR; PG8_WAIT_L(0); PG8_MMA(0, 0, At, B0); PG8_BAR; PG8_SCHED;
;             PG8_LDB(B1, 0, 1); PG8_STAGE(PG8_SB(0, 0), b2, voffB);
;             PG8_BAR; PG8_WAIT_L(0); PG8_MMA(0, 1, At, B1); PG8_BAR;
;             PG8_LDA(At, 0, 1); PG8_STAGE(PG8_SA(0, 0), a2, voffA);
;             PG8_BAR; PG8_WAIT_L(0); PG8_MMA(1, 0, At, B0); PG8_BAR; PG8_SCHED;
.LBB0_884:
	s_ashr_i32 s19, s18, 31
	v_cmp_lt_i64_e32 vcc, s[20:21], v[192:193]
	s_lshl_b64 s[20:21], s[18:19], 19
	s_add_u32 s20, s84, s20
	s_addc_u32 s21, s85, s21
	s_and_b64 s[22:23], vcc, exec
	s_cselect_b32 s19, s21, s25
	s_cselect_b32 s41, s20, s24
	s_ashr_i32 s17, s16, 31
	s_lshl_b64 s[22:23], s[16:17], 19
	s_add_u32 s22, s8, s22
	s_addc_u32 s23, s9, s23
	s_and_b64 s[28:29], vcc, exec
	s_cselect_b32 s17, s23, s27
	s_cselect_b32 s42, s22, s26
	s_add_u32 s24, s24, 0x40080
	s_addc_u32 s25, s25, 0
	s_add_u32 s43, s26, 0x100
	s_addc_u32 s44, s27, 0
	s_mov_b32 s45, -2
	s_waitcnt lgkmcnt(0)
	ds_read_b128 v[130:133], v209
	ds_read_b128 v[134:137], v209 offset:1024
	ds_read_b128 v[138:141], v209 offset:2048
	ds_read_b128 v[142:145], v209 offset:3072
	s_add_u32 s26, s24, 0xfffc0080
	s_addc_u32 s27, s25, -1
	s_cmp_eq_u32 s45, 12
	s_cselect_b32 s29, s19, s27
	s_cselect_b32 s28, s41, s26
	s_cselect_b32 s27, s17, s44
	s_cselect_b32 s26, s42, s43
	v_lshl_add_u64 v[174:175], s[24:25], 0, v[188:189]
	s_add_i32 m0, s30, 0xc000
	ds_read_b128 v[146:149], v210
	ds_read_b128 v[150:153], v210 offset:1024
	ds_read_b128 v[154:157], v210 offset:2048
	ds_read_b128 v[158:161], v210 offset:3072
	ds_read_b128 v[162:165], v210 offset:4096
	ds_read_b128 v[166:169], v210 offset:5120
	ds_read_b128 v[170:173], v210 offset:6144
	ds_read_b128 v[196:199], v210 offset:7168
	global_load_lds_dwordx4 v[174:175], off
	v_lshl_add_u64 v[174:175], s[24:25], 0, v[190:191]
	s_add_i32 m0, s30, 0xe000
	s_nop 0
	global_load_lds_dwordx4 v[174:175], off
	s_waitcnt lgkmcnt(8)
	s_barrier
	s_waitcnt lgkmcnt(0)
	s_setprio 1
	v_mfma_f32_16x16x32_bf16 v[124:127], v[130:133], v[146:149], 0
	v_mfma_f32_16x16x32_bf16 v[120:123], v[138:141], v[146:149], 0
	v_mfma_f32_16x16x32_bf16 v[108:111], v[130:133], v[154:157], 0
	v_mfma_f32_16x16x32_bf16 v[104:107], v[138:141], v[154:157], 0
	v_mfma_f32_16x16x32_bf16 v[92:95], v[130:133], v[162:165], 0
	v_mfma_f32_16x16x32_bf16 v[88:91], v[138:141], v[162:165], 0
	v_mfma_f32_16x16x32_bf16 v[76:79], v[130:133], v[170:173], 0
	v_mfma_f32_16x16x32_bf16 v[72:75], v[138:141], v[170:173], 0
	v_mfma_f32_16x16x32_bf16 v[124:127], v[134:137], v[150:153], v[124:127]
	v_mfma_f32_16x16x32_bf16 v[120:123], v[142:145], v[150:153], v[120:123]
	v_mfma_f32_16x16x32_bf16 v[108:111], v[134:137], v[158:161], v[108:111]
	v_mfma_f32_16x16x32_bf16 v[104:107], v[142:145], v[158:161], v[104:107]
	v_mfma_f32_16x16x32_bf16 v[92:95], v[134:137], v[166:169], v[92:95]
	v_mfma_f32_16x16x32_bf16 v[88:91], v[142:145], v[166:169], v[88:91]
	v_mfma_f32_16x16x32_bf16 v[76:79], v[134:137], v[196:199], v[76:79]
	v_mfma_f32_16x16x32_bf16 v[72:75], v[142:145], v[196:199], v[72:75]
	s_setprio 0
	s_barrier
	s_add_i32 s46, s38, s3
	v_lshl_add_u64 v[174:175], s[26:27], 0, v[182:183]
	s_mov_b32 m0, s46
	ds_read_b128 v[200:203], v211
	ds_read_b128 v[220:223], v211 offset:1024
	ds_read_b128 v[224:227], v211 offset:2048
	ds_read_b128 v[228:231], v211 offset:3072
	global_load_lds_dwordx4 v[174:175], off
	v_lshl_add_u64 v[204:205], s[26:27], 0, v[186:187]
	s_add_i32 m0, s46, 0x2000
	s_nop 0
	global_load_lds_dwordx4 v[204:205], off
	s_barrier
	s_waitcnt lgkmcnt(0)
	s_setprio 1
	v_mfma_f32_16x16x32_bf16 v[116:119], v[200:203], v[146:149], 0
	v_mfma_f32_16x16x32_bf16 v[112:115], v[224:227], v[146:149], 0
	v_mfma_f32_16x16x32_bf16 v[100:103], v[200:203], v[154:157], 0
	v_mfma_f32_16x16x32_bf16 v[96:99], v[224:227], v[154:157], 0
	v_mfma_f32_16x16x32_bf16 v[84:87], v[200:203], v[162:165], 0
	v_mfma_f32_16x16x32_bf16 v[80:83], v[224:227], v[162:165], 0
	v_mfma_f32_16x16x32_bf16 v[68:71], v[200:203], v[170:173], 0
	v_mfma_f32_16x16x32_bf16 v[64:67], v[224:227], v[170:173], 0
	v_mfma_f32_16x16x32_bf16 v[116:119], v[220:223], v[150:153], v[116:119]
	v_mfma_f32_16x16x32_bf16 v[112:115], v[228:231], v[150:153], v[112:115]
	v_mfma_f32_16x16x32_bf16 v[100:103], v[220:223], v[158:161], v[100:103]
	v_mfma_f32_16x16x32_bf16 v[96:99], v[228:231], v[158:161], v[96:99]
	v_mfma_f32_16x16x32_bf16 v[84:87], v[220:223], v[166:169], v[84:87]
	v_mfma_f32_16x16x32_bf16 v[80:83], v[228:231], v[166:169], v[80:83]
	v_mfma_f32_16x16x32_bf16 v[68:71], v[220:223], v[196:199], v[68:71]
	v_mfma_f32_16x16x32_bf16 v[64:67], v[228:231], v[196:199], v[64:67]
	s_setprio 0
	s_mov_b32 m0, s30
	v_lshl_add_u64 v[232:233], s[28:29], 0, v[180:181]
	s_barrier
	ds_read_b128 v[146:149], v210 offset:16384
	ds_read_b128 v[150:153], v210 offset:17408
	ds_read_b128 v[154:157], v210 offset:18432
	ds_read_b128 v[158:161], v210 offset:19456
	ds_read_b128 v[162:165], v210 offset:20480
	ds_read_b128 v[166:169], v210 offset:21504
	ds_read_b128 v[170:173], v210 offset:22528
	ds_read_b128 v[196:199], v210 offset:23552
	global_load_lds_dwordx4 v[232:233], off
	v_lshl_add_u64 v[234:235], s[28:29], 0, v[184:185]
	s_mov_b32 m0, s31
	s_nop 0
	global_load_lds_dwordx4 v[234:235], off
	s_barrier
	s_waitcnt lgkmcnt(0)
	s_setprio 1
	v_mfma_f32_16x16x32_bf16 v[60:63], v[130:133], v[146:149], 0
	v_mfma_f32_16x16x32_bf16 v[56:59], v[138:141], v[146:149], 0
	v_mfma_f32_16x16x32_bf16 v[44:47], v[130:133], v[154:157], 0
	v_mfma_f32_16x16x32_bf16 v[40:43], v[138:141], v[154:157], 0
	v_mfma_f32_16x16x32_bf16 v[28:31], v[130:133], v[162:165], 0
	v_mfma_f32_16x16x32_bf16 v[24:27], v[138:141], v[162:165], 0
	v_mfma_f32_16x16x32_bf16 v[12:15], v[130:133], v[170:173], 0
	v_mfma_f32_16x16x32_bf16 v[8:11], v[138:141], v[170:173], 0
	v_mfma_f32_16x16x32_bf16 v[60:63], v[134:137], v[150:153], v[60:63]
	v_mfma_f32_16x16x32_bf16 v[56:59], v[142:145], v[150:153], v[56:59]
	v_mfma_f32_16x16x32_bf16 v[44:47], v[134:137], v[158:161], v[44:47]
	v_mfma_f32_16x16x32_bf16 v[40:43], v[142:145], v[158:161], v[40:43]
	v_mfma_f32_16x16x32_bf16 v[28:31], v[134:137], v[166:169], v[28:31]
	v_mfma_f32_16x16x32_bf16 v[24:27], v[142:145], v[166:169], v[24:27]
	v_mfma_f32_16x16x32_bf16 v[12:15], v[134:137], v[196:199], v[12:15]
	v_mfma_f32_16x16x32_bf16 v[8:11], v[142:145], v[196:199], v[8:11]
	s_setprio 0
	s_barrier
; #define PG8_STAGE(bufoff, gbase, voff) do { _Pragma("unroll") for (int _i = 0; _i < 2; ++_i) \
;         __builtin_amdgcn_global_load_lds((const unsigned*)((const char*)(gbase) + (voff)[_i]), (PG8_LAS unsigned*)(lds + (bufoff) + ldsw + _i * 8192), 16, 0, 0); } while (0)
; #define PG8_LDA(dst, b, h) do { _Pragma("unroll") for (int m = 0; m < 4; ++m) _Pragma("unroll") for (int k = 0; k < 2; ++k) dst[m][k] = *(const PG8_LAS bf16x8*)(lds + PG8_SA(b, h) + aoff + m * 2048 + k * 1024); } while (0)
; #define PG8_LDB(dst, b, h) do { _Pragma("unroll") for (int n = 0; n < 2; ++n) _Pragma("unroll") for (int k = 0; k < 2; ++k) dst[n][k] = *(const PG8_LAS bf16x8*)(lds + PG8_SB(b, h) + boff + n * 2048 + k * 1024); } while (0)
; #define PG8_MMA(ai, bj, At, Bt) do { __builtin_amdgcn_s_setprio(1); _Pragma("unroll") for (int m = 0; m < 4; ++m) _Pragma("unroll") for (int n = 0; n < 2; ++n) _Pragma("unroll") for (int k = 0; k < 2; ++k) \
;         acc[ai][bj][m][n] = __builtin_amdgcn_mfma_f32_16x16x32_bf16(Bt[n][k], At[m][k], acc[ai][bj][m][n], 0, 0, 0); __builtin_amdgcn_s_setprio(0); } while (0)
; #define PG8_WAIT_V(n) asm volatile("s_waitcnt vmcnt(" #n ")" ::: "memory")
; #define PG8_WAIT_L(n) asm volatile("s_waitcnt lgkmcnt(" #n ")" ::: "memory")
; #define PG8_BAR __builtin_amdgcn_s_barrier()
; #define PG8_SCHED __builtin_amdgcn_sched_barrier(0)
; template <class Epi, class Sched>
; __device__ __forceinline__ void gemm_phase(PG8_LAS unsigned char* lds, const Gemm g, const Sched& S, const Epi& E) {
;     ...
;             PG8_STAGE(PG8_SB(0, 1), b2 + hstep, voffB);
;             PG8_WAIT_V(6); PG8_BAR; PG8_MMA(1, 1, At, B1); PG8_BAR;
;             PG8_LDB(B0, 1, 0); PG8_SCHED; PG8_LDA(At, 1, 0); PG8_STAGE(PG8_SA(0, 1), a2 + hstep, voffA);
;             PG8_WAIT_L(8); PG8_BAR; PG8_WAIT_L(0); PG8_MMA(0, 0, At, B0); PG8_BAR; PG8_SCHED;
;             PG8_LDB(B1, 1, 1); PG8_STAGE(PG8_SB(1, 0), b3, voffB);
	s_add_u32 s46, s26, 0x40000
	s_addc_u32 s47, s27, 0
	s_add_i32 s48, s39, s3
	v_lshl_add_u64 v[130:131], s[46:47], 0, v[182:183]
	s_mov_b32 m0, s48
	s_nop 0
	global_load_lds_dwordx4 v[130:131], off
	v_lshl_add_u64 v[130:131], s[46:47], 0, v[186:187]
	s_add_i32 m0, s48, 0x2000
	s_nop 0
	global_load_lds_dwordx4 v[130:131], off
	s_waitcnt vmcnt(6)
	s_barrier
	s_setprio 1
	v_mfma_f32_16x16x32_bf16 v[52:55], v[200:203], v[146:149], 0
	v_mfma_f32_16x16x32_bf16 v[48:51], v[224:227], v[146:149], 0
	v_mfma_f32_16x16x32_bf16 v[36:39], v[200:203], v[154:157], 0
	v_mfma_f32_16x16x32_bf16 v[32:35], v[224:227], v[154:157], 0
	v_mfma_f32_16x16x32_bf16 v[20:23], v[200:203], v[162:165], 0
	v_mfma_f32_16x16x32_bf16 v[16:19], v[224:227], v[162:165], 0
	v_mfma_f32_16x16x32_bf16 v[4:7], v[200:203], v[170:173], 0
	v_mfma_f32_16x16x32_bf16 v[0:3], v[224:227], v[170:173], 0
	v_mfma_f32_16x16x32_bf16 v[52:55], v[220:223], v[150:153], v[52:55]
	v_mfma_f32_16x16x32_bf16 v[48:51], v[228:231], v[150:153], v[48:51]
	v_mfma_f32_16x16x32_bf16 v[36:39], v[220:223], v[158:161], v[36:39]
	v_mfma_f32_16x16x32_bf16 v[32:35], v[228:231], v[158:161], v[32:35]
	v_mfma_f32_16x16x32_bf16 v[20:23], v[220:223], v[166:169], v[20:23]
	v_mfma_f32_16x16x32_bf16 v[16:19], v[228:231], v[166:169], v[16:19]
	v_mfma_f32_16x16x32_bf16 v[4:7], v[220:223], v[196:199], v[4:7]
	v_mfma_f32_16x16x32_bf16 v[0:3], v[228:231], v[196:199], v[0:3]
	s_setprio 0
	s_add_i32 s46, 0, 0x18000
	v_add_u32_e32 v129, s46, v207
	s_barrier
	ds_read_b128 v[130:133], v129
	ds_read_b128 v[134:137], v129 offset:1024
	ds_read_b128 v[138:141], v129 offset:2048
	ds_read_b128 v[142:145], v129 offset:3072
	s_add_u32 s28, s28, 0x40000
	s_addc_u32 s29, s29, 0
	s_mov_b32 m0, s33
	v_lshl_add_u64 v[200:201], s[28:29], 0, v[180:181]
	ds_read_b128 v[146:149], v210 offset:32768
	ds_read_b128 v[150:153], v210 offset:33792
	ds_read_b128 v[154:157], v210 offset:34816
	ds_read_b128 v[158:161], v210 offset:35840
	ds_read_b128 v[162:165], v210 offset:36864
	ds_read_b128 v[166:169], v210 offset:37888
	ds_read_b128 v[170:173], v210 offset:38912
	ds_read_b128 v[196:199], v210 offset:39936
	global_load_lds_dwordx4 v[200:201], off
	v_lshl_add_u64 v[200:201], s[28:29], 0, v[184:185]
	s_mov_b32 m0, s34
	s_nop 0
	global_load_lds_dwordx4 v[200:201], off
	s_waitcnt lgkmcnt(8)
	s_barrier
	s_waitcnt lgkmcnt(0)
	s_setprio 1
	v_mfma_f32_16x16x32_bf16 v[124:127], v[130:133], v[146:149], v[124:127]
	v_mfma_f32_16x16x32_bf16 v[120:123], v[138:141], v[146:149], v[120:123]
	v_mfma_f32_16x16x32_bf16 v[108:111], v[130:133], v[154:157], v[108:111]
	v_mfma_f32_16x16x32_bf16 v[104:107], v[138:141], v[154:157], v[104:107]
	v_mfma_f32_16x16x32_bf16 v[92:95], v[130:133], v[162:165], v[92:95]
	v_mfma_f32_16x16x32_bf16 v[88:91], v[138:141], v[162:165], v[88:91]
	v_mfma_f32_16x16x32_bf16 v[76:79], v[130:133], v[170:173], v[76:79]
	v_mfma_f32_16x16x32_bf16 v[72:75], v[138:141], v[170:173], v[72:75]
	v_mfma_f32_16x16x32_bf16 v[124:127], v[134:137], v[150:153], v[124:127]
	v_mfma_f32_16x16x32_bf16 v[120:123], v[142:145], v[150:153], v[120:123]
	v_mfma_f32_16x16x32_bf16 v[108:111], v[134:137], v[158:161], v[108:111]
	v_mfma_f32_16x16x32_bf16 v[104:107], v[142:145], v[158:161], v[104:107]
	v_mfma_f32_16x16x32_bf16 v[92:95], v[134:137], v[166:169], v[92:95]
	v_mfma_f32_16x16x32_bf16 v[88:91], v[142:145], v[166:169], v[88:91]
	v_mfma_f32_16x16x32_bf16 v[76:79], v[134:137], v[196:199], v[76:79]
	v_mfma_f32_16x16x32_bf16 v[72:75], v[142:145], v[196:199], v[72:75]
	s_setprio 0
	s_barrier
	s_add_i32 s28, 0, 0x1c000
	s_add_i32 s29, s46, s3
	v_add_u32_e32 v129, s28, v207
	v_lshl_add_u64 v[174:175], v[174:175], 0, s[12:13]
	s_mov_b32 m0, s29
	ds_read_b128 v[200:203], v129
	ds_read_b128 v[220:223], v129 offset:1024
	ds_read_b128 v[224:227], v129 offset:2048
	ds_read_b128 v[228:231], v129 offset:3072
	global_load_lds_dwordx4 v[174:175], off
	v_lshl_add_u64 v[174:175], v[204:205], 0, s[12:13]
	s_add_i32 m0, s29, 0x2000
	s_nop 0
	global_load_lds_dwordx4 v[174:175], off
	s_barrier
; #define PG8_STAGE(bufoff, gbase, voff) do { _Pragma("unroll") for (int _i = 0; _i < 2; ++_i) \
;         __builtin_amdgcn_global_load_lds((const unsigned*)((const char*)(gbase) + (voff)[_i]), (PG8_LAS unsigned*)(lds + (bufoff) + ldsw + _i * 8192), 16, 0, 0); } while (0)
; #define PG8_LDA(dst, b, h) do { _Pragma("unroll") for (int m = 0; m < 4; ++m) _Pragma("unroll") for (int k = 0; k < 2; ++k) dst[m][k] = *(const PG8_LAS bf16x8*)(lds + PG8_SA(b, h) + aoff + m * 2048 + k * 1024); } while (0)
; #define PG8_LDB(dst, b, h) do { _Pragma("unroll") for (int n = 0; n < 2; ++n) _Pragma("unroll") for (int k = 0; k < 2; ++k) dst[n][k] = *(const PG8_LAS bf16x8*)(lds + PG8_SB(b, h) + boff + n * 2048 + k * 1024); } while (0)
; #define PG8_MMA(ai, bj, At, Bt) do { __builtin_amdgcn_s_setprio(1); _Pragma("unroll") for (int m = 0; m < 4; ++m) _Pragma("unroll") for (int n = 0; n < 2; ++n) _Pragma("unroll") for (int k = 0; k < 2; ++k) \
;         acc[ai][bj][m][n] = __builtin_amdgcn_mfma_f32_16x16x32_bf16(Bt[n][k], At[m][k], acc[ai][bj][m][n], 0, 0, 0); __builtin_amdgcn_s_setprio(0); } while (0)
; #define PG8_WAIT_V(n) asm volatile("s_waitcnt vmcnt(" #n ")" ::: "memory")
; #define PG8_WAIT_L(n) asm volatile("s_waitcnt lgkmcnt(" #n ")" ::: "memory")
; #define PG8_BAR __builtin_amdgcn_s_barrier()
; #define PG8_SCHED __builtin_amdgcn_sched_barrier(0)
; template <class Epi, class Sched>
; __device__ __forceinline__ void gemm_phase(PG8_LAS unsigned char* lds, const Gemm g, const Sched& S, const Epi& E) {
;     ...
;             PG8_LDB(B1, 1, 1); PG8_STAGE(PG8_SB(1, 0), b3, voffB);
;             PG8_BAR; PG8_WAIT_L(0); PG8_MMA(0, 1, At, B1); PG8_BAR;
;             PG8_LDA(At, 1, 1); PG8_STAGE(PG8_SA(1, 0), a3, voffA);
;             PG8_BAR; PG8_WAIT_L(0); PG8_MMA(1, 0, At, B0); PG8_BAR; PG8_SCHED;
;             PG8_STAGE(PG8_SB(1, 1), b3 + hstep, voffB);
;             PG8_WAIT_V(6); PG8_BAR; PG8_MMA(1, 1, At, B1); PG8_BAR;
	s_waitcnt lgkmcnt(0)
	s_setprio 1
	v_mfma_f32_16x16x32_bf16 v[116:119], v[200:203], v[146:149], v[116:119]
	v_mfma_f32_16x16x32_bf16 v[112:115], v[224:227], v[146:149], v[112:115]
	v_mfma_f32_16x16x32_bf16 v[100:103], v[200:203], v[154:157], v[100:103]
	v_mfma_f32_16x16x32_bf16 v[96:99], v[224:227], v[154:157], v[96:99]
	v_mfma_f32_16x16x32_bf16 v[84:87], v[200:203], v[162:165], v[84:87]
	v_mfma_f32_16x16x32_bf16 v[80:83], v[224:227], v[162:165], v[80:83]
	v_mfma_f32_16x16x32_bf16 v[68:71], v[200:203], v[170:173], v[68:71]
	v_mfma_f32_16x16x32_bf16 v[64:67], v[224:227], v[170:173], v[64:67]
	v_mfma_f32_16x16x32_bf16 v[116:119], v[220:223], v[150:153], v[116:119]
	v_mfma_f32_16x16x32_bf16 v[112:115], v[228:231], v[150:153], v[112:115]
	v_mfma_f32_16x16x32_bf16 v[100:103], v[220:223], v[158:161], v[100:103]
	v_mfma_f32_16x16x32_bf16 v[96:99], v[228:231], v[158:161], v[96:99]
	v_mfma_f32_16x16x32_bf16 v[84:87], v[220:223], v[166:169], v[84:87]
	v_mfma_f32_16x16x32_bf16 v[80:83], v[228:231], v[166:169], v[80:83]
	v_mfma_f32_16x16x32_bf16 v[68:71], v[220:223], v[196:199], v[68:71]
	v_mfma_f32_16x16x32_bf16 v[64:67], v[228:231], v[196:199], v[64:67]
	s_setprio 0
	s_mov_b32 m0, s36
	v_lshl_add_u64 v[174:175], v[232:233], 0, s[12:13]
	s_barrier
	ds_read_b128 v[146:149], v210 offset:49152
	ds_read_b128 v[150:153], v210 offset:50176
	ds_read_b128 v[154:157], v210 offset:51200
	ds_read_b128 v[158:161], v210 offset:52224
	ds_read_b128 v[162:165], v210 offset:53248
	ds_read_b128 v[166:169], v210 offset:54272
	ds_read_b128 v[170:173], v210 offset:55296
	ds_read_b128 v[196:199], v210 offset:56320
	global_load_lds_dwordx4 v[174:175], off
	v_lshl_add_u64 v[174:175], v[234:235], 0, s[12:13]
	s_mov_b32 m0, s37
	s_nop 0
	global_load_lds_dwordx4 v[174:175], off
	s_barrier
	s_waitcnt lgkmcnt(0)
	s_setprio 1
	v_mfma_f32_16x16x32_bf16 v[60:63], v[130:133], v[146:149], v[60:63]
	v_mfma_f32_16x16x32_bf16 v[56:59], v[138:141], v[146:149], v[56:59]
	v_mfma_f32_16x16x32_bf16 v[44:47], v[130:133], v[154:157], v[44:47]
	v_mfma_f32_16x16x32_bf16 v[40:43], v[138:141], v[154:157], v[40:43]
	v_mfma_f32_16x16x32_bf16 v[28:31], v[130:133], v[162:165], v[28:31]
	v_mfma_f32_16x16x32_bf16 v[24:27], v[138:141], v[162:165], v[24:27]
	v_mfma_f32_16x16x32_bf16 v[12:15], v[130:133], v[170:173], v[12:15]
	v_mfma_f32_16x16x32_bf16 v[8:11], v[138:141], v[170:173], v[8:11]
	v_mfma_f32_16x16x32_bf16 v[60:63], v[134:137], v[150:153], v[60:63]
	v_mfma_f32_16x16x32_bf16 v[56:59], v[142:145], v[150:153], v[56:59]
	v_mfma_f32_16x16x32_bf16 v[44:47], v[134:137], v[158:161], v[44:47]
	v_mfma_f32_16x16x32_bf16 v[40:43], v[142:145], v[158:161], v[40:43]
	v_mfma_f32_16x16x32_bf16 v[28:31], v[134:137], v[166:169], v[28:31]
	v_mfma_f32_16x16x32_bf16 v[24:27], v[142:145], v[166:169], v[24:27]
	v_mfma_f32_16x16x32_bf16 v[12:15], v[134:137], v[196:199], v[12:15]
	v_mfma_f32_16x16x32_bf16 v[8:11], v[142:145], v[196:199], v[8:11]
	s_setprio 0
	s_barrier
	s_add_u32 s26, s26, 0x40080
	s_addc_u32 s27, s27, 0
	s_add_i32 s28, s28, s3
	v_lshl_add_u64 v[130:131], s[26:27], 0, v[182:183]
	s_mov_b32 m0, s28
	s_nop 0
	global_load_lds_dwordx4 v[130:131], off
	v_lshl_add_u64 v[130:131], s[26:27], 0, v[186:187]
	s_add_i32 m0, s28, 0x2000
	s_nop 0
	global_load_lds_dwordx4 v[130:131], off
	s_waitcnt vmcnt(6)
	s_barrier
	s_setprio 1
	v_mfma_f32_16x16x32_bf16 v[52:55], v[200:203], v[146:149], v[52:55]
	v_mfma_f32_16x16x32_bf16 v[48:51], v[224:227], v[146:149], v[48:51]
	v_mfma_f32_16x16x32_bf16 v[36:39], v[200:203], v[154:157], v[36:39]
	v_mfma_f32_16x16x32_bf16 v[32:35], v[224:227], v[154:157], v[32:35]
	v_mfma_f32_16x16x32_bf16 v[20:23], v[200:203], v[162:165], v[20:23]
	v_mfma_f32_16x16x32_bf16 v[16:19], v[224:227], v[162:165], v[16:19]
	v_mfma_f32_16x16x32_bf16 v[4:7], v[200:203], v[170:173], v[4:7]
	v_mfma_f32_16x16x32_bf16 v[0:3], v[224:227], v[170:173], v[0:3]
	v_mfma_f32_16x16x32_bf16 v[52:55], v[220:223], v[150:153], v[52:55]
	v_mfma_f32_16x16x32_bf16 v[48:51], v[228:231], v[150:153], v[48:51]
	v_mfma_f32_16x16x32_bf16 v[36:39], v[220:223], v[158:161], v[36:39]
	v_mfma_f32_16x16x32_bf16 v[32:35], v[228:231], v[158:161], v[32:35]
	v_mfma_f32_16x16x32_bf16 v[20:23], v[220:223], v[166:169], v[20:23]
	v_mfma_f32_16x16x32_bf16 v[16:19], v[228:231], v[166:169], v[16:19]
	v_mfma_f32_16x16x32_bf16 v[4:7], v[220:223], v[196:199], v[4:7]
	v_mfma_f32_16x16x32_bf16 v[0:3], v[228:231], v[196:199], v[0:3]
	s_setprio 0
	s_add_i32 s45, s45, 2
	s_add_u32 s24, s24, 0x100
	s_addc_u32 s25, s25, 0
	s_add_u32 s43, s43, 0x100
	s_addc_u32 s44, s44, 0
	s_cmp_gt_u32 s45, 13
	s_barrier
	s_cbranch_scc1 .Lpeel_x4_LBB0885

; __device__ __forceinline__ unsigned cvt_pk_bf16(float lo, float hi) { unsigned r; asm volatile("v_cvt_pk_bf16_f32 %0, %1, %2" : "=v"(r) : "v"(lo), "v"(hi)); return r; }
; __device__ __forceinline__ float sigmoidf_(float x) { return frcp(1.0f + __expf(-x)); }
;     __device__ __forceinline__ void operator()(const f32x4 (&acc)[2][2][4][2], const Unit& u, int wr, int wc, int fr, int fq, const float (&epre)[8]) const {
;         const int row0 = u.pm * 256 + wr * 64 + fr, col0 = u.pn * 256 + wc * 32 + 8 * fq;
; #pragma unroll
;         for (int ai = 0; ai < 2; ++ai) {
;             float ssv[4];
;             u32x4 hw[4][2], pw[4][2];
; #pragma unroll
;             for (int m = 0; m < 4; ++m)
; #pragma unroll
;                 for (int bj = 0; bj < 2; ++bj) { const size_t o = (size_t)(row0 + ai * 128 + m * 16) * DM + col0 + bj * 128; hw[m][bj] = *(const u32x4*)(HB + o); pw[m][bj] = *(const u32x4*)(PPb + o); }
; #pragma unroll
;             for (int m = 0; m < 4; ++m) { const int row = row0 + ai * 128 + m * 16;
;                 const float rstd = rsqrtf(epre[ai * 4 + m] * (1.0f / DM) + EPS);
;                 float ss = 0.f;
; #pragma unroll
;                 for (int bj = 0; bj < 2; ++bj) { const size_t o = (size_t)row * DM + col0 + bj * 128;
;                     f32x4 h0, h1, p0, p1; unpack8(hw[m][bj], h0, h1); unpack8(pw[m][bj], p0, p1);
; #pragma unroll
;                     for (int j = 0; j < 4; ++j) { h0[j] += sigmoidf_(acc[ai][bj][m][0][j] * rstd) * p0[j]; h1[j] += sigmoidf_(acc[ai][bj][m][1][j] * rstd) * p1[j]; }
;                     u32x4 w; w.x = cvt_pk_bf16(h0[0], h0[1]); w.y = cvt_pk_bf16(h0[2], h0[3]); w.z = cvt_pk_bf16(h1[0], h1[1]); w.w = cvt_pk_bf16(h1[2], h1[3]);
;                     *(u32x4*)(H3 + o) = w;
;                     ss += (h0[0] * h0[0] + h0[1] * h0[1]) + (h0[2] * h0[2] + h0[3] * h0[3]) + (h1[0] * h1[0] + h1[1] * h1[1]) + (h1[2] * h1[2] + h1[3] * h1[3]); }
.Lpeel_x4_LBB0885:
	v_lshl_add_u32 v198, s6, 8, v177
	v_lshl_or_b32 v196, s7, 8, v208
	v_ashrrev_i32_e32 v199, 31, v198
	v_ashrrev_i32_e32 v197, 31, v196
	v_lshlrev_b64 v[130:131], 10, v[198:199]
	v_lshl_add_u64 v[130:131], v[130:131], 0, v[196:197]
	v_lshlrev_b64 v[130:131], 1, v[130:131]
	v_lshl_add_u64 v[132:133], s[84:85], 0, v[130:131]
	global_load_dwordx4 v[220:223], v[132:133], off
	v_lshl_add_u64 v[132:133], s[82:83], 0, v[130:131]
	global_load_dwordx4 v[224:227], v[132:133], off
	s_waitcnt vmcnt(0)
	v_fmamk_f32 v128, v128, 0x3a800000, v212
	v_or_b32_e32 v204, 16, v198
	v_mul_f32_e32 v129, 0x4b800000, v128
	v_ashrrev_i32_e32 v205, 31, v204
	v_cmp_gt_f32_e64 s[6:7], s40, v128
	v_or_b32_e32 v130, 0x100, v130
	v_or_b32_e32 v200, 48, v198
	v_cndmask_b32_e64 v136, v128, v129, s[6:7]
	v_lshlrev_b64 v[128:129], 10, v[204:205]
	v_lshl_add_u64 v[128:129], v[128:129], 0, v[196:197]
	v_rsq_f32_e32 v242, v136
	v_lshlrev_b64 v[128:129], 1, v[128:129]
	v_lshl_add_u64 v[136:137], s[84:85], 0, v[130:131]
	v_lshl_add_u64 v[130:131], s[82:83], 0, v[130:131]
	v_lshl_add_u64 v[138:139], s[84:85], 0, v[128:129]
	v_lshl_add_u64 v[140:141], s[82:83], 0, v[128:129]
	global_load_dwordx4 v[228:231], v[136:137], off
	global_load_dwordx4 v[232:235], v[130:131], off
	global_load_dwordx4 v[172:175], v[138:139], off
	global_load_dwordx4 v[168:171], v[140:141], off
	v_ashrrev_i32_e32 v201, 31, v200
	v_lshlrev_b64 v[134:135], 10, v[200:201]
	v_lshl_add_u64 v[134:135], v[134:135], 0, v[196:197]
	v_lshlrev_b64 v[134:135], 1, v[134:135]
	v_lshl_add_u64 v[146:147], s[84:85], 0, v[134:135]
	v_lshl_add_u64 v[148:149], s[82:83], 0, v[134:135]
	v_or_b32_e32 v134, 0x100, v134
	v_lshl_add_u64 v[238:239], s[84:85], 0, v[134:135]
	v_lshl_add_u64 v[240:241], s[82:83], 0, v[134:135]
	v_mul_f32_e32 v134, 0x45800000, v242
	v_cndmask_b32_e64 v242, v242, v134, s[6:7]
	v_mul_f32_e32 v120, v242, v120
	v_mul_f32_e32 v120, 0xbfb8aa3b, v120
	v_exp_f32_e32 v120, v120
	v_or_b32_e32 v202, 32, v198
	v_ashrrev_i32_e32 v203, 31, v202
	v_lshlrev_b64 v[132:133], 10, v[202:203]
	v_mul_f32_e32 v121, v242, v121
	v_lshl_add_u64 v[132:133], v[132:133], 0, v[196:197]
	v_add_f32_e32 v120, 1.0, v120
	v_mul_f32_e32 v121, 0xbfb8aa3b, v121
	v_lshlrev_b64 v[132:133], 1, v[132:133]
	v_rcp_f32_e32 v120, v120
	v_exp_f32_e32 v121, v121
	v_or_b32_e32 v128, 0x100, v128
	v_lshl_add_u64 v[142:143], s[84:85], 0, v[132:133]
	v_lshl_add_u64 v[144:145], s[82:83], 0, v[132:133]
	v_or_b32_e32 v132, 0x100, v132
	v_lshl_add_u64 v[130:131], s[84:85], 0, v[128:129]
	v_lshl_add_u64 v[128:129], s[82:83], 0, v[128:129]
	global_load_dwordx4 v[156:159], v[142:143], off
	global_load_dwordx4 v[152:155], v[144:145], off
	v_lshl_add_u64 v[144:145], s[84:85], 0, v[132:133]
	v_lshl_add_u64 v[132:133], s[82:83], 0, v[132:133]
	global_load_dwordx4 v[140:143], v[146:147], off
	global_load_dwordx4 v[136:139], v[148:149], off
	global_load_dwordx4 v[164:167], v[130:131], off
	global_load_dwordx4 v[160:163], v[128:129], off
	s_nop 0
	global_load_dwordx4 v[148:151], v[144:145], off
	s_nop 0
	global_load_dwordx4 v[144:147], v[132:133], off
	s_nop 0
	global_load_dwordx4 v[132:135], v[238:239], off
	global_load_dwordx4 v[128:131], v[240:241], off
	v_mul_f32_e32 v122, v242, v122
	v_mul_f32_e32 v122, 0xbfb8aa3b, v122
	v_exp_f32_e32 v122, v122
	v_mul_f32_e32 v124, v242, v124
	v_mul_f32_e32 v125, v242, v125
	v_mul_f32_e32 v123, v242, v123
	v_mul_f32_e32 v124, 0xbfb8aa3b, v124
	v_mul_f32_e32 v125, 0xbfb8aa3b, v125
	v_mul_f32_e32 v123, 0xbfb8aa3b, v123
	v_exp_f32_e32 v124, v124
	v_exp_f32_e32 v125, v125
	v_exp_f32_e32 v123, v123
	v_mul_f32_e32 v112, v242, v112
	v_mul_f32_e32 v112, 0xbfb8aa3b, v112
	v_exp_f32_e32 v112, v112
	v_add_f32_e32 v124, 1.0, v124
	v_add_f32_e32 v125, 1.0, v125
	v_add_f32_e32 v123, 1.0, v123
	v_rcp_f32_e32 v124, v124
	v_rcp_f32_e32 v125, v125
	v_rcp_f32_e32 v123, v123
	v_mul_f32_e32 v113, v242, v113
	v_add_f32_e32 v112, 1.0, v112
	v_mul_f32_e32 v113, 0xbfb8aa3b, v113
	v_lshlrev_b32_e32 v240, 16, v222
	v_and_b32_e32 v222, 0xffff0000, v222
	v_lshlrev_b32_e32 v245, 16, v226
	v_fmac_f32_e32 v240, v120, v245
	v_add_f32_e32 v120, 1.0, v121
	v_mul_f32_e32 v121, v242, v126
	v_mul_f32_e32 v121, 0xbfb8aa3b, v121
	v_rcp_f32_e32 v120, v120
	v_exp_f32_e32 v121, v121
	v_and_b32_e32 v226, 0xffff0000, v226
	v_lshlrev_b64 v[236:237], 11, v[198:199]
	v_fmac_f32_e32 v222, v120, v226
	v_add_f32_e32 v120, 1.0, v121
	v_add_f32_e32 v121, 1.0, v122
	v_mul_f32_e32 v122, v242, v127
	v_mul_f32_e32 v122, 0xbfb8aa3b, v122
	v_exp_f32_e32 v122, v122
	v_rcp_f32_e32 v120, v120
	v_rcp_f32_e32 v121, v121
	v_lshlrev_b32_e32 v239, 16, v221
	v_add_f32_e32 v122, 1.0, v122
	v_rcp_f32_e32 v122, v122
	v_lshlrev_b32_e32 v241, 16, v223
	v_lshlrev_b32_e32 v244, 16, v225
	v_lshlrev_b32_e32 v246, 16, v227
	v_rcp_f32_e32 v112, v112
	v_exp_f32_e32 v113, v113
	v_lshlrev_b32_e32 v238, 16, v220
	v_and_b32_e32 v220, 0xffff0000, v220
	v_and_b32_e32 v221, 0xffff0000, v221
	v_and_b32_e32 v223, 0xffff0000, v223
	v_lshlrev_b32_e32 v243, 16, v224
	v_and_b32_e32 v224, 0xffff0000, v224
	v_and_b32_e32 v225, 0xffff0000, v225
	v_and_b32_e32 v227, 0xffff0000, v227
	v_fmac_f32_e32 v239, v120, v244
	v_fmac_f32_e32 v241, v121, v246
	v_lshl_add_u64 v[126:127], s[68:69], 0, v[236:237]
	v_lshlrev_b64 v[120:121], 1, v[196:197]
	v_fmac_f32_e32 v238, v124, v243
	v_fmac_f32_e32 v220, v125, v224
	v_fmac_f32_e32 v221, v122, v225
	v_fmac_f32_e32 v223, v123, v227
	v_cvt_pk_bf16_f32 v122, v238, v220
	v_cvt_pk_bf16_f32 v123, v239, v221
	v_cvt_pk_bf16_f32 v124, v240, v222
	v_cvt_pk_bf16_f32 v125, v241, v223
	v_lshl_add_u64 v[126:127], v[126:127], 0, v[120:121]
	global_store_dwordx4 v[126:127], v[122:125], off
	v_mul_f32_e32 v114, v242, v114
	v_mul_f32_e32 v114, 0xbfb8aa3b, v114
	v_mul_f32_e32 v122, v220, v220
	v_mul_f32_e32 v123, v221, v221
	s_waitcnt vmcnt(0)
; __device__ __forceinline__ unsigned cvt_pk_bf16(float lo, float hi) { unsigned r; asm volatile("v_cvt_pk_bf16_f32 %0, %1, %2" : "=v"(r) : "v"(lo), "v"(hi)); return r; }
; __device__ __forceinline__ float sigmoidf_(float x) { return frcp(1.0f + __expf(-x)); }
;     __device__ __forceinline__ void operator()(const f32x4 (&acc)[2][2][4][2], const Unit& u, int wr, int wc, int fr, int fq, const float (&epre)[8]) const {
;     ...
;             for (int m = 0; m < 4; ++m) { const int row = row0 + ai * 128 + m * 16;
;                 const float rstd = rsqrtf(epre[ai * 4 + m] * (1.0f / DM) + EPS);
;                 float ss = 0.f;
; #pragma unroll
;                 for (int bj = 0; bj < 2; ++bj) { const size_t o = (size_t)row * DM + col0 + bj * 128;
;                     f32x4 h0, h1, p0, p1; unpack8(hw[m][bj], h0, h1); unpack8(pw[m][bj], p0, p1);
; #pragma unroll
;                     for (int j = 0; j < 4; ++j) { h0[j] += sigmoidf_(acc[ai][bj][m][0][j] * rstd) * p0[j]; h1[j] += sigmoidf_(acc[ai][bj][m][1][j] * rstd) * p1[j]; }
;                     u32x4 w; w.x = cvt_pk_bf16(h0[0], h0[1]); w.y = cvt_pk_bf16(h0[2], h0[3]); w.z = cvt_pk_bf16(h1[0], h1[1]); w.w = cvt_pk_bf16(h1[2], h1[3]);
;                     *(u32x4*)(H3 + o) = w;
;                     ss += (h0[0] * h0[0] + h0[1] * h0[1]) + (h0[2] * h0[2] + h0[3] * h0[3]) + (h1[0] * h1[0] + h1[1] * h1[1]) + (h1[2] * h1[2] + h1[3] * h1[3]); }
	v_lshlrev_b32_e32 v125, 16, v229
	v_and_b32_e32 v220, 0xffff0000, v229
	v_lshlrev_b32_e32 v221, 16, v230
	v_lshlrev_b32_e32 v229, 16, v234
	v_fmac_f32_e32 v221, v112, v229
	v_add_f32_e32 v112, 1.0, v113
	v_mul_f32_e32 v113, v242, v118
	v_mul_f32_e32 v113, 0xbfb8aa3b, v113
	v_rcp_f32_e32 v112, v112
	v_exp_f32_e32 v113, v113
	v_exp_f32_e32 v114, v114
	v_fmac_f32_e32 v122, v238, v238
	v_fmac_f32_e32 v123, v239, v239
	v_add_f32_e32 v122, v122, v123
	v_mul_f32_e32 v123, v222, v222
	v_and_b32_e32 v222, 0xffff0000, v230
	v_and_b32_e32 v230, 0xffff0000, v234
	v_mul_f32_e32 v116, v242, v116
	v_mul_f32_e32 v117, v242, v117
	v_fmac_f32_e32 v222, v112, v230
	v_add_f32_e32 v112, 1.0, v113
	v_add_f32_e32 v113, 1.0, v114
	v_mul_f32_e32 v114, v242, v119
	v_mul_f32_e32 v116, 0xbfb8aa3b, v116
	v_mul_f32_e32 v117, 0xbfb8aa3b, v117
	v_mul_f32_e32 v114, 0xbfb8aa3b, v114
	v_mul_f32_e32 v115, v242, v115
	v_exp_f32_e32 v116, v116
	v_exp_f32_e32 v117, v117
	v_exp_f32_e32 v114, v114
	v_mul_f32_e32 v115, 0xbfb8aa3b, v115
	v_exp_f32_e32 v115, v115
	v_add_f32_e32 v116, 1.0, v116
	v_add_f32_e32 v117, 1.0, v117
	v_add_f32_e32 v114, 1.0, v114
	v_fmac_f32_e32 v123, v240, v240
	v_rcp_f32_e32 v116, v116
	v_rcp_f32_e32 v117, v117
	v_rcp_f32_e32 v112, v112
	v_rcp_f32_e32 v113, v113
	v_rcp_f32_e32 v114, v114
	v_add_f32_e32 v115, 1.0, v115
	v_add_f32_e32 v122, v123, v122
	v_mul_f32_e32 v123, v223, v223
	v_rcp_f32_e32 v115, v115
	v_fmac_f32_e32 v123, v241, v241
	v_add_f32_e32 v122, v123, v122
	v_lshlrev_b32_e32 v123, 16, v228
	v_and_b32_e32 v124, 0xffff0000, v228
	v_lshlrev_b32_e32 v223, 16, v231
	v_and_b32_e32 v224, 0xffff0000, v231
	v_lshlrev_b32_e32 v225, 16, v232
	v_and_b32_e32 v226, 0xffff0000, v232
	v_lshlrev_b32_e32 v227, 16, v233
	v_and_b32_e32 v228, 0xffff0000, v233
	v_lshlrev_b32_e32 v231, 16, v235
	v_and_b32_e32 v232, 0xffff0000, v235
	v_fmac_f32_e32 v123, v116, v225
	v_fmac_f32_e32 v124, v117, v226
	v_fmac_f32_e32 v125, v112, v227
	v_fmac_f32_e32 v223, v113, v231
	v_fmac_f32_e32 v220, v114, v228
	v_cvt_pk_bf16_f32 v112, v123, v124
	v_cvt_pk_bf16_f32 v113, v125, v220
	v_cvt_pk_bf16_f32 v114, v221, v222
	v_fmac_f32_e32 v224, v115, v232
	v_cvt_pk_bf16_f32 v115, v223, v224
	global_store_dwordx4 v[126:127], v[112:115], off offset:256
	v_lshlrev_b32_e32 v116, 16, v172
	v_and_b32_e32 v117, 0xffff0000, v172
	v_fmamk_f32 v114, v219, 0x3a800000, v212
	v_mul_f32_e32 v112, v124, v124
	v_mul_f32_e32 v113, v220, v220
	v_mul_f32_e32 v115, 0x4b800000, v114
	v_cmp_gt_f32_e64 s[6:7], s40, v114
	v_fmac_f32_e32 v112, v123, v123
	v_fmac_f32_e32 v113, v125, v125
	v_cndmask_b32_e64 v114, v114, v115, s[6:7]
	v_add_f32_e32 v112, v112, v113
	v_mul_f32_e32 v113, v222, v222
	v_rsq_f32_e32 v114, v114
	v_fmac_f32_e32 v113, v221, v221
	v_add_f32_e32 v112, v113, v112
	v_mul_f32_e32 v113, v224, v224
	v_fmac_f32_e32 v113, v223, v223
	v_add_f32_e32 v112, v113, v112
	v_mul_f32_e32 v113, 0x45800000, v114
	v_cndmask_b32_e64 v113, v114, v113, s[6:7]
	v_mul_f32_e32 v104, v113, v104
	v_mul_f32_e32 v104, 0xbfb8aa3b, v104
	v_exp_f32_e32 v104, v104
	v_mul_f32_e32 v105, v113, v105
	v_mul_f32_e32 v105, 0xbfb8aa3b, v105
	v_exp_f32_e32 v105, v105
	v_add_f32_e32 v104, 1.0, v104
	v_rcp_f32_e32 v104, v104
	v_add_f32_e32 v112, v122, v112
	v_lshlrev_b32_e32 v122, 16, v174
	v_lshlrev_b32_e32 v172, 16, v170
	v_fmac_f32_e32 v122, v104, v172
	v_add_f32_e32 v104, 1.0, v105
	v_mul_f32_e32 v105, v113, v110
	v_mul_f32_e32 v106, v113, v106
	v_mul_f32_e32 v105, 0xbfb8aa3b, v105
	v_mul_f32_e32 v106, 0xbfb8aa3b, v106
	v_rcp_f32_e32 v104, v104
	v_exp_f32_e32 v105, v105
	v_exp_f32_e32 v106, v106
	v_and_b32_e32 v123, 0xffff0000, v174
	v_mul_f32_e32 v108, v113, v108
	v_and_b32_e32 v170, 0xffff0000, v170
	v_mul_f32_e32 v109, v113, v109
	v_mul_f32_e32 v108, 0xbfb8aa3b, v108
	v_mul_f32_e32 v109, 0xbfb8aa3b, v109
	v_fmac_f32_e32 v123, v104, v170
	v_add_f32_e32 v104, 1.0, v105
	v_add_f32_e32 v105, 1.0, v106
	v_mul_f32_e32 v106, v113, v111
	v_exp_f32_e32 v108, v108
	v_exp_f32_e32 v109, v109
	v_mul_f32_e32 v106, 0xbfb8aa3b, v106
	v_mul_f32_e32 v107, v113, v107
	v_exp_f32_e32 v106, v106
	v_mul_f32_e32 v107, 0xbfb8aa3b, v107
	v_exp_f32_e32 v107, v107
	v_mul_f32_e32 v96, v113, v96
	v_add_f32_e32 v108, 1.0, v108
	v_add_f32_e32 v109, 1.0, v109
	v_mul_f32_e32 v96, 0xbfb8aa3b, v96
	v_rcp_f32_e32 v108, v108
	v_rcp_f32_e32 v109, v109
	v_add_f32_e32 v106, 1.0, v106
	v_exp_f32_e32 v96, v96
	v_rcp_f32_e32 v104, v104
	v_rcp_f32_e32 v105, v105
	v_rcp_f32_e32 v106, v106
	v_add_f32_e32 v107, 1.0, v107
	v_rcp_f32_e32 v107, v107
	v_lshlrev_b64 v[114:115], 11, v[204:205]
	v_lshlrev_b32_e32 v126, 16, v168
	v_and_b32_e32 v127, 0xffff0000, v168
	v_mul_f32_e32 v97, v113, v97
	v_lshlrev_b32_e32 v118, 16, v173
	v_and_b32_e32 v119, 0xffff0000, v173
	v_lshlrev_b32_e32 v124, 16, v175
	v_lshlrev_b32_e32 v168, 16, v169
	v_and_b32_e32 v169, 0xffff0000, v169
	v_lshlrev_b32_e32 v173, 16, v171
	v_fmac_f32_e32 v116, v108, v126
	v_fmac_f32_e32 v117, v109, v127
	v_lshl_add_u64 v[108:109], s[68:69], 0, v[114:115]
	v_add_f32_e32 v96, 1.0, v96
	v_mul_f32_e32 v97, 0xbfb8aa3b, v97
	v_and_b32_e32 v125, 0xffff0000, v175
	v_and_b32_e32 v171, 0xffff0000, v171
	v_fmac_f32_e32 v118, v104, v168
	v_fmac_f32_e32 v124, v105, v173
	v_fmac_f32_e32 v119, v106, v169
	v_cvt_pk_bf16_f32 v104, v116, v117
	v_cvt_pk_bf16_f32 v105, v118, v119
	v_lshl_add_u64 v[108:109], v[108:109], 0, v[120:121]
	v_rcp_f32_e32 v96, v96
	v_exp_f32_e32 v97, v97
	v_fmac_f32_e32 v125, v107, v171
	v_cvt_pk_bf16_f32 v106, v122, v123
	v_cvt_pk_bf16_f32 v107, v124, v125
	global_store_dwordx4 v[108:109], v[104:107], off
	v_lshlrev_b32_e32 v111, 16, v166
	v_mul_f32_e32 v98, v113, v98
	v_mul_f32_e32 v104, v117, v117
; __device__ __forceinline__ unsigned cvt_pk_bf16(float lo, float hi) { unsigned r; asm volatile("v_cvt_pk_bf16_f32 %0, %1, %2" : "=v"(r) : "v"(lo), "v"(hi)); return r; }
; __device__ __forceinline__ float sigmoidf_(float x) { return frcp(1.0f + __expf(-x)); }
;     __device__ __forceinline__ void operator()(const f32x4 (&acc)[2][2][4][2], const Unit& u, int wr, int wc, int fr, int fq, const float (&epre)[8]) const {
;     ...
;             for (int m = 0; m < 4; ++m) { const int row = row0 + ai * 128 + m * 16;
;                 const float rstd = rsqrtf(epre[ai * 4 + m] * (1.0f / DM) + EPS);
;                 float ss = 0.f;
; #pragma unroll
;                 for (int bj = 0; bj < 2; ++bj) { const size_t o = (size_t)row * DM + col0 + bj * 128;
;                     f32x4 h0, h1, p0, p1; unpack8(hw[m][bj], h0, h1); unpack8(pw[m][bj], p0, p1);
; #pragma unroll
;                     for (int j = 0; j < 4; ++j) { h0[j] += sigmoidf_(acc[ai][bj][m][0][j] * rstd) * p0[j]; h1[j] += sigmoidf_(acc[ai][bj][m][1][j] * rstd) * p1[j]; }
;                     u32x4 w; w.x = cvt_pk_bf16(h0[0], h0[1]); w.y = cvt_pk_bf16(h0[2], h0[3]); w.z = cvt_pk_bf16(h1[0], h1[1]); w.w = cvt_pk_bf16(h1[2], h1[3]);
;                     *(u32x4*)(H3 + o) = w;
;                     ss += (h0[0] * h0[0] + h0[1] * h0[1]) + (h0[2] * h0[2] + h0[3] * h0[3]) + (h1[0] * h1[0] + h1[1] * h1[1]) + (h1[2] * h1[2] + h1[3] * h1[3]); }
	v_mul_f32_e32 v105, v119, v119
	v_fmac_f32_e32 v104, v116, v116
	v_fmac_f32_e32 v105, v118, v118
	v_add_f32_e32 v104, v104, v105
	v_mul_f32_e32 v105, v123, v123
	v_lshlrev_b32_e32 v123, 16, v162
	v_fmac_f32_e32 v111, v96, v123
	v_add_f32_e32 v96, 1.0, v97
	v_mul_f32_e32 v97, v113, v102
	v_mul_f32_e32 v97, 0xbfb8aa3b, v97
	v_mul_f32_e32 v98, 0xbfb8aa3b, v98
	v_rcp_f32_e32 v96, v96
	v_exp_f32_e32 v97, v97
	v_exp_f32_e32 v98, v98
	v_fmac_f32_e32 v105, v122, v122
	v_add_f32_e32 v104, v105, v104
	v_mul_f32_e32 v105, v125, v125
	v_fmac_f32_e32 v105, v124, v124
	v_and_b32_e32 v114, 0xffff0000, v166
	v_and_b32_e32 v124, 0xffff0000, v162
	v_mul_f32_e32 v100, v113, v100
	v_mul_f32_e32 v101, v113, v101
	v_fmac_f32_e32 v114, v96, v124
	v_add_f32_e32 v96, 1.0, v97
	v_add_f32_e32 v97, 1.0, v98
	v_mul_f32_e32 v98, v113, v103
	v_mul_f32_e32 v100, 0xbfb8aa3b, v100
	v_mul_f32_e32 v101, 0xbfb8aa3b, v101
	v_mul_f32_e32 v98, 0xbfb8aa3b, v98
	v_mul_f32_e32 v99, v113, v99
	v_exp_f32_e32 v100, v100
	v_exp_f32_e32 v101, v101
	v_exp_f32_e32 v98, v98
	v_mul_f32_e32 v99, 0xbfb8aa3b, v99
	v_exp_f32_e32 v99, v99
	v_add_f32_e32 v100, 1.0, v100
	v_add_f32_e32 v101, 1.0, v101
	v_add_f32_e32 v98, 1.0, v98
	v_rcp_f32_e32 v100, v100
	v_rcp_f32_e32 v101, v101
	v_rcp_f32_e32 v96, v96
	v_rcp_f32_e32 v97, v97
	v_rcp_f32_e32 v98, v98
	v_add_f32_e32 v99, 1.0, v99
	v_rcp_f32_e32 v99, v99
	v_add_f32_e32 v104, v105, v104
	v_lshlrev_b32_e32 v105, 16, v164
	v_and_b32_e32 v106, 0xffff0000, v164
	v_lshlrev_b32_e32 v107, 16, v165
	v_and_b32_e32 v110, 0xffff0000, v165
	v_lshlrev_b32_e32 v115, 16, v167
	v_lshlrev_b32_e32 v117, 16, v160
	v_and_b32_e32 v118, 0xffff0000, v160
	v_lshlrev_b32_e32 v119, 16, v161
	v_and_b32_e32 v122, 0xffff0000, v161
	v_lshlrev_b32_e32 v125, 16, v163
	v_and_b32_e32 v116, 0xffff0000, v167
	v_and_b32_e32 v126, 0xffff0000, v163
	v_fmac_f32_e32 v105, v100, v117
	v_fmac_f32_e32 v106, v101, v118
	v_fmac_f32_e32 v107, v96, v119
	v_fmac_f32_e32 v115, v97, v125
	v_fmac_f32_e32 v110, v98, v122
	v_cvt_pk_bf16_f32 v96, v105, v106
	v_cvt_pk_bf16_f32 v97, v107, v110
	v_cvt_pk_bf16_f32 v98, v111, v114
	v_fmac_f32_e32 v116, v99, v126
	v_cvt_pk_bf16_f32 v99, v115, v116
	global_store_dwordx4 v[108:109], v[96:99], off offset:256
	v_lshlrev_b32_e32 v113, 16, v154
	v_lshlrev_b32_e32 v100, 16, v156
	v_mul_f32_e32 v96, v106, v106
	v_mul_f32_e32 v97, v110, v110
	v_fmamk_f32 v98, v218, 0x3a800000, v212
	v_fmac_f32_e32 v96, v105, v105
	v_fmac_f32_e32 v97, v107, v107
	v_mul_f32_e32 v99, 0x4b800000, v98
	v_cmp_gt_f32_e64 s[6:7], s40, v98
	v_add_f32_e32 v96, v96, v97
	v_mul_f32_e32 v97, v114, v114
	v_cndmask_b32_e64 v98, v98, v99, s[6:7]
	v_fmac_f32_e32 v97, v111, v111
	v_rsq_f32_e32 v98, v98
	v_add_f32_e32 v96, v97, v96
	v_mul_f32_e32 v97, v116, v116
	v_fmac_f32_e32 v97, v115, v115
	v_add_f32_e32 v96, v97, v96
	v_add_f32_e32 v99, v104, v96
	v_mul_f32_e32 v96, 0x45800000, v98
	v_cndmask_b32_e64 v98, v98, v96, s[6:7]
	v_mul_f32_e32 v88, v98, v88
	v_mul_f32_e32 v88, 0xbfb8aa3b, v88
	v_exp_f32_e32 v88, v88
	v_mul_f32_e32 v89, v98, v89
	v_mul_f32_e32 v89, 0xbfb8aa3b, v89
	v_exp_f32_e32 v89, v89
	v_add_f32_e32 v88, 1.0, v88
	v_rcp_f32_e32 v88, v88
	v_lshlrev_b32_e32 v104, 16, v158
	v_mul_f32_e32 v90, v98, v90
	v_mul_f32_e32 v90, 0xbfb8aa3b, v90
	v_fmac_f32_e32 v104, v88, v113
	v_add_f32_e32 v88, 1.0, v89
	v_mul_f32_e32 v89, v98, v94
	v_mul_f32_e32 v89, 0xbfb8aa3b, v89
	v_rcp_f32_e32 v88, v88
	v_exp_f32_e32 v89, v89
	v_exp_f32_e32 v90, v90
	v_and_b32_e32 v105, 0xffff0000, v158
	v_mul_f32_e32 v92, v98, v92
	v_and_b32_e32 v114, 0xffff0000, v154
	v_mul_f32_e32 v93, v98, v93
	v_mul_f32_e32 v92, 0xbfb8aa3b, v92
	v_mul_f32_e32 v93, 0xbfb8aa3b, v93
	v_fmac_f32_e32 v105, v88, v114
	v_add_f32_e32 v88, 1.0, v89
	v_add_f32_e32 v89, 1.0, v90
	v_mul_f32_e32 v90, v98, v95
	v_exp_f32_e32 v92, v92
	v_exp_f32_e32 v93, v93
	v_mul_f32_e32 v90, 0xbfb8aa3b, v90
	v_mul_f32_e32 v91, v98, v91
	v_exp_f32_e32 v90, v90
	v_mul_f32_e32 v91, 0xbfb8aa3b, v91
	v_exp_f32_e32 v91, v91
	v_mul_f32_e32 v80, v98, v80
	v_add_f32_e32 v92, 1.0, v92
	v_add_f32_e32 v93, 1.0, v93
	v_mul_f32_e32 v80, 0xbfb8aa3b, v80
	v_rcp_f32_e32 v92, v92
	v_rcp_f32_e32 v93, v93
	v_add_f32_e32 v90, 1.0, v90
	v_exp_f32_e32 v80, v80
	v_rcp_f32_e32 v88, v88
	v_rcp_f32_e32 v89, v89
	v_rcp_f32_e32 v90, v90
	v_add_f32_e32 v91, 1.0, v91
	v_rcp_f32_e32 v91, v91
	v_lshlrev_b64 v[96:97], 11, v[202:203]
	v_and_b32_e32 v101, 0xffff0000, v156
	v_lshlrev_b32_e32 v108, 16, v152
	v_and_b32_e32 v109, 0xffff0000, v152
	v_mul_f32_e32 v81, v98, v81
	v_lshlrev_b32_e32 v102, 16, v157
	v_and_b32_e32 v103, 0xffff0000, v157
	v_lshlrev_b32_e32 v106, 16, v159
	v_lshlrev_b32_e32 v110, 16, v153
	v_and_b32_e32 v111, 0xffff0000, v153
	v_lshlrev_b32_e32 v115, 16, v155
	v_fmac_f32_e32 v100, v92, v108
	v_fmac_f32_e32 v101, v93, v109
	v_lshl_add_u64 v[92:93], s[68:69], 0, v[96:97]
	v_add_f32_e32 v80, 1.0, v80
	v_mul_f32_e32 v81, 0xbfb8aa3b, v81
	v_and_b32_e32 v107, 0xffff0000, v159
	v_and_b32_e32 v116, 0xffff0000, v155
	v_fmac_f32_e32 v102, v88, v110
	v_fmac_f32_e32 v106, v89, v115
	v_fmac_f32_e32 v103, v90, v111
	v_cvt_pk_bf16_f32 v88, v100, v101
	v_cvt_pk_bf16_f32 v89, v102, v103
	v_lshl_add_u64 v[92:93], v[92:93], 0, v[120:121]
	v_rcp_f32_e32 v80, v80
	v_exp_f32_e32 v81, v81
	v_fmac_f32_e32 v107, v91, v116
	v_cvt_pk_bf16_f32 v90, v104, v105
	v_cvt_pk_bf16_f32 v91, v106, v107
	global_store_dwordx4 v[92:93], v[88:91], off
	v_lshlrev_b32_e32 v95, 16, v150
	v_mul_f32_e32 v82, v98, v82
	v_mul_f32_e32 v88, v101, v101
	v_mul_f32_e32 v89, v103, v103
	v_fmac_f32_e32 v88, v100, v100
	v_fmac_f32_e32 v89, v102, v102
	v_add_f32_e32 v88, v88, v89
	v_mul_f32_e32 v89, v105, v105
	v_lshlrev_b32_e32 v105, 16, v146
; __device__ __forceinline__ unsigned cvt_pk_bf16(float lo, float hi) { unsigned r; asm volatile("v_cvt_pk_bf16_f32 %0, %1, %2" : "=v"(r) : "v"(lo), "v"(hi)); return r; }
; __device__ __forceinline__ float sigmoidf_(float x) { return frcp(1.0f + __expf(-x)); }
;     __device__ __forceinline__ void operator()(const f32x4 (&acc)[2][2][4][2], const Unit& u, int wr, int wc, int fr, int fq, const float (&epre)[8]) const {
;     ...
;             for (int m = 0; m < 4; ++m) { const int row = row0 + ai * 128 + m * 16;
;                 const float rstd = rsqrtf(epre[ai * 4 + m] * (1.0f / DM) + EPS);
;                 float ss = 0.f;
; #pragma unroll
;                 for (int bj = 0; bj < 2; ++bj) { const size_t o = (size_t)row * DM + col0 + bj * 128;
;                     f32x4 h0, h1, p0, p1; unpack8(hw[m][bj], h0, h1); unpack8(pw[m][bj], p0, p1);
; #pragma unroll
;                     for (int j = 0; j < 4; ++j) { h0[j] += sigmoidf_(acc[ai][bj][m][0][j] * rstd) * p0[j]; h1[j] += sigmoidf_(acc[ai][bj][m][1][j] * rstd) * p1[j]; }
;                     u32x4 w; w.x = cvt_pk_bf16(h0[0], h0[1]); w.y = cvt_pk_bf16(h0[2], h0[3]); w.z = cvt_pk_bf16(h1[0], h1[1]); w.w = cvt_pk_bf16(h1[2], h1[3]);
;                     *(u32x4*)(H3 + o) = w;
;                     ss += (h0[0] * h0[0] + h0[1] * h0[1]) + (h0[2] * h0[2] + h0[3] * h0[3]) + (h1[0] * h1[0] + h1[1] * h1[1]) + (h1[2] * h1[2] + h1[3] * h1[3]); }
	v_fmac_f32_e32 v95, v80, v105
	v_add_f32_e32 v80, 1.0, v81
	v_mul_f32_e32 v81, v98, v86
	v_mul_f32_e32 v81, 0xbfb8aa3b, v81
	v_mul_f32_e32 v82, 0xbfb8aa3b, v82
	v_rcp_f32_e32 v80, v80
	v_exp_f32_e32 v81, v81
	v_exp_f32_e32 v82, v82
	v_fmac_f32_e32 v89, v104, v104
	v_add_f32_e32 v88, v89, v88
	v_mul_f32_e32 v89, v107, v107
	v_fmac_f32_e32 v89, v106, v106
	v_and_b32_e32 v96, 0xffff0000, v150
	v_and_b32_e32 v106, 0xffff0000, v146
	v_mul_f32_e32 v84, v98, v84
	v_mul_f32_e32 v85, v98, v85
	v_fmac_f32_e32 v96, v80, v106
	v_add_f32_e32 v80, 1.0, v81
	v_add_f32_e32 v81, 1.0, v82
	v_mul_f32_e32 v82, v98, v87
	v_mul_f32_e32 v84, 0xbfb8aa3b, v84
	v_mul_f32_e32 v85, 0xbfb8aa3b, v85
	v_mul_f32_e32 v82, 0xbfb8aa3b, v82
	v_mul_f32_e32 v83, v98, v83
	v_exp_f32_e32 v84, v84
	v_exp_f32_e32 v85, v85
	v_exp_f32_e32 v82, v82
	v_mul_f32_e32 v83, 0xbfb8aa3b, v83
	v_exp_f32_e32 v83, v83
	v_add_f32_e32 v84, 1.0, v84
	v_add_f32_e32 v85, 1.0, v85
	v_add_f32_e32 v82, 1.0, v82
	v_rcp_f32_e32 v84, v84
	v_rcp_f32_e32 v85, v85
	v_rcp_f32_e32 v80, v80
	v_rcp_f32_e32 v81, v81
	v_rcp_f32_e32 v82, v82
	v_add_f32_e32 v83, 1.0, v83
	v_rcp_f32_e32 v83, v83
	v_add_f32_e32 v88, v89, v88
	v_lshlrev_b32_e32 v89, 16, v148
	v_and_b32_e32 v90, 0xffff0000, v148
	v_lshlrev_b32_e32 v91, 16, v149
	v_and_b32_e32 v94, 0xffff0000, v149
	v_lshlrev_b32_e32 v97, 16, v151
	v_lshlrev_b32_e32 v101, 16, v144
	v_and_b32_e32 v102, 0xffff0000, v144
	v_lshlrev_b32_e32 v103, 16, v145
	v_and_b32_e32 v104, 0xffff0000, v145
	v_lshlrev_b32_e32 v107, 16, v147
	v_and_b32_e32 v100, 0xffff0000, v151
	v_and_b32_e32 v108, 0xffff0000, v147
	v_fmac_f32_e32 v89, v84, v101
	v_fmac_f32_e32 v90, v85, v102
	v_fmac_f32_e32 v91, v80, v103
	v_fmac_f32_e32 v97, v81, v107
	v_fmac_f32_e32 v94, v82, v104
	v_cvt_pk_bf16_f32 v80, v89, v90
	v_cvt_pk_bf16_f32 v81, v91, v94
	v_cvt_pk_bf16_f32 v82, v95, v96
	v_fmac_f32_e32 v100, v83, v108
	v_cvt_pk_bf16_f32 v83, v97, v100
	global_store_dwordx4 v[92:93], v[80:83], off offset:256
	v_lshlrev_b32_e32 v84, 16, v140
	v_and_b32_e32 v85, 0xffff0000, v140
	v_mul_f32_e32 v80, v90, v90
	v_mul_f32_e32 v81, v94, v94
	v_fmamk_f32 v82, v217, 0x3a800000, v212
	v_fmac_f32_e32 v80, v89, v89
	v_fmac_f32_e32 v81, v91, v91
	v_mul_f32_e32 v83, 0x4b800000, v82
	v_cmp_gt_f32_e64 s[6:7], s40, v82
	v_add_f32_e32 v80, v80, v81
	v_mul_f32_e32 v81, v96, v96
	v_cndmask_b32_e64 v82, v82, v83, s[6:7]
	v_fmac_f32_e32 v81, v95, v95
	v_rsq_f32_e32 v82, v82
	v_add_f32_e32 v80, v81, v80
	v_mul_f32_e32 v81, v100, v100
	v_fmac_f32_e32 v81, v97, v97
	v_add_f32_e32 v80, v81, v80
	v_add_f32_e32 v83, v88, v80
	v_mul_f32_e32 v80, 0x45800000, v82
	v_cndmask_b32_e64 v82, v82, v80, s[6:7]
	v_mul_f32_e32 v72, v82, v72
	v_mul_f32_e32 v72, 0xbfb8aa3b, v72
	v_exp_f32_e32 v72, v72
	v_mul_f32_e32 v73, v82, v73
	v_mul_f32_e32 v73, 0xbfb8aa3b, v73
	v_exp_f32_e32 v73, v73
	v_add_f32_e32 v72, 1.0, v72
	v_rcp_f32_e32 v72, v72
	v_lshlrev_b32_e32 v88, 16, v142
	v_lshlrev_b32_e32 v96, 16, v138
	v_mul_f32_e32 v74, v82, v74
	v_fmac_f32_e32 v88, v72, v96
	v_add_f32_e32 v72, 1.0, v73
	v_mul_f32_e32 v73, v82, v78
	v_mul_f32_e32 v73, 0xbfb8aa3b, v73
	v_mul_f32_e32 v74, 0xbfb8aa3b, v74
	v_rcp_f32_e32 v72, v72
	v_exp_f32_e32 v73, v73
	v_exp_f32_e32 v74, v74
	v_and_b32_e32 v89, 0xffff0000, v142
	v_mul_f32_e32 v76, v82, v76
	v_and_b32_e32 v97, 0xffff0000, v138
	v_mul_f32_e32 v77, v82, v77
	v_mul_f32_e32 v76, 0xbfb8aa3b, v76
	v_mul_f32_e32 v77, 0xbfb8aa3b, v77
	v_fmac_f32_e32 v89, v72, v97
	v_add_f32_e32 v72, 1.0, v73
	v_add_f32_e32 v73, 1.0, v74
	v_mul_f32_e32 v74, v82, v79
	v_exp_f32_e32 v76, v76
	v_exp_f32_e32 v77, v77
	v_mul_f32_e32 v74, 0xbfb8aa3b, v74
	v_mul_f32_e32 v75, v82, v75
	v_exp_f32_e32 v74, v74
	v_mul_f32_e32 v75, 0xbfb8aa3b, v75
	v_exp_f32_e32 v75, v75
	v_mul_f32_e32 v64, v82, v64
	v_add_f32_e32 v76, 1.0, v76
	v_add_f32_e32 v77, 1.0, v77
	v_mul_f32_e32 v64, 0xbfb8aa3b, v64
	v_rcp_f32_e32 v76, v76
	v_rcp_f32_e32 v77, v77
	v_add_f32_e32 v74, 1.0, v74
	v_exp_f32_e32 v64, v64
	v_rcp_f32_e32 v72, v72
	v_rcp_f32_e32 v73, v73
	v_rcp_f32_e32 v74, v74
	v_add_f32_e32 v75, 1.0, v75
	v_rcp_f32_e32 v75, v75
	v_lshlrev_b64 v[80:81], 11, v[200:201]
	v_lshlrev_b32_e32 v92, 16, v136
	v_and_b32_e32 v93, 0xffff0000, v136
	v_mul_f32_e32 v65, v82, v65
	v_lshlrev_b32_e32 v86, 16, v141
	v_and_b32_e32 v87, 0xffff0000, v141
	v_lshlrev_b32_e32 v90, 16, v143
	v_lshlrev_b32_e32 v94, 16, v137
	v_and_b32_e32 v95, 0xffff0000, v137
	v_lshlrev_b32_e32 v98, 16, v139
; __device__ __forceinline__ unsigned cvt_pk_bf16(float lo, float hi) { unsigned r; asm volatile("v_cvt_pk_bf16_f32 %0, %1, %2" : "=v"(r) : "v"(lo), "v"(hi)); return r; }
; __device__ __forceinline__ float sigmoidf_(float x) { return frcp(1.0f + __expf(-x)); }
;     __device__ __forceinline__ void operator()(const f32x4 (&acc)[2][2][4][2], const Unit& u, int wr, int wc, int fr, int fq, const float (&epre)[8]) const {
;     ...
;             for (int m = 0; m < 4; ++m) { const int row = row0 + ai * 128 + m * 16;
;                 const float rstd = rsqrtf(epre[ai * 4 + m] * (1.0f / DM) + EPS);
;                 float ss = 0.f;
; #pragma unroll
;                 for (int bj = 0; bj < 2; ++bj) { const size_t o = (size_t)row * DM + col0 + bj * 128;
;                     f32x4 h0, h1, p0, p1; unpack8(hw[m][bj], h0, h1); unpack8(pw[m][bj], p0, p1);
; #pragma unroll
;                     for (int j = 0; j < 4; ++j) { h0[j] += sigmoidf_(acc[ai][bj][m][0][j] * rstd) * p0[j]; h1[j] += sigmoidf_(acc[ai][bj][m][1][j] * rstd) * p1[j]; }
;                     u32x4 w; w.x = cvt_pk_bf16(h0[0], h0[1]); w.y = cvt_pk_bf16(h0[2], h0[3]); w.z = cvt_pk_bf16(h1[0], h1[1]); w.w = cvt_pk_bf16(h1[2], h1[3]);
;                     *(u32x4*)(H3 + o) = w;
;                     ss += (h0[0] * h0[0] + h0[1] * h0[1]) + (h0[2] * h0[2] + h0[3] * h0[3]) + (h1[0] * h1[0] + h1[1] * h1[1]) + (h1[2] * h1[2] + h1[3] * h1[3]); }
;                 ssv[m] = ss;
;             }
; #pragma unroll
;             for (int m = 0; m < 4; ++m) ssv[m] += __shfl_xor(ssv[m], 16);
; #pragma unroll
;             for (int m = 0; m < 4; ++m) ssv[m] += __shfl_xor(ssv[m], 32);
;             if (fq == 0) {
; #pragma unroll
;                 for (int m = 0; m < 4; ++m) atomicAdd(sumsq3 + row0 + ai * 128 + m * 16, ssv[m]); }
	v_fmac_f32_e32 v84, v76, v92
	v_fmac_f32_e32 v85, v77, v93
	v_lshl_add_u64 v[76:77], s[68:69], 0, v[80:81]
	v_add_f32_e32 v64, 1.0, v64
	v_mul_f32_e32 v65, 0xbfb8aa3b, v65
	v_and_b32_e32 v91, 0xffff0000, v143
	v_and_b32_e32 v100, 0xffff0000, v139
	v_fmac_f32_e32 v86, v72, v94
	v_fmac_f32_e32 v90, v73, v98
	v_fmac_f32_e32 v87, v74, v95
	v_cvt_pk_bf16_f32 v72, v84, v85
	v_cvt_pk_bf16_f32 v73, v86, v87
	v_lshl_add_u64 v[76:77], v[76:77], 0, v[120:121]
	v_rcp_f32_e32 v64, v64
	v_exp_f32_e32 v65, v65
	v_fmac_f32_e32 v91, v75, v100
	v_cvt_pk_bf16_f32 v74, v88, v89
	v_cvt_pk_bf16_f32 v75, v90, v91
	global_store_dwordx4 v[76:77], v[72:75], off
	v_lshlrev_b32_e32 v80, 16, v134
	v_mul_f32_e32 v66, v82, v66
	v_mul_f32_e32 v72, v85, v85
	v_mul_f32_e32 v73, v87, v87
	v_fmac_f32_e32 v72, v84, v84
	v_fmac_f32_e32 v73, v86, v86
	v_add_f32_e32 v72, v72, v73
	v_mul_f32_e32 v73, v89, v89
	v_lshlrev_b32_e32 v89, 16, v130
	v_fmac_f32_e32 v80, v64, v89
	v_add_f32_e32 v64, 1.0, v65
	v_mul_f32_e32 v65, v82, v70
	v_mul_f32_e32 v65, 0xbfb8aa3b, v65
	v_mul_f32_e32 v66, 0xbfb8aa3b, v66
	v_rcp_f32_e32 v64, v64
	v_exp_f32_e32 v65, v65
	v_exp_f32_e32 v66, v66
	v_fmac_f32_e32 v73, v88, v88
	v_add_f32_e32 v72, v73, v72
	v_mul_f32_e32 v73, v91, v91
	v_fmac_f32_e32 v73, v90, v90
	v_and_b32_e32 v81, 0xffff0000, v134
	v_and_b32_e32 v90, 0xffff0000, v130
	v_mul_f32_e32 v69, v82, v69
	v_fmac_f32_e32 v81, v64, v90
	v_add_f32_e32 v64, 1.0, v65
	v_add_f32_e32 v65, 1.0, v66
	v_mul_f32_e32 v66, v82, v71
	v_mul_f32_e32 v68, v82, v68
	v_mul_f32_e32 v69, 0xbfb8aa3b, v69
	v_mul_f32_e32 v66, 0xbfb8aa3b, v66
	v_mul_f32_e32 v68, 0xbfb8aa3b, v68
	v_exp_f32_e32 v69, v69
	v_exp_f32_e32 v66, v66
	v_exp_f32_e32 v68, v68
	v_mul_f32_e32 v67, v82, v67
	v_mul_f32_e32 v67, 0xbfb8aa3b, v67
	v_add_f32_e32 v69, 1.0, v69
	v_exp_f32_e32 v67, v67
	v_add_f32_e32 v66, 1.0, v66
	v_add_f32_e32 v68, 1.0, v68
	v_rcp_f32_e32 v69, v69
	v_rcp_f32_e32 v66, v66
	v_rcp_f32_e32 v68, v68
	v_rcp_f32_e32 v64, v64
	v_rcp_f32_e32 v65, v65
	v_and_b32_e32 v75, 0xffff0000, v132
	v_and_b32_e32 v79, 0xffff0000, v133
	v_and_b32_e32 v86, 0xffff0000, v128
	v_and_b32_e32 v88, 0xffff0000, v129
	v_add_f32_e32 v67, 1.0, v67
	v_add_f32_e32 v73, v73, v72
	v_lshlrev_b32_e32 v74, 16, v132
	v_lshlrev_b32_e32 v78, 16, v133
	v_lshlrev_b32_e32 v84, 16, v135
	v_lshlrev_b32_e32 v72, 16, v128
	v_lshlrev_b32_e32 v87, 16, v129
	v_lshlrev_b32_e32 v91, 16, v131
	v_fmac_f32_e32 v75, v69, v86
	v_rcp_f32_e32 v67, v67
	v_fmac_f32_e32 v79, v66, v88
	v_fmac_f32_e32 v74, v68, v72
	v_fmac_f32_e32 v78, v64, v87
	v_fmac_f32_e32 v84, v65, v91
	v_mul_f32_e32 v64, v75, v75
	v_mul_f32_e32 v65, v79, v79
	v_fmac_f32_e32 v64, v74, v74
	v_fmac_f32_e32 v65, v78, v78
	v_and_b32_e32 v85, 0xffff0000, v135
	v_and_b32_e32 v92, 0xffff0000, v131
	v_add_f32_e32 v64, v64, v65
	v_mul_f32_e32 v65, v81, v81
	v_fmac_f32_e32 v85, v67, v92
	v_fmac_f32_e32 v65, v80, v80
	v_add_f32_e32 v64, v65, v64
	v_mul_f32_e32 v65, v85, v85
	v_fmac_f32_e32 v65, v84, v84
	v_add_f32_e32 v64, v65, v64
	v_and_b32_e32 v65, 64, v179
	v_add_f32_e32 v67, v73, v64
	v_xor_b32_e32 v64, 16, v179
	v_add_u32_e32 v68, 64, v65
	v_cmp_lt_i32_e64 s[6:7], v64, v68
	v_cvt_pk_bf16_f32 v72, v74, v75
	v_cvt_pk_bf16_f32 v73, v78, v79
	v_cvt_pk_bf16_f32 v74, v80, v81
	v_cvt_pk_bf16_f32 v75, v84, v85
	global_store_dwordx4 v[76:77], v[72:75], off offset:256
	s_nop 0
	v_cndmask_b32_e64 v64, v179, v64, s[6:7]
	v_lshlrev_b32_e32 v122, 2, v64
	ds_bpermute_b32 v69, v122, v67
	ds_bpermute_b32 v64, v122, v112
	ds_bpermute_b32 v65, v122, v99
	ds_bpermute_b32 v66, v122, v83
	s_waitcnt lgkmcnt(0)
	v_add_f32_e32 v67, v67, v69
	v_xor_b32_e32 v69, 32, v179
	v_cmp_lt_i32_e64 s[6:7], v69, v68
	v_add_f32_e32 v64, v112, v64
	v_add_f32_e32 v65, v99, v65
	v_cndmask_b32_e64 v68, v179, v69, s[6:7]
	v_add_f32_e32 v66, v83, v66
	v_lshlrev_b32_e32 v123, 2, v68
	ds_bpermute_b32 v68, v123, v64
	ds_bpermute_b32 v69, v123, v65
	ds_bpermute_b32 v70, v123, v66
	ds_bpermute_b32 v71, v123, v67
	v_lshl_add_u64 v[112:113], v[198:199], 2, s[10:11]
	s_and_saveexec_b64 s[6:7], s[4:5]
	s_cbranch_execz .LBB0_888
	s_waitcnt lgkmcnt(3)
	v_add_f32_e32 v64, v64, v68
	s_waitcnt lgkmcnt(0)
	v_add_f32_e32 v67, v67, v71
	v_add_f32_e32 v66, v66, v70
	v_add_f32_e32 v65, v65, v69
	global_atomic_add_f32 v[112:113], v64, off
	global_atomic_add_f32 v[112:113], v65, off offset:64
	global_atomic_add_f32 v[112:113], v66, off offset:128
	global_atomic_add_f32 v[112:113], v67, off offset:192
